# fp8 expert tables stored slice-major (per-XCD 2 MiB slice contiguous) instead of row-major: gather lines no longer all map to 1/8 of the cache sets
# speedup vs baseline: 1.0520x; 1.0281x over previous
; DI void convert_rows_fp8(const float* __restrict__ src, unsigned char* __restrict__ dst, float* __restrict__ inv, int nrows) {
;     const int lane = threadIdx.x & 63, w = threadIdx.x >> 6;
;     const int gwave = blockIdx.x * 4 + w, nwave = gridDim.x * 4;
;     for (int row_ = gwave; row_ < nrows * REP_P0; row_ += nwave) {
;         const int row = (REP_P0 == 1) ? row_ : row_ % nrows;
;         const f32x4* p = (const f32x4*)(src + (size_t)row * DM + 16 * lane);
;         f32x4 v[4];
; #pragma unroll
;         for (int i = 0; i < 4; ++i) v[i] = p[i];
;         float am = 0.f;
; #pragma unroll
;         for (int i = 0; i < 4; ++i) am = fmaxf(am, fmaxf(fmaxf(fabsf(v[i].x), fabsf(v[i].y)), fmaxf(fabsf(v[i].z), fabsf(v[i].w))));
; #pragma unroll
;         for (int o = 32; o >= 1; o >>= 1) am = fmaxf(am, __shfl_xor(am, o));
;         const unsigned eb = (__float_as_uint(am) >> 23) & 0xffu;
;         float sc = 1.0f, isc = 1.0f;
;         if (eb >= 16u && eb <= 250u) { sc = __uint_as_float((261u - eb) << 23); isc = __uint_as_float((eb - 7u) << 23); }
;         u32x4 o;
; #pragma unroll
;         for (int i = 0; i < 4; ++i) {
;             int pk = __builtin_amdgcn_cvt_pk_fp8_f32(v[i].x * sc, v[i].y * sc, 0, false);
;             pk = __builtin_amdgcn_cvt_pk_fp8_f32(v[i].z * sc, v[i].w * sc, pk, true);
;             o[i] = (unsigned)pk;
;         }
;         *(u32x4*)(dst + (size_t)row * DM + 16 * lane) = o;
;         if (lane == 0) inv[row] = isc;
.LBB0_8:
	s_or_b64 exec, exec, s[6:7]
	s_load_dwordx16 s[36:51], s[0:1], 0x40
	v_lshrrev_b32_e32 v1, 6, v174
	s_lshl_b32 s0, s2, 2
	v_writelane_b32 v253, s0, 5
	v_add_u32_e32 v170, s0, v1
	s_movk_i32 s0, 0x7fff
	v_cmp_lt_i32_e32 vcc, s0, v170
	s_and_saveexec_b64 s[0:1], vcc
	s_xor_b64 s[0:1], exec, s[0:1]
	s_or_saveexec_b64 s[6:7], s[0:1]
	s_lshl_b32 s26, s30, 2
	v_ashrrev_i32_e32 v171, 31, v170
	v_and_b32_e32 v172, 63, v174
	v_mbcnt_lo_u32_b32 v173, -1, 0
	s_xor_b64 exec, exec, s[6:7]
	s_cbranch_execz .LBB0_18
	v_mbcnt_hi_u32_b32 v6, -1, v173
	v_and_b32_e32 v7, 64, v6
	v_add_u32_e32 v7, 64, v7
	v_xor_b32_e32 v8, 32, v6
	v_cmp_lt_i32_e64 s[0:1], v8, v7
	v_lshlrev_b64 v[10:11], 10, v[170:171]
	v_lshl_or_b32 v10, v172, 4, v10
	v_cndmask_b32_e64 v8, v6, v8, s[0:1]
	v_lshlrev_b32_e32 v18, 2, v8
	v_xor_b32_e32 v8, 16, v6
	v_cmp_lt_i32_e64 s[0:1], v8, v7
	v_lshlrev_b64 v[12:13], 12, v[170:171]
	v_lshlrev_b32_e32 v16, 6, v172
	v_cndmask_b32_e64 v8, v6, v8, s[0:1]
	v_lshlrev_b32_e32 v19, 2, v8
	v_xor_b32_e32 v8, 8, v6
	v_cmp_lt_i32_e64 s[0:1], v8, v7
	s_ashr_i32 s27, s26, 31
	v_lshl_add_u64 v[10:11], s[90:91], 0, v[10:11]
	v_cndmask_b32_e64 v8, v6, v8, s[0:1]
	v_lshlrev_b32_e32 v20, 2, v8
	v_xor_b32_e32 v8, 4, v6
	v_cmp_lt_i32_e64 s[0:1], v8, v7
	v_or3_b32 v12, v12, v16, 32
	v_cmp_eq_u32_e32 vcc, 0, v172
	v_cndmask_b32_e64 v8, v6, v8, s[0:1]
	v_lshlrev_b32_e32 v21, 2, v8
	v_xor_b32_e32 v8, 2, v6
	v_cmp_lt_i32_e64 s[0:1], v8, v7
	s_lshl_b64 s[8:9], s[26:27], 2
	s_lshl_b64 s[10:11], s[26:27], 10
	v_cndmask_b32_e64 v8, v6, v8, s[0:1]
	v_lshlrev_b32_e32 v22, 2, v8
	v_xor_b32_e32 v8, 1, v6
	v_cmp_lt_i32_e64 s[0:1], v8, v7
	s_waitcnt lgkmcnt(0)
	v_lshl_add_u64 v[16:17], s[44:45], 0, v[12:13]
	s_lshl_b64 s[12:13], s[26:27], 12
	v_cndmask_b32_e64 v6, v6, v8, s[0:1]
	v_lshlrev_b32_e32 v23, 2, v6
	v_lshlrev_b64 v[6:7], 2, v[170:171]
	v_lshl_add_u64 v[6:7], s[90:91], 0, v[6:7]
	s_mov_b64 s[0:1], 0x3d400000
	v_lshl_add_u64 v[8:9], v[6:7], 0, s[0:1]
	s_mov_b64 s[0:1], 0x34000000
	v_lshl_add_u64 v[14:15], v[10:11], 0, s[0:1]
	v_mov_b32_e32 v50, s90
	v_mov_b32_e32 v51, s91
	v_lshl_add_u64 v[50:51], v[50:51], 0, s[0:1]
	s_mov_b64 s[14:15], 0
	s_movk_i32 s18, 0xeb
	s_movk_i32 s19, 0x7fff
	v_mov_b32_e32 v24, v170
	s_branch .LBB0_11

; DI void convert_rows_fp8(const float* __restrict__ src, unsigned char* __restrict__ dst, float* __restrict__ inv, int nrows) {
;     ...
;     for (int row_ = gwave; row_ < nrows * REP_P0; row_ += nwave) {
;         const int row = (REP_P0 == 1) ? row_ : row_ % nrows;
;         const f32x4* p = (const f32x4*)(src + (size_t)row * DM + 16 * lane);
;         f32x4 v[4];
; #pragma unroll
;         for (int i = 0; i < 4; ++i) v[i] = p[i];
;         float am = 0.f;
; #pragma unroll
;         for (int i = 0; i < 4; ++i) am = fmaxf(am, fmaxf(fmaxf(fabsf(v[i].x), fabsf(v[i].y)), fmaxf(fabsf(v[i].z), fabsf(v[i].w))));
; #pragma unroll
;         for (int o = 32; o >= 1; o >>= 1) am = fmaxf(am, __shfl_xor(am, o));
;         const unsigned eb = (__float_as_uint(am) >> 23) & 0xffu;
;         float sc = 1.0f, isc = 1.0f;
;         if (eb >= 16u && eb <= 250u) { sc = __uint_as_float((261u - eb) << 23); isc = __uint_as_float((eb - 7u) << 23); }
;         u32x4 o;
; #pragma unroll
;         for (int i = 0; i < 4; ++i) {
;             int pk = __builtin_amdgcn_cvt_pk_fp8_f32(v[i].x * sc, v[i].y * sc, 0, false);
;             pk = __builtin_amdgcn_cvt_pk_fp8_f32(v[i].z * sc, v[i].w * sc, pk, true);
;             o[i] = (unsigned)pk;
;         }
;         *(u32x4*)(dst + (size_t)row * DM + 16 * lane) = o;
;         if (lane == 0) inv[row] = isc;
;     }
.LBB0_11:
	global_load_dwordx4 v[26:29], v[16:17], off offset:-32
	global_load_dwordx4 v[30:33], v[16:17], off offset:-16
	global_load_dwordx4 v[34:37], v[16:17], off
	global_load_dwordx4 v[38:41], v[16:17], off offset:16
	s_waitcnt vmcnt(3)
	v_max_f32_e64 v25, |v29|, |v29|
	v_max_f32_e64 v42, |v28|, |v28|
	s_waitcnt vmcnt(2)
	v_max_f32_e64 v43, |v33|, |v33|
	v_max_f32_e64 v44, |v32|, |v32|
	s_waitcnt vmcnt(1)
	v_max_f32_e64 v45, |v37|, |v37|
	v_max_f32_e64 v46, |v36|, |v36|
	s_waitcnt vmcnt(0)
	v_max_f32_e64 v47, |v41|, |v41|
	v_max_f32_e64 v48, |v40|, |v40|
	v_max_f32_e32 v25, v42, v25
	v_max_f32_e32 v42, v44, v43
	v_max_f32_e32 v43, v46, v45
	v_max_f32_e32 v44, v48, v47
	v_max3_f32 v25, |v26|, |v27|, v25
	v_max3_f32 v42, |v30|, |v31|, v42
	v_max3_f32 v43, |v34|, |v35|, v43
	v_max3_f32 v44, |v38|, |v39|, v44
	v_max3_f32 v25, v25, 0, v42
	v_max3_f32 v25, v25, v43, v44
	ds_bpermute_b32 v42, v18, v25
	v_mov_b32_e32 v43, 0
	v_mov_b32_e32 v44, 0
	v_mov_b32_e32 v45, 0
	s_waitcnt lgkmcnt(0)
	v_max_f32_e32 v42, v42, v42
	v_max_f32_e32 v25, v25, v42
	ds_bpermute_b32 v42, v19, v25
	s_waitcnt lgkmcnt(0)
	v_max_f32_e32 v42, v42, v42
	v_max_f32_e32 v25, v25, v42
	ds_bpermute_b32 v42, v20, v25
	s_waitcnt lgkmcnt(0)
	v_max_f32_e32 v42, v42, v42
	v_max_f32_e32 v25, v25, v42
	ds_bpermute_b32 v42, v21, v25
	s_waitcnt lgkmcnt(0)
	v_max_f32_e32 v42, v42, v42
	v_max_f32_e32 v25, v25, v42
	ds_bpermute_b32 v42, v22, v25
	s_waitcnt lgkmcnt(0)
	v_max_f32_e32 v42, v42, v42
	v_max_f32_e32 v25, v25, v42
	ds_bpermute_b32 v46, v23, v25
	v_mov_b32_e32 v42, 0
	s_waitcnt lgkmcnt(0)
	v_max_f32_e32 v46, v46, v46
	v_max_f32_e32 v25, v25, v46
	v_bfe_u32 v25, v25, 23, 8
	v_add_u32_e32 v46, -16, v25
	v_lshlrev_b32_e32 v25, 23, v25
	v_sub_u32_e32 v47, 0x82800000, v25
	v_cmp_gt_u32_e64 s[0:1], s18, v46
	s_nop 1
	v_cndmask_b32_e64 v46, 1.0, v47, s[0:1]
	v_mul_f32_e32 v26, v26, v46
	v_mul_f32_e32 v27, v27, v46
	v_mul_f32_e32 v30, v30, v46
	v_mul_f32_e32 v31, v31, v46
	v_mul_f32_e32 v34, v34, v46
	v_mul_f32_e32 v35, v35, v46
	v_mul_f32_e32 v38, v38, v46
	v_mul_f32_e32 v39, v39, v46
	v_cvt_pk_fp8_f32 v42, v26, v27
	v_cvt_pk_fp8_f32 v43, v30, v31
	v_cvt_pk_fp8_f32 v44, v34, v35
	v_cvt_pk_fp8_f32 v45, v38, v39
	v_mul_f32_e32 v28, v28, v46
	v_mul_f32_e32 v29, v29, v46
	v_mul_f32_e32 v32, v32, v46
	v_mul_f32_e32 v33, v33, v46
	v_mul_f32_e32 v36, v36, v46
	v_mul_f32_e32 v37, v37, v46
	v_mul_f32_e32 v40, v40, v46
	v_mul_f32_e32 v41, v41, v46
	v_cvt_pk_fp8_f32 v42, v28, v29 op_sel:[0,0,1]
	v_cvt_pk_fp8_f32 v43, v32, v33 op_sel:[0,0,1]
	v_cvt_pk_fp8_f32 v44, v36, v37 op_sel:[0,0,1]
	v_cvt_pk_fp8_f32 v45, v40, v41 op_sel:[0,0,1]
	v_lshrrev_b32_e32 v52, 14, v24
	v_lshlrev_b32_e32 v52, 24, v52
	v_and_b32_e32 v53, 0x3fff, v24
	v_lshl_or_b32 v52, v53, 7, v52
	v_lshrrev_b32_e32 v53, 3, v172
	v_lshl_or_b32 v52, v53, 21, v52
	v_and_b32_e32 v53, 7, v172
	v_lshl_or_b32 v52, v53, 4, v52
	v_mov_b32_e32 v53, 0
	v_lshl_add_u64 v[52:53], v[50:51], 0, v[52:53]
	global_store_dwordx4 v[52:53], v[42:45], off
	s_and_saveexec_b64 s[16:17], vcc
	s_cbranch_execz .LBB0_10
	v_add_u32_e32 v25, 0xfc800000, v25
	v_cndmask_b32_e64 v25, 1.0, v25, s[0:1]
	global_store_dword v[8:9], v25, off
	s_branch .LBB0_10
.LBB0_13:
	s_or_b64 exec, exec, s[14:15]
	s_mov_b64 s[0:1], 0x3d420000
	v_lshl_add_u64 v[6:7], v[6:7], 0, s[0:1]
	s_mov_b64 s[0:1], 0x36000000
	v_lshl_add_u64 v[8:9], v[10:11], 0, s[0:1]
	v_mov_b32_e32 v50, s90
	v_mov_b32_e32 v51, s91
	v_lshl_add_u64 v[50:51], v[50:51], 0, s[0:1]
	v_lshl_add_u64 v[10:11], s[46:47], 0, v[12:13]
	s_mov_b64 s[14:15], 0
	s_movk_i32 s18, 0xeb
	s_movk_i32 s19, 0x7fff
	v_mov_b32_e32 v12, v170
	s_branch .LBB0_15

; DI void convert_rows_fp8(const float* __restrict__ src, unsigned char* __restrict__ dst, float* __restrict__ inv, int nrows) {
;     ...
;     for (int row_ = gwave; row_ < nrows * REP_P0; row_ += nwave) {
;         const int row = (REP_P0 == 1) ? row_ : row_ % nrows;
;         const f32x4* p = (const f32x4*)(src + (size_t)row * DM + 16 * lane);
;         f32x4 v[4];
; #pragma unroll
;         for (int i = 0; i < 4; ++i) v[i] = p[i];
;         float am = 0.f;
; #pragma unroll
;         for (int i = 0; i < 4; ++i) am = fmaxf(am, fmaxf(fmaxf(fabsf(v[i].x), fabsf(v[i].y)), fmaxf(fabsf(v[i].z), fabsf(v[i].w))));
; #pragma unroll
;         for (int o = 32; o >= 1; o >>= 1) am = fmaxf(am, __shfl_xor(am, o));
;         const unsigned eb = (__float_as_uint(am) >> 23) & 0xffu;
;         float sc = 1.0f, isc = 1.0f;
;         if (eb >= 16u && eb <= 250u) { sc = __uint_as_float((261u - eb) << 23); isc = __uint_as_float((eb - 7u) << 23); }
;         u32x4 o;
; #pragma unroll
;         for (int i = 0; i < 4; ++i) {
;             int pk = __builtin_amdgcn_cvt_pk_fp8_f32(v[i].x * sc, v[i].y * sc, 0, false);
;             pk = __builtin_amdgcn_cvt_pk_fp8_f32(v[i].z * sc, v[i].w * sc, pk, true);
;             o[i] = (unsigned)pk;
;         }
;         *(u32x4*)(dst + (size_t)row * DM + 16 * lane) = o;
;         if (lane == 0) inv[row] = isc;
;     }
.LBB0_15:
	global_load_dwordx4 v[14:17], v[10:11], off offset:-32
	global_load_dwordx4 v[24:27], v[10:11], off offset:-16
	global_load_dwordx4 v[28:31], v[10:11], off
	global_load_dwordx4 v[32:35], v[10:11], off offset:16
	s_waitcnt vmcnt(3)
	v_max_f32_e64 v13, |v17|, |v17|
	v_max_f32_e64 v36, |v16|, |v16|
	s_waitcnt vmcnt(2)
	v_max_f32_e64 v37, |v27|, |v27|
	v_max_f32_e64 v38, |v26|, |v26|
	s_waitcnt vmcnt(1)
	v_max_f32_e64 v39, |v31|, |v31|
	v_max_f32_e64 v40, |v30|, |v30|
	s_waitcnt vmcnt(0)
	v_max_f32_e64 v41, |v35|, |v35|
	v_max_f32_e64 v42, |v34|, |v34|
	v_max_f32_e32 v13, v36, v13
	v_max_f32_e32 v36, v38, v37
	v_max_f32_e32 v37, v40, v39
	v_max_f32_e32 v38, v42, v41
	v_max3_f32 v13, |v14|, |v15|, v13
	v_max3_f32 v36, |v24|, |v25|, v36
	v_max3_f32 v37, |v28|, |v29|, v37
	v_max3_f32 v38, |v32|, |v33|, v38
	v_max3_f32 v13, v13, 0, v36
	v_max3_f32 v13, v13, v37, v38
	ds_bpermute_b32 v36, v18, v13
	v_mov_b32_e32 v37, 0
	v_mov_b32_e32 v38, 0
	v_mov_b32_e32 v39, 0
	s_waitcnt lgkmcnt(0)
	v_max_f32_e32 v36, v36, v36
	v_max_f32_e32 v13, v13, v36
	ds_bpermute_b32 v36, v19, v13
	s_waitcnt lgkmcnt(0)
	v_max_f32_e32 v36, v36, v36
	v_max_f32_e32 v13, v13, v36
	ds_bpermute_b32 v36, v20, v13
	s_waitcnt lgkmcnt(0)
	v_max_f32_e32 v36, v36, v36
	v_max_f32_e32 v13, v13, v36
	ds_bpermute_b32 v36, v21, v13
	s_waitcnt lgkmcnt(0)
	v_max_f32_e32 v36, v36, v36
	v_max_f32_e32 v13, v13, v36
	ds_bpermute_b32 v36, v22, v13
	s_waitcnt lgkmcnt(0)
	v_max_f32_e32 v36, v36, v36
	v_max_f32_e32 v13, v13, v36
	ds_bpermute_b32 v40, v23, v13
	v_mov_b32_e32 v36, 0
	s_waitcnt lgkmcnt(0)
	v_max_f32_e32 v40, v40, v40
	v_max_f32_e32 v13, v13, v40
	v_bfe_u32 v13, v13, 23, 8
	v_add_u32_e32 v40, -16, v13
	v_lshlrev_b32_e32 v13, 23, v13
	v_sub_u32_e32 v41, 0x82800000, v13
	v_cmp_gt_u32_e64 s[0:1], s18, v40
	s_nop 1
	v_cndmask_b32_e64 v40, 1.0, v41, s[0:1]
	v_mul_f32_e32 v14, v14, v40
	v_mul_f32_e32 v15, v15, v40
	v_mul_f32_e32 v24, v24, v40
	v_mul_f32_e32 v25, v25, v40
	v_mul_f32_e32 v28, v28, v40
	v_mul_f32_e32 v29, v29, v40
	v_mul_f32_e32 v32, v32, v40
	v_mul_f32_e32 v33, v33, v40
	v_cvt_pk_fp8_f32 v36, v14, v15
	v_cvt_pk_fp8_f32 v37, v24, v25
	v_cvt_pk_fp8_f32 v38, v28, v29
	v_cvt_pk_fp8_f32 v39, v32, v33
	v_mul_f32_e32 v16, v16, v40
	v_mul_f32_e32 v17, v17, v40
	v_mul_f32_e32 v26, v26, v40
	v_mul_f32_e32 v27, v27, v40
	v_mul_f32_e32 v30, v30, v40
	v_mul_f32_e32 v31, v31, v40
	v_mul_f32_e32 v34, v34, v40
	v_mul_f32_e32 v35, v35, v40
	v_cvt_pk_fp8_f32 v36, v16, v17 op_sel:[0,0,1]
	v_cvt_pk_fp8_f32 v37, v26, v27 op_sel:[0,0,1]
	v_cvt_pk_fp8_f32 v38, v30, v31 op_sel:[0,0,1]
	v_cvt_pk_fp8_f32 v39, v34, v35 op_sel:[0,0,1]
	v_lshrrev_b32_e32 v52, 14, v12
	v_lshlrev_b32_e32 v52, 24, v52
	v_and_b32_e32 v53, 0x3fff, v12
	v_lshl_or_b32 v52, v53, 7, v52
	v_lshrrev_b32_e32 v53, 3, v172
	v_lshl_or_b32 v52, v53, 21, v52
	v_and_b32_e32 v53, 7, v172
	v_lshl_or_b32 v52, v53, 4, v52
	v_mov_b32_e32 v53, 0
	v_lshl_add_u64 v[52:53], v[50:51], 0, v[52:53]
	global_store_dwordx4 v[52:53], v[36:39], off
	s_and_saveexec_b64 s[16:17], vcc
	s_cbranch_execz .LBB0_14
	v_add_u32_e32 v13, 0xfc800000, v13
	v_cndmask_b32_e64 v13, 1.0, v13, s[0:1]
	global_store_dword v[6:7], v13, off
	s_branch .LBB0_14

; #define U_ISSUE(SEG, E0, E1) { _Pragma("unroll") for (int b = 0; b < 16; ++b) { const int e = __shfl((b < 8) ? (E0) : (E1), (b & 7) * 8 + grp); SEG[b] = *(const u32x4*)(ub + (size_t)e * DM); } }
; DI void peer_u_phase(const bf16_t* __restrict__ x1, const int* __restrict__ eidx, const unsigned char* __restrict__ U8, float* __restrict__ ph) {
;     ...
;     for (int j_ = sm.j0; j_ < 8 * REP_PU; j_ += sm.jstep) {
;         const int j = j_ & 7;
;         const unsigned char* ub = U8 + 128 * j + 16 * l8;
;         const bf16_t* xb_ = x1 + 128 * j + 16 * l8;
;         float* pj = ph + (size_t)j * T_TOK * 128;
;         const int step = sm.nslot;
;         int t = sm.wslot;
;         if (t >= T_TOK) continue;
;         u32x4 sa[16], sb[16];
;         int e0n = 0, e1n = 0;
;         u32x4 xa, xb, xan, xbn;
;     ...
;         {
;             const int e0 = eidx[(size_t)t * 128 + lane], e1 = eidx[(size_t)t * 128 + 64 + lane];
;             xa = *(const u32x4*)(xb_ + (size_t)t * DM); xb = *(const u32x4*)(xb_ + (size_t)t * DM + 8);
;             U_ISSUE(sa, e0, e1)
;             if (t + step < T_TOK) { e0n = eidx[(size_t)(t + step) * 128 + lane]; e1n = eidx[(size_t)(t + step) * 128 + 64 + lane]; }
;         }
.LBB0_525:
	s_and_saveexec_b64 s[58:59], vcc
	s_cbranch_execz .LBB0_524
	global_load_dword v81, v[158:159], off
	global_load_dword v83, v[158:159], off offset:256
	s_lshl_b32 s56, s27, 21
	v_lshl_add_u64 v[168:169], v[154:155], 0, s[56:57]
	v_and_b32_e32 v252, 7, v172
	v_lshlrev_b32_e32 v252, 4, v252
	v_readfirstlane_b32 s98, v168
	v_readfirstlane_b32 s99, v169
	s_lshl_b32 s56, s27, 8
	v_lshl_add_u64 v[182:183], v[156:157], 0, s[56:57]
	v_lshl_add_u64 v[78:79], v[182:183], 0, v[160:161]
	global_load_dwordx4 v[74:77], v[78:79], off
	v_mov_b32_e32 v210, 0
	v_mov_b32_e32 v203, 0
	s_waitcnt vmcnt(2)
	ds_bpermute_b32 v80, v1, v81
	ds_bpermute_b32 v82, v149, v81
	ds_bpermute_b32 v84, v153, v81
	ds_bpermute_b32 v86, v198, v81
	ds_bpermute_b32 v88, v199, v81
	ds_bpermute_b32 v90, v200, v81
	ds_bpermute_b32 v92, v201, v81
	ds_bpermute_b32 v94, v202, v81
	s_waitcnt vmcnt(1)
	ds_bpermute_b32 v96, v1, v83
	ds_bpermute_b32 v98, v149, v83
	ds_bpermute_b32 v100, v153, v83
	ds_bpermute_b32 v102, v198, v83
	ds_bpermute_b32 v104, v199, v83
	ds_bpermute_b32 v106, v200, v83
	ds_bpermute_b32 v108, v201, v83
	ds_bpermute_b32 v110, v202, v83
	s_waitcnt lgkmcnt(0)
	v_lshl_add_u32 v80, v80, 7, v252
	v_lshl_add_u32 v82, v82, 7, v252
	v_lshl_add_u32 v84, v84, 7, v252
	v_lshl_add_u32 v86, v86, 7, v252
	v_lshl_add_u32 v88, v88, 7, v252
	v_lshl_add_u32 v90, v90, 7, v252
	v_lshl_add_u32 v92, v92, 7, v252
	v_lshl_add_u32 v94, v94, 7, v252
	v_lshl_add_u32 v96, v96, 7, v252
	v_lshl_add_u32 v98, v98, 7, v252
	v_lshl_add_u32 v100, v100, 7, v252
	v_lshl_add_u32 v102, v102, 7, v252
	v_lshl_add_u32 v104, v104, 7, v252
	v_lshl_add_u32 v106, v106, 7, v252
	v_lshl_add_u32 v108, v108, 7, v252
	v_lshl_add_u32 v110, v110, 7, v252
	v_mov_b32_e32 v112, v84
	v_mov_b32_e32 v114, v86
	v_mov_b32_e32 v116, v88
	v_mov_b32_e32 v118, v90
	v_mov_b32_e32 v120, v92
	v_mov_b32_e32 v122, v94
	v_mov_b32_e32 v124, v96
	v_mov_b32_e32 v126, v98
	v_mov_b32_e32 v128, v100
	v_mov_b32_e32 v130, v102
	v_mov_b32_e32 v132, v104
	v_mov_b32_e32 v134, v106
	v_mov_b32_e32 v136, v108
	v_mov_b32_e32 v138, v110
	global_load_dwordx4 v[142:145], v[78:79], off offset:16
	s_nop 0
	global_load_dwordx4 v[78:81], v80, s[98:99]
	s_nop 0
	global_load_dwordx4 v[82:85], v82, s[98:99]
	s_nop 0
	global_load_dwordx4 v[86:89], v112, s[98:99]
	global_load_dwordx4 v[90:93], v114, s[98:99]
	global_load_dwordx4 v[94:97], v116, s[98:99]
	global_load_dwordx4 v[98:101], v118, s[98:99]
	global_load_dwordx4 v[102:105], v120, s[98:99]
	global_load_dwordx4 v[106:109], v122, s[98:99]
	global_load_dwordx4 v[110:113], v124, s[98:99]
	s_nop 0
	global_load_dwordx4 v[114:117], v126, s[98:99]
	global_load_dwordx4 v[118:121], v128, s[98:99]
	global_load_dwordx4 v[122:125], v130, s[98:99]
	s_nop 0
	global_load_dwordx4 v[126:129], v132, s[98:99]
	s_nop 0
	global_load_dwordx4 v[130:133], v134, s[98:99]
	s_nop 0
	global_load_dwordx4 v[134:137], v136, s[98:99]
	s_nop 0
	global_load_dwordx4 v[138:141], v138, s[98:99]
	s_and_saveexec_b64 s[0:1], s[10:11]
	s_cbranch_execz .LBB0_528
	global_load_dword v203, v[162:163], off
	global_load_dword v210, v[162:163], off offset:256

; #define U_ISSUE(SEG, E0, E1) { _Pragma("unroll") for (int b = 0; b < 16; ++b) { const int e = __shfl((b < 8) ? (E0) : (E1), (b & 7) * 8 + grp); SEG[b] = *(const u32x4*)(ub + (size_t)e * DM); } }
; DI void peer_u_phase(const bf16_t* __restrict__ x1, const int* __restrict__ eidx, const unsigned char* __restrict__ U8, float* __restrict__ ph) {
;     ...
;         {
;             const int e0 = eidx[(size_t)t * 128 + lane], e1 = eidx[(size_t)t * 128 + 64 + lane];
;             xa = *(const u32x4*)(xb_ + (size_t)t * DM); xb = *(const u32x4*)(xb_ + (size_t)t * DM + 8);
;             U_ISSUE(sa, e0, e1)
;             if (t + step < T_TOK) { e0n = eidx[(size_t)(t + step) * 128 + lane]; e1n = eidx[(size_t)(t + step) * 128 + 64 + lane]; }
;         }
;         for (; t < T_TOK; t += 2 * step) {
;             int e0nn = 0, e1nn = 0;
;             const bool n1 = t + step < T_TOK, n2 = t + 2 * step < T_TOK, n3 = t + 3 * step < T_TOK;
;             if (n1) { U_ISSUE(sb, e0n, e1n) xan = *(const u32x4*)(xb_ + (size_t)(t + step) * DM); xbn = *(const u32x4*)(xb_ + (size_t)(t + step) * DM + 8); }
;             if (n2) { e0nn = eidx[(size_t)(t + 2 * step) * 128 + lane]; e1nn = eidx[(size_t)(t + 2 * step) * 128 + 64 + lane]; }
.LBB0_531:
	v_add_u32_e32 v186, s54, v188
	v_cmp_gt_i32_e64 s[18:19], s24, v186
	v_ashrrev_i32_e32 v187, 31, v186
	s_and_saveexec_b64 s[0:1], s[18:19]
	s_cbranch_execz .LBB0_533
	s_waitcnt vmcnt(1)
	ds_bpermute_b32 v2, v1, v203
	ds_bpermute_b32 v4, v149, v203
	ds_bpermute_b32 v10, v153, v203
	ds_bpermute_b32 v12, v198, v203
	ds_bpermute_b32 v18, v199, v203
	ds_bpermute_b32 v20, v200, v203
	ds_bpermute_b32 v26, v201, v203
	ds_bpermute_b32 v28, v202, v203
	s_waitcnt vmcnt(0)
	ds_bpermute_b32 v34, v1, v210
	ds_bpermute_b32 v36, v149, v210
	ds_bpermute_b32 v42, v153, v210
	ds_bpermute_b32 v44, v198, v210
	ds_bpermute_b32 v50, v199, v210
	ds_bpermute_b32 v52, v200, v210
	ds_bpermute_b32 v58, v201, v210
	ds_bpermute_b32 v60, v202, v210
	s_waitcnt lgkmcnt(0)
	v_lshl_add_u32 v2, v2, 7, v252
	v_lshl_add_u32 v4, v4, 7, v252
	v_lshl_add_u32 v10, v10, 7, v252
	v_lshl_add_u32 v12, v12, 7, v252
	v_lshl_add_u32 v18, v18, 7, v252
	v_lshl_add_u32 v20, v20, 7, v252
	v_lshl_add_u32 v26, v26, 7, v252
	v_lshl_add_u32 v28, v28, 7, v252
	v_lshl_add_u32 v34, v34, 7, v252
	v_lshl_add_u32 v36, v36, 7, v252
	v_lshl_add_u32 v42, v42, 7, v252
	v_lshl_add_u32 v44, v44, 7, v252
	v_lshl_add_u32 v50, v50, 7, v252
	v_lshl_add_u32 v52, v52, 7, v252
	v_lshl_add_u32 v58, v58, 7, v252
	v_lshl_add_u32 v60, v60, 7, v252
	v_lshlrev_b64 v[66:67], 11, v[186:187]
	v_lshl_add_u64 v[66:67], v[182:183], 0, v[66:67]
	global_load_dwordx4 v[6:9], v2, s[98:99]
	s_nop 0
	global_load_dwordx4 v[2:5], v4, s[98:99]
	s_nop 0
	global_load_dwordx4 v[14:17], v10, s[98:99]
	s_nop 0
	global_load_dwordx4 v[10:13], v12, s[98:99]
	s_nop 0
	global_load_dwordx4 v[22:25], v18, s[98:99]
	s_nop 0
	global_load_dwordx4 v[18:21], v20, s[98:99]
	s_nop 0
	global_load_dwordx4 v[30:33], v26, s[98:99]
	s_nop 0
	global_load_dwordx4 v[26:29], v28, s[98:99]
	s_nop 0
	global_load_dwordx4 v[38:41], v34, s[98:99]
	s_nop 0
	global_load_dwordx4 v[34:37], v36, s[98:99]
	s_nop 0
	global_load_dwordx4 v[46:49], v42, s[98:99]
	s_nop 0
	global_load_dwordx4 v[42:45], v44, s[98:99]
	s_nop 0
	global_load_dwordx4 v[54:57], v50, s[98:99]
	s_nop 0
	global_load_dwordx4 v[50:53], v52, s[98:99]
	s_nop 0
	global_load_dwordx4 v[62:65], v58, s[98:99]
	s_nop 0
	global_load_dwordx4 v[58:61], v60, s[98:99]
	s_nop 0
	global_load_dwordx4 v[70:73], v[66:67], off offset:16
	s_nop 0
	global_load_dwordx4 v[66:69], v[66:67], off

; DI float dot_fp8_row(u32x4 u, u32x4 xa, u32x4 xb) {
;     unsigned a[8];
; #pragma unroll
;     for (int j = 0; j < 4; ++j) {
;         a[2 * j] = __builtin_bit_cast(unsigned, __builtin_amdgcn_cvt_scalef32_pk_bf16_fp8(u[j], 1.0f, false));
;         a[2 * j + 1] = __builtin_bit_cast(unsigned, __builtin_amdgcn_cvt_scalef32_pk_bf16_fp8(u[j], 1.0f, true));
;     }
;     return dot16(a, xa, xb);
; }
.LBB0_535:
	s_or_b64 exec, exec, s[0:1]
	s_setprio 1
	s_waitcnt vmcnt(15)
	v_cvt_scalef32_pk_bf16_fp8 v213, v79, 1.0
	v_cvt_scalef32_pk_bf16_fp8 v189, v78, 1.0
	v_cvt_scalef32_pk_bf16_fp8 v212, v78, 1.0 op_sel:[1,0,0]
	v_cvt_scalef32_pk_bf16_fp8 v214, v79, 1.0 op_sel:[1,0,0]
	v_cvt_scalef32_pk_bf16_fp8 v215, v80, 1.0
	v_cvt_scalef32_pk_bf16_fp8 v216, v80, 1.0 op_sel:[1,0,0]
	v_cvt_scalef32_pk_bf16_fp8 v217, v81, 1.0
	v_cvt_scalef32_pk_bf16_fp8 v218, v81, 1.0 op_sel:[1,0,0]
	v_dot2_f32_bf16 v219, v189, v74, 0
	v_dot2_f32_bf16 v219, v212, v75, v219
	v_dot2_f32_bf16 v219, v213, v76, v219
	v_dot2_f32_bf16 v219, v214, v77, v219
	v_dot2_f32_bf16 v219, v215, v142, v219
	v_dot2_f32_bf16 v219, v216, v143, v219
	v_dot2_f32_bf16 v219, v217, v144, v219
	v_dot2_f32_bf16 v219, v218, v145, v219
	s_nop 2
	s_waitcnt vmcnt(14)
	v_cvt_scalef32_pk_bf16_fp8 v213, v83, 1.0
	v_cvt_scalef32_pk_bf16_fp8 v189, v82, 1.0
	v_cvt_scalef32_pk_bf16_fp8 v212, v82, 1.0 op_sel:[1,0,0]
	v_cvt_scalef32_pk_bf16_fp8 v214, v83, 1.0 op_sel:[1,0,0]
	v_cvt_scalef32_pk_bf16_fp8 v215, v84, 1.0
	v_cvt_scalef32_pk_bf16_fp8 v216, v84, 1.0 op_sel:[1,0,0]
	v_cvt_scalef32_pk_bf16_fp8 v217, v85, 1.0
	v_cvt_scalef32_pk_bf16_fp8 v218, v85, 1.0 op_sel:[1,0,0]
	v_dot2_f32_bf16 v220, v189, v74, 0
	v_dot2_f32_bf16 v220, v212, v75, v220
	v_dot2_f32_bf16 v220, v213, v76, v220
	v_dot2_f32_bf16 v220, v214, v77, v220
	v_dot2_f32_bf16 v220, v215, v142, v220
	v_dot2_f32_bf16 v220, v216, v143, v220
	v_dot2_f32_bf16 v220, v217, v144, v220
	v_dot2_f32_bf16 v220, v218, v145, v220
	s_nop 2
	s_waitcnt vmcnt(13)
	v_cvt_scalef32_pk_bf16_fp8 v213, v87, 1.0
	v_cvt_scalef32_pk_bf16_fp8 v189, v86, 1.0
	v_cvt_scalef32_pk_bf16_fp8 v212, v86, 1.0 op_sel:[1,0,0]
	v_cvt_scalef32_pk_bf16_fp8 v214, v87, 1.0 op_sel:[1,0,0]
	v_cvt_scalef32_pk_bf16_fp8 v215, v88, 1.0
	v_cvt_scalef32_pk_bf16_fp8 v216, v88, 1.0 op_sel:[1,0,0]
	v_cvt_scalef32_pk_bf16_fp8 v217, v89, 1.0
	v_cvt_scalef32_pk_bf16_fp8 v218, v89, 1.0 op_sel:[1,0,0]
	v_dot2_f32_bf16 v221, v189, v74, 0
	v_dot2_f32_bf16 v221, v212, v75, v221
	v_dot2_f32_bf16 v221, v213, v76, v221
	v_dot2_f32_bf16 v221, v214, v77, v221
	v_dot2_f32_bf16 v221, v215, v142, v221
	v_dot2_f32_bf16 v221, v216, v143, v221
	v_dot2_f32_bf16 v221, v217, v144, v221
	v_dot2_f32_bf16 v221, v218, v145, v221
	s_nop 2
	s_waitcnt vmcnt(12)
	v_cvt_scalef32_pk_bf16_fp8 v213, v91, 1.0
	v_cvt_scalef32_pk_bf16_fp8 v189, v90, 1.0
	v_cvt_scalef32_pk_bf16_fp8 v212, v90, 1.0 op_sel:[1,0,0]
	v_cvt_scalef32_pk_bf16_fp8 v214, v91, 1.0 op_sel:[1,0,0]
	v_cvt_scalef32_pk_bf16_fp8 v215, v92, 1.0
	v_cvt_scalef32_pk_bf16_fp8 v216, v92, 1.0 op_sel:[1,0,0]
	v_cvt_scalef32_pk_bf16_fp8 v217, v93, 1.0
	v_cvt_scalef32_pk_bf16_fp8 v218, v93, 1.0 op_sel:[1,0,0]
	v_dot2_f32_bf16 v222, v189, v74, 0
	v_dot2_f32_bf16 v222, v212, v75, v222
	v_dot2_f32_bf16 v222, v213, v76, v222
	v_dot2_f32_bf16 v222, v214, v77, v222
	v_dot2_f32_bf16 v222, v215, v142, v222
	v_dot2_f32_bf16 v222, v216, v143, v222
	v_dot2_f32_bf16 v222, v217, v144, v222
	v_dot2_f32_bf16 v222, v218, v145, v222
	s_nop 2
	s_waitcnt vmcnt(11)
	v_cvt_scalef32_pk_bf16_fp8 v213, v95, 1.0
	v_cvt_scalef32_pk_bf16_fp8 v189, v94, 1.0
	v_cvt_scalef32_pk_bf16_fp8 v212, v94, 1.0 op_sel:[1,0,0]
	v_cvt_scalef32_pk_bf16_fp8 v214, v95, 1.0 op_sel:[1,0,0]
	v_cvt_scalef32_pk_bf16_fp8 v215, v96, 1.0
	v_cvt_scalef32_pk_bf16_fp8 v216, v96, 1.0 op_sel:[1,0,0]
	v_cvt_scalef32_pk_bf16_fp8 v217, v97, 1.0
	v_cvt_scalef32_pk_bf16_fp8 v218, v97, 1.0 op_sel:[1,0,0]
	v_dot2_f32_bf16 v223, v189, v74, 0
	v_dot2_f32_bf16 v223, v212, v75, v223
	v_dot2_f32_bf16 v223, v213, v76, v223
	v_dot2_f32_bf16 v223, v214, v77, v223
	v_dot2_f32_bf16 v223, v215, v142, v223
	v_dot2_f32_bf16 v223, v216, v143, v223
	v_dot2_f32_bf16 v223, v217, v144, v223
	v_dot2_f32_bf16 v223, v218, v145, v223
	s_nop 2
	s_waitcnt vmcnt(10)
	v_cvt_scalef32_pk_bf16_fp8 v213, v99, 1.0
	v_cvt_scalef32_pk_bf16_fp8 v189, v98, 1.0
	v_cvt_scalef32_pk_bf16_fp8 v212, v98, 1.0 op_sel:[1,0,0]
	v_cvt_scalef32_pk_bf16_fp8 v214, v99, 1.0 op_sel:[1,0,0]
	v_cvt_scalef32_pk_bf16_fp8 v215, v100, 1.0
	v_cvt_scalef32_pk_bf16_fp8 v216, v100, 1.0 op_sel:[1,0,0]
	v_cvt_scalef32_pk_bf16_fp8 v217, v101, 1.0
	v_cvt_scalef32_pk_bf16_fp8 v218, v101, 1.0 op_sel:[1,0,0]
	v_dot2_f32_bf16 v224, v189, v74, 0
	v_dot2_f32_bf16 v224, v212, v75, v224
	v_dot2_f32_bf16 v224, v213, v76, v224
	v_dot2_f32_bf16 v224, v214, v77, v224
	v_dot2_f32_bf16 v224, v215, v142, v224
	v_dot2_f32_bf16 v224, v216, v143, v224
	v_dot2_f32_bf16 v224, v217, v144, v224
	v_dot2_f32_bf16 v224, v218, v145, v224
	s_nop 2
	s_waitcnt vmcnt(9)
	v_cvt_scalef32_pk_bf16_fp8 v213, v103, 1.0
	v_cvt_scalef32_pk_bf16_fp8 v189, v102, 1.0
	v_cvt_scalef32_pk_bf16_fp8 v212, v102, 1.0 op_sel:[1,0,0]
	v_cvt_scalef32_pk_bf16_fp8 v214, v103, 1.0 op_sel:[1,0,0]
	v_cvt_scalef32_pk_bf16_fp8 v215, v104, 1.0
	v_cvt_scalef32_pk_bf16_fp8 v216, v104, 1.0 op_sel:[1,0,0]
	v_cvt_scalef32_pk_bf16_fp8 v217, v105, 1.0
	v_cvt_scalef32_pk_bf16_fp8 v218, v105, 1.0 op_sel:[1,0,0]
	v_dot2_f32_bf16 v225, v189, v74, 0
	v_dot2_f32_bf16 v225, v212, v75, v225
	v_dot2_f32_bf16 v225, v213, v76, v225
	v_dot2_f32_bf16 v225, v214, v77, v225
	v_dot2_f32_bf16 v225, v215, v142, v225
	v_dot2_f32_bf16 v225, v216, v143, v225
	v_dot2_f32_bf16 v225, v217, v144, v225
	v_dot2_f32_bf16 v225, v218, v145, v225
	s_nop 2
	s_waitcnt vmcnt(8)
; DI float dot_fp8_row(u32x4 u, u32x4 xa, u32x4 xb) {
;     unsigned a[8];
; #pragma unroll
;     for (int j = 0; j < 4; ++j) {
;         a[2 * j] = __builtin_bit_cast(unsigned, __builtin_amdgcn_cvt_scalef32_pk_bf16_fp8(u[j], 1.0f, false));
;         a[2 * j + 1] = __builtin_bit_cast(unsigned, __builtin_amdgcn_cvt_scalef32_pk_bf16_fp8(u[j], 1.0f, true));
;     }
;     return dot16(a, xa, xb);
; }
	v_cvt_scalef32_pk_bf16_fp8 v213, v107, 1.0
	v_cvt_scalef32_pk_bf16_fp8 v189, v106, 1.0
	v_cvt_scalef32_pk_bf16_fp8 v212, v106, 1.0 op_sel:[1,0,0]
	v_cvt_scalef32_pk_bf16_fp8 v214, v107, 1.0 op_sel:[1,0,0]
	v_cvt_scalef32_pk_bf16_fp8 v215, v108, 1.0
	v_cvt_scalef32_pk_bf16_fp8 v216, v108, 1.0 op_sel:[1,0,0]
	v_cvt_scalef32_pk_bf16_fp8 v218, v109, 1.0
	v_cvt_scalef32_pk_bf16_fp8 v226, v109, 1.0 op_sel:[1,0,0]
	v_dot2_f32_bf16 v227, v189, v74, 0
	v_dot2_f32_bf16 v227, v212, v75, v227
	v_dot2_f32_bf16 v227, v213, v76, v227
	v_dot2_f32_bf16 v227, v214, v77, v227
	v_dot2_f32_bf16 v227, v215, v142, v227
	v_dot2_f32_bf16 v227, v216, v143, v227
	v_dot2_f32_bf16 v227, v218, v144, v227
	v_dot2_f32_bf16 v227, v226, v145, v227
	s_nop 2
	v_cndmask_b32_e64 v213, v220, v224, s[12:13]
	ds_bpermute_b32 v213, v193, v213
	v_cndmask_b32_e64 v214, v221, v225, s[12:13]
	ds_bpermute_b32 v214, v193, v214
	v_cndmask_b32_e64 v215, v222, v227, s[12:13]
	v_cndmask_b32_e64 v217, v219, v223, s[12:13]
	ds_bpermute_b32 v215, v193, v215
	ds_bpermute_b32 v217, v193, v217
	v_cndmask_b32_e64 v212, v224, v220, s[12:13]
	s_waitcnt lgkmcnt(3)
	v_add_f32_e32 v212, v212, v213
	v_cndmask_b32_e64 v213, v225, v221, s[12:13]
	s_waitcnt lgkmcnt(2)
	v_add_f32_e32 v213, v213, v214
	v_cndmask_b32_e64 v214, v227, v222, s[12:13]
	v_cndmask_b32_e64 v189, v223, v219, s[12:13]
	s_waitcnt lgkmcnt(1)
	v_add_f32_e32 v214, v214, v215
	s_waitcnt lgkmcnt(0)
	v_add_f32_e32 v189, v189, v217
	v_cndmask_b32_e64 v216, v212, v214, s[14:15]
	v_cndmask_b32_e64 v215, v189, v213, s[14:15]
	ds_bpermute_b32 v216, v194, v216
	ds_bpermute_b32 v215, v194, v215
	v_cndmask_b32_e64 v212, v214, v212, s[14:15]
	v_cndmask_b32_e64 v189, v213, v189, s[14:15]
	s_waitcnt vmcnt(7)
	v_cvt_scalef32_pk_bf16_fp8 v214, v110, 1.0
	s_waitcnt lgkmcnt(1)
	v_add_f32_e32 v212, v212, v216
	v_cvt_scalef32_pk_bf16_fp8 v216, v111, 1.0
	s_waitcnt lgkmcnt(0)
	v_add_f32_e32 v189, v189, v215
	v_cvt_scalef32_pk_bf16_fp8 v215, v110, 1.0 op_sel:[1,0,0]
	v_cvt_scalef32_pk_bf16_fp8 v217, v111, 1.0 op_sel:[1,0,0]
	v_cvt_scalef32_pk_bf16_fp8 v218, v112, 1.0
	v_cvt_scalef32_pk_bf16_fp8 v219, v112, 1.0 op_sel:[1,0,0]
	v_cvt_scalef32_pk_bf16_fp8 v220, v113, 1.0
	v_cvt_scalef32_pk_bf16_fp8 v221, v113, 1.0 op_sel:[1,0,0]
	v_dot2_f32_bf16 v222, v214, v74, 0
	v_dot2_f32_bf16 v222, v215, v75, v222
	v_dot2_f32_bf16 v222, v216, v76, v222
	v_dot2_f32_bf16 v222, v217, v77, v222
	v_dot2_f32_bf16 v222, v218, v142, v222
	v_dot2_f32_bf16 v222, v219, v143, v222
	v_dot2_f32_bf16 v222, v220, v144, v222
	v_dot2_f32_bf16 v222, v221, v145, v222
	s_nop 2
	s_waitcnt vmcnt(6)
	v_cvt_scalef32_pk_bf16_fp8 v216, v115, 1.0
	v_cvt_scalef32_pk_bf16_fp8 v214, v114, 1.0
	v_cvt_scalef32_pk_bf16_fp8 v215, v114, 1.0 op_sel:[1,0,0]
	v_cvt_scalef32_pk_bf16_fp8 v217, v115, 1.0 op_sel:[1,0,0]
	v_cvt_scalef32_pk_bf16_fp8 v218, v116, 1.0
	v_cvt_scalef32_pk_bf16_fp8 v219, v116, 1.0 op_sel:[1,0,0]
	v_cvt_scalef32_pk_bf16_fp8 v220, v117, 1.0
	v_cvt_scalef32_pk_bf16_fp8 v221, v117, 1.0 op_sel:[1,0,0]
	v_dot2_f32_bf16 v223, v214, v74, 0
	v_dot2_f32_bf16 v223, v215, v75, v223
	v_dot2_f32_bf16 v223, v216, v76, v223
	v_dot2_f32_bf16 v223, v217, v77, v223
	v_dot2_f32_bf16 v223, v218, v142, v223
	v_dot2_f32_bf16 v223, v219, v143, v223
	v_dot2_f32_bf16 v223, v220, v144, v223
	v_dot2_f32_bf16 v223, v221, v145, v223
	s_nop 2
	s_waitcnt vmcnt(5)
	v_cvt_scalef32_pk_bf16_fp8 v216, v119, 1.0
	v_cvt_scalef32_pk_bf16_fp8 v214, v118, 1.0
	v_cvt_scalef32_pk_bf16_fp8 v215, v118, 1.0 op_sel:[1,0,0]
	v_cvt_scalef32_pk_bf16_fp8 v217, v119, 1.0 op_sel:[1,0,0]
	v_cvt_scalef32_pk_bf16_fp8 v218, v120, 1.0
	v_cvt_scalef32_pk_bf16_fp8 v219, v120, 1.0 op_sel:[1,0,0]
	v_cvt_scalef32_pk_bf16_fp8 v220, v121, 1.0
	v_cvt_scalef32_pk_bf16_fp8 v221, v121, 1.0 op_sel:[1,0,0]
	v_dot2_f32_bf16 v224, v214, v74, 0
	v_dot2_f32_bf16 v224, v215, v75, v224
	v_dot2_f32_bf16 v224, v216, v76, v224
	v_dot2_f32_bf16 v224, v217, v77, v224
	v_dot2_f32_bf16 v224, v218, v142, v224
	v_dot2_f32_bf16 v224, v219, v143, v224
	v_dot2_f32_bf16 v224, v220, v144, v224
	v_dot2_f32_bf16 v224, v221, v145, v224
	s_nop 2
	s_waitcnt vmcnt(4)
	v_cvt_scalef32_pk_bf16_fp8 v216, v123, 1.0
	v_cvt_scalef32_pk_bf16_fp8 v214, v122, 1.0
	v_cvt_scalef32_pk_bf16_fp8 v215, v122, 1.0 op_sel:[1,0,0]
	v_cvt_scalef32_pk_bf16_fp8 v217, v123, 1.0 op_sel:[1,0,0]
	v_cvt_scalef32_pk_bf16_fp8 v218, v124, 1.0
	v_cvt_scalef32_pk_bf16_fp8 v219, v124, 1.0 op_sel:[1,0,0]
	v_cvt_scalef32_pk_bf16_fp8 v220, v125, 1.0
	v_cvt_scalef32_pk_bf16_fp8 v221, v125, 1.0 op_sel:[1,0,0]
	v_dot2_f32_bf16 v225, v214, v74, 0
	v_dot2_f32_bf16 v225, v215, v75, v225
	v_dot2_f32_bf16 v225, v216, v76, v225
	v_dot2_f32_bf16 v225, v217, v77, v225
	v_dot2_f32_bf16 v225, v218, v142, v225
	v_dot2_f32_bf16 v225, v219, v143, v225
	v_dot2_f32_bf16 v225, v220, v144, v225
	v_dot2_f32_bf16 v225, v221, v145, v225
	s_nop 2
	s_waitcnt vmcnt(3)
	v_cvt_scalef32_pk_bf16_fp8 v216, v127, 1.0
	v_cvt_scalef32_pk_bf16_fp8 v214, v126, 1.0
	v_cvt_scalef32_pk_bf16_fp8 v215, v126, 1.0 op_sel:[1,0,0]
	v_cvt_scalef32_pk_bf16_fp8 v217, v127, 1.0 op_sel:[1,0,0]
	v_cvt_scalef32_pk_bf16_fp8 v218, v128, 1.0
	v_cvt_scalef32_pk_bf16_fp8 v219, v128, 1.0 op_sel:[1,0,0]
	v_cvt_scalef32_pk_bf16_fp8 v220, v129, 1.0
	v_cvt_scalef32_pk_bf16_fp8 v221, v129, 1.0 op_sel:[1,0,0]
	v_dot2_f32_bf16 v226, v214, v74, 0
	v_dot2_f32_bf16 v226, v215, v75, v226
	v_dot2_f32_bf16 v226, v216, v76, v226
	v_dot2_f32_bf16 v226, v217, v77, v226
	v_dot2_f32_bf16 v226, v218, v142, v226
	v_dot2_f32_bf16 v226, v219, v143, v226
	v_dot2_f32_bf16 v226, v220, v144, v226
	v_dot2_f32_bf16 v226, v221, v145, v226
	s_nop 2
	s_waitcnt vmcnt(2)
; #define U_ISSUE(SEG, E0, E1) { _Pragma("unroll") for (int b = 0; b < 16; ++b) { const int e = __shfl((b < 8) ? (E0) : (E1), (b & 7) * 8 + grp); SEG[b] = *(const u32x4*)(ub + (size_t)e * DM); } }
; DI void peer_u_phase(const bf16_t* __restrict__ x1, const int* __restrict__ eidx, const unsigned char* __restrict__ U8, float* __restrict__ ph) {
;     ...
;         {
;             const int e0 = eidx[(size_t)t * 128 + lane], e1 = eidx[(size_t)t * 128 + 64 + lane];
;             xa = *(const u32x4*)(xb_ + (size_t)t * DM); xb = *(const u32x4*)(xb_ + (size_t)t * DM + 8);
;             U_ISSUE(sa, e0, e1)
;             if (t + step < T_TOK) { e0n = eidx[(size_t)(t + step) * 128 + lane]; e1n = eidx[(size_t)(t + step) * 128 + 64 + lane]; }
;         }
;         for (; t < T_TOK; t += 2 * step) {
;             int e0nn = 0, e1nn = 0;
;             const bool n1 = t + step < T_TOK, n2 = t + 2 * step < T_TOK, n3 = t + 3 * step < T_TOK;
;             if (n1) { U_ISSUE(sb, e0n, e1n) xan = *(const u32x4*)(xb_ + (size_t)(t + step) * DM); xbn = *(const u32x4*)(xb_ + (size_t)(t + step) * DM + 8); }
;             if (n2) { e0nn = eidx[(size_t)(t + 2 * step) * 128 + lane]; e1nn = eidx[(size_t)(t + 2 * step) * 128 + 64 + lane]; }
;             U_COMPUTE(sa, t)
;             if (n1) {
;                 xa = xan; xb = xbn;
;                 if (n2) { U_ISSUE(sa, e0nn, e1nn) xan = *(const u32x4*)(xb_ + (size_t)(t + 2 * step) * DM); xbn = *(const u32x4*)(xb_ + (size_t)(t + 2 * step) * DM + 8); }
	v_cvt_scalef32_pk_bf16_fp8 v216, v131, 1.0
	v_cvt_scalef32_pk_bf16_fp8 v214, v130, 1.0
	v_cvt_scalef32_pk_bf16_fp8 v215, v130, 1.0 op_sel:[1,0,0]
	v_cvt_scalef32_pk_bf16_fp8 v217, v131, 1.0 op_sel:[1,0,0]
	v_cvt_scalef32_pk_bf16_fp8 v218, v132, 1.0
	v_cvt_scalef32_pk_bf16_fp8 v219, v132, 1.0 op_sel:[1,0,0]
	v_cvt_scalef32_pk_bf16_fp8 v220, v133, 1.0
	v_cvt_scalef32_pk_bf16_fp8 v221, v133, 1.0 op_sel:[1,0,0]
	v_dot2_f32_bf16 v227, v214, v74, 0
	v_dot2_f32_bf16 v227, v215, v75, v227
	v_dot2_f32_bf16 v227, v216, v76, v227
	v_dot2_f32_bf16 v227, v217, v77, v227
	v_dot2_f32_bf16 v227, v218, v142, v227
	v_dot2_f32_bf16 v227, v219, v143, v227
	v_dot2_f32_bf16 v227, v220, v144, v227
	v_dot2_f32_bf16 v227, v221, v145, v227
	s_nop 2
	s_waitcnt vmcnt(1)
	v_cvt_scalef32_pk_bf16_fp8 v216, v135, 1.0
	v_cvt_scalef32_pk_bf16_fp8 v214, v134, 1.0
	v_cvt_scalef32_pk_bf16_fp8 v215, v134, 1.0 op_sel:[1,0,0]
	v_cvt_scalef32_pk_bf16_fp8 v217, v135, 1.0 op_sel:[1,0,0]
	v_cvt_scalef32_pk_bf16_fp8 v218, v136, 1.0
	v_cvt_scalef32_pk_bf16_fp8 v219, v136, 1.0 op_sel:[1,0,0]
	v_cvt_scalef32_pk_bf16_fp8 v220, v137, 1.0
	v_cvt_scalef32_pk_bf16_fp8 v221, v137, 1.0 op_sel:[1,0,0]
	v_dot2_f32_bf16 v228, v214, v74, 0
	v_dot2_f32_bf16 v228, v215, v75, v228
	v_dot2_f32_bf16 v228, v216, v76, v228
	v_dot2_f32_bf16 v228, v217, v77, v228
	v_dot2_f32_bf16 v228, v218, v142, v228
	v_dot2_f32_bf16 v228, v219, v143, v228
	v_dot2_f32_bf16 v228, v220, v144, v228
	v_dot2_f32_bf16 v228, v221, v145, v228
	s_nop 2
	s_waitcnt vmcnt(0)
	v_cvt_scalef32_pk_bf16_fp8 v216, v139, 1.0
	v_cvt_scalef32_pk_bf16_fp8 v214, v138, 1.0
	v_cvt_scalef32_pk_bf16_fp8 v215, v138, 1.0 op_sel:[1,0,0]
	v_cvt_scalef32_pk_bf16_fp8 v217, v139, 1.0 op_sel:[1,0,0]
	v_cvt_scalef32_pk_bf16_fp8 v218, v140, 1.0
	v_cvt_scalef32_pk_bf16_fp8 v219, v140, 1.0 op_sel:[1,0,0]
	v_cvt_scalef32_pk_bf16_fp8 v221, v141, 1.0
	v_cvt_scalef32_pk_bf16_fp8 v229, v141, 1.0 op_sel:[1,0,0]
	v_dot2_f32_bf16 v230, v214, v74, 0
	v_dot2_f32_bf16 v230, v215, v75, v230
	v_dot2_f32_bf16 v230, v216, v76, v230
	v_dot2_f32_bf16 v230, v217, v77, v230
	v_dot2_f32_bf16 v230, v218, v142, v230
	v_dot2_f32_bf16 v230, v219, v143, v230
	v_dot2_f32_bf16 v230, v221, v144, v230
	v_dot2_f32_bf16 v230, v229, v145, v230
	s_nop 2
	v_cndmask_b32_e64 v216, v223, v227, s[12:13]
	ds_bpermute_b32 v216, v193, v216
	v_cndmask_b32_e64 v217, v224, v228, s[12:13]
	v_cndmask_b32_e64 v220, v222, v226, s[12:13]
	ds_bpermute_b32 v217, v193, v217
	v_cndmask_b32_e64 v218, v225, v230, s[12:13]
	ds_bpermute_b32 v220, v193, v220
	ds_bpermute_b32 v218, v193, v218
	v_cndmask_b32_e64 v215, v227, v223, s[12:13]
	s_waitcnt lgkmcnt(3)
	v_add_f32_e32 v215, v215, v216
	v_cndmask_b32_e64 v216, v228, v224, s[12:13]
	v_cndmask_b32_e64 v214, v226, v222, s[12:13]
	s_waitcnt lgkmcnt(2)
	v_add_f32_e32 v216, v216, v217
	v_cndmask_b32_e64 v217, v230, v225, s[12:13]
	s_waitcnt lgkmcnt(1)
	v_add_f32_e32 v214, v214, v220
	s_waitcnt lgkmcnt(0)
	v_add_f32_e32 v217, v217, v218
	v_cndmask_b32_e64 v218, v214, v216, s[14:15]
	v_cndmask_b32_e64 v219, v215, v217, s[14:15]
	ds_bpermute_b32 v218, v194, v218
	ds_bpermute_b32 v219, v194, v219
	v_cndmask_b32_e64 v214, v216, v214, s[14:15]
	v_cndmask_b32_e64 v215, v217, v215, s[14:15]
	v_cndmask_b32_e64 v213, v189, v212, s[16:17]
	s_waitcnt lgkmcnt(1)
	v_add_f32_e32 v214, v214, v218
	s_waitcnt lgkmcnt(0)
	v_add_f32_e32 v215, v215, v219
	ds_bpermute_b32 v213, v195, v213
	v_cndmask_b32_e64 v216, v214, v215, s[16:17]
	ds_bpermute_b32 v216, v195, v216
	v_cndmask_b32_e64 v189, v212, v189, s[16:17]
	s_waitcnt lgkmcnt(1)
	v_add_f32_e32 v217, v189, v213
	v_cndmask_b32_e64 v189, v215, v214, s[16:17]
	s_waitcnt lgkmcnt(0)
	v_add_f32_e32 v214, v189, v216
	s_setprio 0
	v_ashrrev_i32_e32 v189, 31, v188
	v_lshlrev_b64 v[212:213], 9, v[188:189]
	v_lshl_add_u64 v[212:213], v[184:185], 0, v[212:213]
	global_store_dword v[212:213], v217, off
	global_store_dword v[212:213], v214, off offset:256
	s_and_saveexec_b64 s[74:75], s[18:19]
	s_cbranch_execz .LBB0_530
	v_mov_b64_e32 v[144:145], v[72:73]
	v_mov_b64_e32 v[76:77], v[68:69]
	v_mov_b64_e32 v[142:143], v[70:71]
	v_mov_b64_e32 v[74:75], v[66:67]
	s_and_saveexec_b64 s[0:1], s[20:21]
	s_cbranch_execz .LBB0_538
	ds_bpermute_b32 v74, v1, v211
	ds_bpermute_b32 v76, v149, v211
	ds_bpermute_b32 v86, v153, v211
	ds_bpermute_b32 v88, v198, v211
	ds_bpermute_b32 v94, v199, v211
	s_waitcnt lgkmcnt(4)
	ds_bpermute_b32 v96, v200, v211
	s_waitcnt lgkmcnt(4)
	v_lshl_add_u32 v74, v74, 7, v252
	ds_bpermute_b32 v102, v201, v211
	v_lshl_add_u32 v76, v76, 7, v252
	s_waitcnt lgkmcnt(4)
	ds_bpermute_b32 v104, v202, v211
	global_load_dwordx4 v[78:81], v74, s[98:99]
	global_load_dwordx4 v[82:85], v76, s[98:99]
	v_lshl_add_u32 v74, v86, 7, v252
	s_waitcnt lgkmcnt(4)
	ds_bpermute_b32 v110, v1, v191
	v_lshl_add_u32 v76, v88, 7, v252
	s_waitcnt lgkmcnt(4)
	ds_bpermute_b32 v112, v149, v191
	global_load_dwordx4 v[86:89], v74, s[98:99]
	global_load_dwordx4 v[90:93], v76, s[98:99]
	v_lshl_add_u32 v74, v94, 7, v252
	s_waitcnt lgkmcnt(4)
	ds_bpermute_b32 v118, v153, v191
	v_lshl_add_u32 v76, v96, 7, v252
	s_waitcnt lgkmcnt(4)
	ds_bpermute_b32 v120, v198, v191
	global_load_dwordx4 v[94:97], v74, s[98:99]
	global_load_dwordx4 v[98:101], v76, s[98:99]
	v_lshl_add_u32 v74, v102, 7, v252
	s_waitcnt lgkmcnt(4)
	ds_bpermute_b32 v126, v199, v191
	v_lshl_add_u32 v76, v104, 7, v252
	s_waitcnt lgkmcnt(4)
	ds_bpermute_b32 v128, v200, v191
	global_load_dwordx4 v[102:105], v74, s[98:99]
	global_load_dwordx4 v[106:109], v76, s[98:99]
	v_lshl_add_u32 v74, v110, 7, v252
	s_waitcnt lgkmcnt(4)
	ds_bpermute_b32 v134, v201, v191
	v_lshl_add_u32 v76, v112, 7, v252
	s_waitcnt lgkmcnt(4)
	ds_bpermute_b32 v136, v202, v191
	global_load_dwordx4 v[110:113], v74, s[98:99]
	global_load_dwordx4 v[114:117], v76, s[98:99]
	v_lshl_add_u32 v74, v118, 7, v252
	s_waitcnt lgkmcnt(4)
	v_lshl_add_u32 v76, v120, 7, v252
	s_waitcnt lgkmcnt(3)
	global_load_dwordx4 v[118:121], v74, s[98:99]
	global_load_dwordx4 v[122:125], v76, s[98:99]
	v_lshl_add_u32 v74, v126, 7, v252
	s_waitcnt lgkmcnt(2)
	v_lshl_add_u32 v76, v128, 7, v252
	s_waitcnt lgkmcnt(1)
	global_load_dwordx4 v[126:129], v74, s[98:99]
	global_load_dwordx4 v[130:133], v76, s[98:99]
	v_lshl_add_u32 v74, v134, 7, v252
	s_waitcnt lgkmcnt(0)
	v_lshl_add_u32 v76, v136, 7, v252
	v_ashrrev_i32_e32 v191, 31, v190
	global_load_dwordx4 v[134:137], v74, s[98:99]
	global_load_dwordx4 v[138:141], v76, s[98:99]
	v_lshlrev_b64 v[74:75], 11, v[190:191]
	v_lshl_add_u64 v[74:75], v[182:183], 0, v[74:75]
	global_load_dwordx4 v[142:145], v[74:75], off offset:16
	s_nop 0
	global_load_dwordx4 v[74:77], v[74:75], off

; #define V_ISSUE(SEG, E0, E1) { _Pragma("unroll") for (int b = 0; b < 16; ++b) { const int e = __shfl((b < 8) ? (E0) : (E1), (b & 7) * 8 + grp); SEG[b] = *(const u32x4*)(vb + (size_t)e * DM); } }
; DI void peer_v_phase(const bf16_t* __restrict__ x1, const int* __restrict__ eidx, const float* __restrict__ wgt, const unsigned char* __restrict__ V8, bf16_t* __restrict__ y) {
;     ...
;     for (int j_ = sm.j0; j_ < 8 * REP_PV; j_ += sm.jstep) {
;         const int j = j_ & 7;
;         const unsigned char* vb = V8 + 128 * j + 16 * l8;
;         const int col = 128 * j + 16 * l8 + 2 * grp;
;         const int step = sm.nslot;
;         int t = sm.wslot;
;         if (t >= T_TOK) continue;
;         u32x4 sa[16], sb[16];
;         int e0n = 0, e1n = 0;
;         float w0, w1, w0n = 0.f, w1n = 0.f;
;     ...
;         {
;             const int e0 = eidx[(size_t)t * 128 + lane], e1 = eidx[(size_t)t * 128 + 64 + lane];
;             w0 = wgt[(size_t)t * 128 + lane]; w1 = wgt[(size_t)t * 128 + 64 + lane];
;             V_ISSUE(sa, e0, e1)
;             if (t + step < T_TOK) { e0n = eidx[(size_t)(t + step) * 128 + lane]; e1n = eidx[(size_t)(t + step) * 128 + 64 + lane]; }
;         }
.LBB0_654:
	s_and_saveexec_b64 s[72:73], vcc
	s_cbranch_execz .LBB0_653
	global_load_dword v67, v[136:137], off
	global_load_dword v69, v[138:139], off
	s_lshl_b32 s56, s27, 21
	v_lshl_add_u64 v[158:159], v[134:135], 0, s[56:57]
	s_lshl_b32 s56, s27, 7
	v_and_b32_e32 v252, 7, v172
	v_lshlrev_b32_e32 v252, 4, v252
	v_readfirstlane_b32 s98, v158
	v_readfirstlane_b32 s99, v159
	global_load_dword v189, v[140:141], off
	global_load_dword v191, v[142:143], off
	v_mov_b32_e32 v198, 0
	v_mov_b32_e32 v190, 0
	v_mov_b32_e32 v188, 0
	s_waitcnt vmcnt(3)
	ds_bpermute_b32 v66, v131, v67
	ds_bpermute_b32 v68, v149, v67
	ds_bpermute_b32 v70, v182, v67
	ds_bpermute_b32 v72, v183, v67
	ds_bpermute_b32 v74, v184, v67
	ds_bpermute_b32 v76, v185, v67
	ds_bpermute_b32 v78, v186, v67
	ds_bpermute_b32 v80, v187, v67
	s_waitcnt vmcnt(2)
	ds_bpermute_b32 v82, v131, v69
	ds_bpermute_b32 v84, v149, v69
	ds_bpermute_b32 v86, v182, v69
	ds_bpermute_b32 v88, v183, v69
	ds_bpermute_b32 v90, v184, v69
	ds_bpermute_b32 v92, v185, v69
	ds_bpermute_b32 v94, v186, v69
	ds_bpermute_b32 v96, v187, v69
	s_waitcnt lgkmcnt(0)
	v_lshl_add_u32 v66, v66, 7, v252
	v_lshl_add_u32 v68, v68, 7, v252
	v_lshl_add_u32 v70, v70, 7, v252
	v_lshl_add_u32 v72, v72, 7, v252
	v_lshl_add_u32 v74, v74, 7, v252
	v_lshl_add_u32 v76, v76, 7, v252
	v_lshl_add_u32 v78, v78, 7, v252
	v_lshl_add_u32 v80, v80, 7, v252
	v_lshl_add_u32 v82, v82, 7, v252
	v_lshl_add_u32 v84, v84, 7, v252
	v_lshl_add_u32 v86, v86, 7, v252
	v_lshl_add_u32 v88, v88, 7, v252
	v_lshl_add_u32 v90, v90, 7, v252
	v_lshl_add_u32 v92, v92, 7, v252
	v_lshl_add_u32 v94, v94, 7, v252
	v_lshl_add_u32 v96, v96, 7, v252
	v_mov_b32_e32 v98, v68
	v_mov_b32_e32 v100, v70
	v_mov_b32_e32 v102, v72
	v_mov_b32_e32 v104, v74
	v_mov_b32_e32 v106, v76
	v_mov_b32_e32 v108, v78
	v_mov_b32_e32 v110, v80
	v_mov_b32_e32 v112, v82
	v_mov_b32_e32 v114, v84
	v_mov_b32_e32 v116, v86
	v_mov_b32_e32 v118, v88
	v_mov_b32_e32 v120, v90
	v_mov_b32_e32 v122, v92
	v_mov_b32_e32 v124, v94
	v_mov_b32_e32 v126, v96
	global_load_dwordx4 v[66:69], v66, s[98:99]
	s_nop 0
	global_load_dwordx4 v[70:73], v98, s[98:99]
	global_load_dwordx4 v[74:77], v100, s[98:99]
	global_load_dwordx4 v[78:81], v102, s[98:99]
	global_load_dwordx4 v[82:85], v104, s[98:99]
	global_load_dwordx4 v[86:89], v106, s[98:99]
	global_load_dwordx4 v[90:93], v108, s[98:99]
	global_load_dwordx4 v[94:97], v110, s[98:99]
	global_load_dwordx4 v[98:101], v112, s[98:99]
	s_nop 0
	global_load_dwordx4 v[102:105], v114, s[98:99]
	global_load_dwordx4 v[106:109], v116, s[98:99]
	global_load_dwordx4 v[110:113], v118, s[98:99]
	s_nop 0
	global_load_dwordx4 v[114:117], v120, s[98:99]
	s_nop 0
	global_load_dwordx4 v[118:121], v122, s[98:99]
	s_nop 0
	global_load_dwordx4 v[122:125], v124, s[98:99]
	s_nop 0
	global_load_dwordx4 v[126:129], v126, s[98:99]
	s_and_saveexec_b64 s[0:1], s[10:11]
	s_cbranch_execz .LBB0_657
	global_load_dword v188, v[152:153], off
	global_load_dword v190, v[152:153], off offset:256

; #define V_ISSUE(SEG, E0, E1) { _Pragma("unroll") for (int b = 0; b < 16; ++b) { const int e = __shfl((b < 8) ? (E0) : (E1), (b & 7) * 8 + grp); SEG[b] = *(const u32x4*)(vb + (size_t)e * DM); } }
; DI void peer_v_phase(const bf16_t* __restrict__ x1, const int* __restrict__ eidx, const float* __restrict__ wgt, const unsigned char* __restrict__ V8, bf16_t* __restrict__ y) {
;     ...
;         {
;             const int e0 = eidx[(size_t)t * 128 + lane], e1 = eidx[(size_t)t * 128 + 64 + lane];
;             w0 = wgt[(size_t)t * 128 + lane]; w1 = wgt[(size_t)t * 128 + 64 + lane];
;             V_ISSUE(sa, e0, e1)
;             if (t + step < T_TOK) { e0n = eidx[(size_t)(t + step) * 128 + lane]; e1n = eidx[(size_t)(t + step) * 128 + 64 + lane]; }
;         }
;         for (; t < T_TOK; t += 2 * step) {
;             int e0nn = 0, e1nn = 0;
;             const bool n1 = t + step < T_TOK, n2 = t + 2 * step < T_TOK, n3 = t + 3 * step < T_TOK;
;             if (n1) { V_ISSUE(sb, e0n, e1n) w0n = wgt[(size_t)(t + step) * 128 + lane]; w1n = wgt[(size_t)(t + step) * 128 + 64 + lane]; }
.LBB0_660:
	v_add_u32_e32 v164, s54, v166
	v_cmp_gt_i32_e64 s[18:19], s24, v164
	v_ashrrev_i32_e32 v165, 31, v164
	s_and_saveexec_b64 s[0:1], s[18:19]
	s_cbranch_execz .LBB0_662
	s_waitcnt vmcnt(1)
	ds_bpermute_b32 v2, v131, v188
	ds_bpermute_b32 v4, v149, v188
	ds_bpermute_b32 v10, v182, v188
	ds_bpermute_b32 v12, v183, v188
	ds_bpermute_b32 v18, v184, v188
	ds_bpermute_b32 v20, v185, v188
	ds_bpermute_b32 v26, v186, v188
	ds_bpermute_b32 v28, v187, v188
	s_waitcnt vmcnt(0)
	ds_bpermute_b32 v34, v131, v190
	ds_bpermute_b32 v36, v149, v190
	ds_bpermute_b32 v42, v182, v190
	ds_bpermute_b32 v44, v183, v190
	ds_bpermute_b32 v50, v184, v190
	ds_bpermute_b32 v52, v185, v190
	ds_bpermute_b32 v58, v186, v190
	ds_bpermute_b32 v60, v187, v190
	s_waitcnt lgkmcnt(0)
	v_lshl_add_u32 v2, v2, 7, v252
	v_lshl_add_u32 v4, v4, 7, v252
	v_lshl_add_u32 v10, v10, 7, v252
	v_lshl_add_u32 v12, v12, 7, v252
	v_lshl_add_u32 v18, v18, 7, v252
	v_lshl_add_u32 v20, v20, 7, v252
	v_lshl_add_u32 v26, v26, 7, v252
	v_lshl_add_u32 v28, v28, 7, v252
	v_lshl_add_u32 v34, v34, 7, v252
	v_lshl_add_u32 v36, v36, 7, v252
	v_lshl_add_u32 v42, v42, 7, v252
	v_lshl_add_u32 v44, v44, 7, v252
	v_lshl_add_u32 v50, v50, 7, v252
	v_lshl_add_u32 v52, v52, 7, v252
	v_lshl_add_u32 v58, v58, 7, v252
	v_lshl_add_u32 v60, v60, 7, v252
	v_lshlrev_b64 v[168:169], 9, v[164:165]
	v_mov_b32_e32 v22, v20
	v_mov_b32_e32 v30, v28
	v_mov_b32_e32 v38, v36
	v_mov_b32_e32 v46, v44
	v_mov_b32_e32 v54, v52
	v_mov_b32_e32 v62, v60
	v_lshl_add_u64 v[168:169], v[154:155], 0, v[168:169]
	global_load_dwordx4 v[6:9], v2, s[98:99]
	s_nop 0
	global_load_dwordx4 v[2:5], v4, s[98:99]
	s_nop 0
	global_load_dwordx4 v[14:17], v10, s[98:99]
	s_nop 0
	global_load_dwordx4 v[10:13], v12, s[98:99]
	s_nop 0
	global_load_dwordx4 v[18:21], v18, s[98:99]
	s_nop 0
	global_load_dwordx4 v[22:25], v22, s[98:99]
	s_nop 0
	global_load_dwordx4 v[26:29], v26, s[98:99]
	s_nop 0
	global_load_dwordx4 v[30:33], v30, s[98:99]
	s_nop 0
	global_load_dwordx4 v[34:37], v34, s[98:99]
	s_nop 0
	global_load_dwordx4 v[38:41], v38, s[98:99]
	s_nop 0
	global_load_dwordx4 v[42:45], v42, s[98:99]
	s_nop 0
	global_load_dwordx4 v[46:49], v46, s[98:99]
	s_nop 0
	global_load_dwordx4 v[50:53], v50, s[98:99]
	s_nop 0
	global_load_dwordx4 v[54:57], v54, s[98:99]
	s_nop 0
	global_load_dwordx4 v[58:61], v58, s[98:99]
	s_nop 0
	global_load_dwordx4 v[62:65], v62, s[98:99]
	s_nop 0
	global_load_dword v198, v[168:169], off
	global_load_dword v132, v[168:169], off offset:256

; DI void axpy_fp8_row(f32x2 (&o)[8], float wgt, u32x4 v) {
;     const f32x2 w2 = {wgt, wgt};
; #pragma unroll
;     for (int j = 0; j < 4; ++j) {
;         const f32x2 lo = __builtin_amdgcn_cvt_pk_f32_fp8(v[j], false), hi = __builtin_amdgcn_cvt_pk_f32_fp8(v[j], true);
;         o[2 * j] = __builtin_elementwise_fma(w2, lo, o[2 * j]);
;         o[2 * j + 1] = __builtin_elementwise_fma(w2, hi, o[2 * j + 1]);
;     }
; }
.LBB0_664:
	s_or_b64 exec, exec, s[0:1]
	s_setprio 1
	s_waitcnt vmcnt(17)
	ds_bpermute_b32 v200, v131, v189
	s_waitcnt vmcnt(15)
	v_cvt_pk_f32_fp8_e32 v[202:203], v66
	v_cvt_pk_f32_fp8_sdwa v[210:211], v66 src0_sel:WORD_1
	v_cvt_pk_f32_fp8_e32 v[212:213], v67
	v_cvt_pk_f32_fp8_sdwa v[214:215], v67 src0_sel:WORD_1
	v_cvt_pk_f32_fp8_e32 v[216:217], v68
	v_cvt_pk_f32_fp8_sdwa v[218:219], v68 src0_sel:WORD_1
	v_cvt_pk_f32_fp8_e32 v[220:221], v69
	v_cvt_pk_f32_fp8_sdwa v[222:223], v69 src0_sel:WORD_1
	s_waitcnt lgkmcnt(0)
	v_pk_fma_f32 v[202:203], v[200:201], v[202:203], 0 op_sel_hi:[0,1,0]
	v_pk_fma_f32 v[210:211], v[200:201], v[210:211], 0 op_sel_hi:[0,1,0]
	v_pk_fma_f32 v[212:213], v[200:201], v[212:213], 0 op_sel_hi:[0,1,0]
	v_pk_fma_f32 v[214:215], v[200:201], v[214:215], 0 op_sel_hi:[0,1,0]
	v_pk_fma_f32 v[216:217], v[200:201], v[216:217], 0 op_sel_hi:[0,1,0]
	v_pk_fma_f32 v[218:219], v[200:201], v[218:219], 0 op_sel_hi:[0,1,0]
	v_pk_fma_f32 v[220:221], v[200:201], v[220:221], 0 op_sel_hi:[0,1,0]
	v_pk_fma_f32 v[200:201], v[200:201], v[222:223], 0 op_sel_hi:[0,1,0]
	ds_bpermute_b32 v222, v149, v189
	s_waitcnt vmcnt(14)
	v_cvt_pk_f32_fp8_e32 v[224:225], v70
	v_cvt_pk_f32_fp8_sdwa v[226:227], v70 src0_sel:WORD_1
	v_cvt_pk_f32_fp8_e32 v[228:229], v71
	v_cvt_pk_f32_fp8_sdwa v[230:231], v71 src0_sel:WORD_1
	s_waitcnt lgkmcnt(0)
	v_pk_fma_f32 v[202:203], v[222:223], v[224:225], v[202:203] op_sel_hi:[0,1,1]
	v_pk_fma_f32 v[210:211], v[222:223], v[226:227], v[210:211] op_sel_hi:[0,1,1]
	v_pk_fma_f32 v[212:213], v[222:223], v[228:229], v[212:213] op_sel_hi:[0,1,1]
	v_pk_fma_f32 v[214:215], v[222:223], v[230:231], v[214:215] op_sel_hi:[0,1,1]
	v_cvt_pk_f32_fp8_e32 v[224:225], v72
	v_cvt_pk_f32_fp8_sdwa v[226:227], v72 src0_sel:WORD_1
	v_cvt_pk_f32_fp8_e32 v[228:229], v73
	v_cvt_pk_f32_fp8_sdwa v[230:231], v73 src0_sel:WORD_1
	v_pk_fma_f32 v[216:217], v[222:223], v[224:225], v[216:217] op_sel_hi:[0,1,1]
	v_pk_fma_f32 v[218:219], v[222:223], v[226:227], v[218:219] op_sel_hi:[0,1,1]
	v_pk_fma_f32 v[220:221], v[222:223], v[228:229], v[220:221] op_sel_hi:[0,1,1]
	v_pk_fma_f32 v[200:201], v[222:223], v[230:231], v[200:201] op_sel_hi:[0,1,1]
	ds_bpermute_b32 v222, v182, v189
	s_waitcnt vmcnt(13)
	v_cvt_pk_f32_fp8_e32 v[224:225], v74
	v_cvt_pk_f32_fp8_sdwa v[226:227], v74 src0_sel:WORD_1
	v_cvt_pk_f32_fp8_e32 v[228:229], v75
	v_cvt_pk_f32_fp8_sdwa v[230:231], v75 src0_sel:WORD_1
	s_waitcnt lgkmcnt(0)
	v_pk_fma_f32 v[202:203], v[222:223], v[224:225], v[202:203] op_sel_hi:[0,1,1]
	v_pk_fma_f32 v[210:211], v[222:223], v[226:227], v[210:211] op_sel_hi:[0,1,1]
	v_pk_fma_f32 v[212:213], v[222:223], v[228:229], v[212:213] op_sel_hi:[0,1,1]
	v_pk_fma_f32 v[214:215], v[222:223], v[230:231], v[214:215] op_sel_hi:[0,1,1]
	v_cvt_pk_f32_fp8_e32 v[224:225], v76
	v_cvt_pk_f32_fp8_sdwa v[226:227], v76 src0_sel:WORD_1
	v_cvt_pk_f32_fp8_e32 v[228:229], v77
	v_cvt_pk_f32_fp8_sdwa v[230:231], v77 src0_sel:WORD_1
	v_pk_fma_f32 v[216:217], v[222:223], v[224:225], v[216:217] op_sel_hi:[0,1,1]
	v_pk_fma_f32 v[218:219], v[222:223], v[226:227], v[218:219] op_sel_hi:[0,1,1]
	v_pk_fma_f32 v[220:221], v[222:223], v[228:229], v[220:221] op_sel_hi:[0,1,1]
	v_pk_fma_f32 v[200:201], v[222:223], v[230:231], v[200:201] op_sel_hi:[0,1,1]
	ds_bpermute_b32 v222, v183, v189
	s_waitcnt vmcnt(12)
	v_cvt_pk_f32_fp8_e32 v[224:225], v78
	v_cvt_pk_f32_fp8_sdwa v[226:227], v78 src0_sel:WORD_1
	v_cvt_pk_f32_fp8_e32 v[228:229], v79
	v_cvt_pk_f32_fp8_sdwa v[230:231], v79 src0_sel:WORD_1
	s_waitcnt lgkmcnt(0)
	v_pk_fma_f32 v[202:203], v[222:223], v[224:225], v[202:203] op_sel_hi:[0,1,1]
	v_pk_fma_f32 v[210:211], v[222:223], v[226:227], v[210:211] op_sel_hi:[0,1,1]
	v_pk_fma_f32 v[212:213], v[222:223], v[228:229], v[212:213] op_sel_hi:[0,1,1]
	v_pk_fma_f32 v[214:215], v[222:223], v[230:231], v[214:215] op_sel_hi:[0,1,1]
	v_cvt_pk_f32_fp8_e32 v[224:225], v80
	v_cvt_pk_f32_fp8_sdwa v[226:227], v80 src0_sel:WORD_1
	v_cvt_pk_f32_fp8_e32 v[228:229], v81
	v_cvt_pk_f32_fp8_sdwa v[230:231], v81 src0_sel:WORD_1
	v_pk_fma_f32 v[216:217], v[222:223], v[224:225], v[216:217] op_sel_hi:[0,1,1]
	v_pk_fma_f32 v[218:219], v[222:223], v[226:227], v[218:219] op_sel_hi:[0,1,1]
	v_pk_fma_f32 v[220:221], v[222:223], v[228:229], v[220:221] op_sel_hi:[0,1,1]
	v_pk_fma_f32 v[200:201], v[222:223], v[230:231], v[200:201] op_sel_hi:[0,1,1]
	ds_bpermute_b32 v222, v184, v189
	s_waitcnt vmcnt(11)
	v_cvt_pk_f32_fp8_e32 v[224:225], v82
	v_cvt_pk_f32_fp8_sdwa v[226:227], v82 src0_sel:WORD_1
	v_cvt_pk_f32_fp8_e32 v[228:229], v83
	v_cvt_pk_f32_fp8_sdwa v[230:231], v83 src0_sel:WORD_1
	s_waitcnt lgkmcnt(0)
	v_pk_fma_f32 v[202:203], v[222:223], v[224:225], v[202:203] op_sel_hi:[0,1,1]
	v_pk_fma_f32 v[210:211], v[222:223], v[226:227], v[210:211] op_sel_hi:[0,1,1]
	v_pk_fma_f32 v[212:213], v[222:223], v[228:229], v[212:213] op_sel_hi:[0,1,1]
	v_pk_fma_f32 v[214:215], v[222:223], v[230:231], v[214:215] op_sel_hi:[0,1,1]
	v_cvt_pk_f32_fp8_e32 v[224:225], v84
	v_cvt_pk_f32_fp8_sdwa v[226:227], v84 src0_sel:WORD_1
	v_cvt_pk_f32_fp8_e32 v[228:229], v85
	v_cvt_pk_f32_fp8_sdwa v[230:231], v85 src0_sel:WORD_1
	v_pk_fma_f32 v[216:217], v[222:223], v[224:225], v[216:217] op_sel_hi:[0,1,1]
	v_pk_fma_f32 v[218:219], v[222:223], v[226:227], v[218:219] op_sel_hi:[0,1,1]
	v_pk_fma_f32 v[220:221], v[222:223], v[228:229], v[220:221] op_sel_hi:[0,1,1]
	v_pk_fma_f32 v[200:201], v[222:223], v[230:231], v[200:201] op_sel_hi:[0,1,1]
	ds_bpermute_b32 v222, v185, v189
	s_waitcnt vmcnt(10)
	v_cvt_pk_f32_fp8_e32 v[224:225], v86
	v_cvt_pk_f32_fp8_sdwa v[226:227], v86 src0_sel:WORD_1
	v_cvt_pk_f32_fp8_e32 v[228:229], v87
	v_cvt_pk_f32_fp8_sdwa v[230:231], v87 src0_sel:WORD_1
	s_waitcnt lgkmcnt(0)
; DI void axpy_fp8_row(f32x2 (&o)[8], float wgt, u32x4 v) {
;     const f32x2 w2 = {wgt, wgt};
; #pragma unroll
;     for (int j = 0; j < 4; ++j) {
;         const f32x2 lo = __builtin_amdgcn_cvt_pk_f32_fp8(v[j], false), hi = __builtin_amdgcn_cvt_pk_f32_fp8(v[j], true);
;         o[2 * j] = __builtin_elementwise_fma(w2, lo, o[2 * j]);
;         o[2 * j + 1] = __builtin_elementwise_fma(w2, hi, o[2 * j + 1]);
;     }
; }
	v_pk_fma_f32 v[202:203], v[222:223], v[224:225], v[202:203] op_sel_hi:[0,1,1]
	v_pk_fma_f32 v[210:211], v[222:223], v[226:227], v[210:211] op_sel_hi:[0,1,1]
	v_pk_fma_f32 v[212:213], v[222:223], v[228:229], v[212:213] op_sel_hi:[0,1,1]
	v_pk_fma_f32 v[214:215], v[222:223], v[230:231], v[214:215] op_sel_hi:[0,1,1]
	v_cvt_pk_f32_fp8_e32 v[224:225], v88
	v_cvt_pk_f32_fp8_sdwa v[226:227], v88 src0_sel:WORD_1
	v_cvt_pk_f32_fp8_e32 v[228:229], v89
	v_cvt_pk_f32_fp8_sdwa v[230:231], v89 src0_sel:WORD_1
	v_pk_fma_f32 v[216:217], v[222:223], v[224:225], v[216:217] op_sel_hi:[0,1,1]
	v_pk_fma_f32 v[218:219], v[222:223], v[226:227], v[218:219] op_sel_hi:[0,1,1]
	v_pk_fma_f32 v[220:221], v[222:223], v[228:229], v[220:221] op_sel_hi:[0,1,1]
	v_pk_fma_f32 v[200:201], v[222:223], v[230:231], v[200:201] op_sel_hi:[0,1,1]
	ds_bpermute_b32 v222, v186, v189
	s_waitcnt vmcnt(9)
	v_cvt_pk_f32_fp8_e32 v[224:225], v90
	v_cvt_pk_f32_fp8_sdwa v[226:227], v90 src0_sel:WORD_1
	v_cvt_pk_f32_fp8_e32 v[228:229], v91
	v_cvt_pk_f32_fp8_sdwa v[230:231], v91 src0_sel:WORD_1
	s_waitcnt lgkmcnt(0)
	v_pk_fma_f32 v[202:203], v[222:223], v[224:225], v[202:203] op_sel_hi:[0,1,1]
	v_pk_fma_f32 v[210:211], v[222:223], v[226:227], v[210:211] op_sel_hi:[0,1,1]
	v_pk_fma_f32 v[212:213], v[222:223], v[228:229], v[212:213] op_sel_hi:[0,1,1]
	v_pk_fma_f32 v[214:215], v[222:223], v[230:231], v[214:215] op_sel_hi:[0,1,1]
	v_cvt_pk_f32_fp8_e32 v[224:225], v92
	v_cvt_pk_f32_fp8_sdwa v[226:227], v92 src0_sel:WORD_1
	v_cvt_pk_f32_fp8_e32 v[228:229], v93
	v_cvt_pk_f32_fp8_sdwa v[230:231], v93 src0_sel:WORD_1
	v_pk_fma_f32 v[216:217], v[222:223], v[224:225], v[216:217] op_sel_hi:[0,1,1]
	v_pk_fma_f32 v[218:219], v[222:223], v[226:227], v[218:219] op_sel_hi:[0,1,1]
	v_pk_fma_f32 v[220:221], v[222:223], v[228:229], v[220:221] op_sel_hi:[0,1,1]
	v_pk_fma_f32 v[200:201], v[222:223], v[230:231], v[200:201] op_sel_hi:[0,1,1]
	ds_bpermute_b32 v222, v187, v189
	s_waitcnt vmcnt(8)
	v_cvt_pk_f32_fp8_e32 v[224:225], v94
	v_cvt_pk_f32_fp8_sdwa v[226:227], v94 src0_sel:WORD_1
	v_cvt_pk_f32_fp8_e32 v[228:229], v95
	v_cvt_pk_f32_fp8_sdwa v[230:231], v95 src0_sel:WORD_1
	s_waitcnt lgkmcnt(0)
	v_pk_fma_f32 v[202:203], v[222:223], v[224:225], v[202:203] op_sel_hi:[0,1,1]
	v_pk_fma_f32 v[210:211], v[222:223], v[226:227], v[210:211] op_sel_hi:[0,1,1]
	v_pk_fma_f32 v[212:213], v[222:223], v[228:229], v[212:213] op_sel_hi:[0,1,1]
	v_pk_fma_f32 v[214:215], v[222:223], v[230:231], v[214:215] op_sel_hi:[0,1,1]
	v_cvt_pk_f32_fp8_e32 v[224:225], v96
	v_cvt_pk_f32_fp8_sdwa v[226:227], v96 src0_sel:WORD_1
	v_cvt_pk_f32_fp8_e32 v[228:229], v97
	v_cvt_pk_f32_fp8_sdwa v[230:231], v97 src0_sel:WORD_1
	v_pk_fma_f32 v[216:217], v[222:223], v[224:225], v[216:217] op_sel_hi:[0,1,1]
	v_pk_fma_f32 v[218:219], v[222:223], v[226:227], v[218:219] op_sel_hi:[0,1,1]
	v_pk_fma_f32 v[220:221], v[222:223], v[228:229], v[220:221] op_sel_hi:[0,1,1]
	v_pk_fma_f32 v[200:201], v[222:223], v[230:231], v[200:201] op_sel_hi:[0,1,1]
	ds_bpermute_b32 v222, v131, v191
	s_waitcnt vmcnt(7)
	v_cvt_pk_f32_fp8_e32 v[224:225], v98
	v_cvt_pk_f32_fp8_sdwa v[226:227], v98 src0_sel:WORD_1
	v_cvt_pk_f32_fp8_e32 v[228:229], v99
	v_cvt_pk_f32_fp8_sdwa v[230:231], v99 src0_sel:WORD_1
	s_waitcnt lgkmcnt(0)
	v_pk_fma_f32 v[202:203], v[222:223], v[224:225], v[202:203] op_sel_hi:[0,1,1]
	v_pk_fma_f32 v[210:211], v[222:223], v[226:227], v[210:211] op_sel_hi:[0,1,1]
	v_pk_fma_f32 v[212:213], v[222:223], v[228:229], v[212:213] op_sel_hi:[0,1,1]
	v_pk_fma_f32 v[214:215], v[222:223], v[230:231], v[214:215] op_sel_hi:[0,1,1]
	v_cvt_pk_f32_fp8_e32 v[224:225], v100
	v_cvt_pk_f32_fp8_sdwa v[226:227], v100 src0_sel:WORD_1
	v_cvt_pk_f32_fp8_e32 v[228:229], v101
	v_cvt_pk_f32_fp8_sdwa v[230:231], v101 src0_sel:WORD_1
	v_pk_fma_f32 v[216:217], v[222:223], v[224:225], v[216:217] op_sel_hi:[0,1,1]
	v_pk_fma_f32 v[218:219], v[222:223], v[226:227], v[218:219] op_sel_hi:[0,1,1]
	v_pk_fma_f32 v[220:221], v[222:223], v[228:229], v[220:221] op_sel_hi:[0,1,1]
	v_pk_fma_f32 v[200:201], v[222:223], v[230:231], v[200:201] op_sel_hi:[0,1,1]
	ds_bpermute_b32 v222, v149, v191
	s_waitcnt vmcnt(6)
	v_cvt_pk_f32_fp8_e32 v[224:225], v102
	v_cvt_pk_f32_fp8_sdwa v[226:227], v102 src0_sel:WORD_1
	v_cvt_pk_f32_fp8_e32 v[228:229], v103
	v_cvt_pk_f32_fp8_sdwa v[230:231], v103 src0_sel:WORD_1
	s_waitcnt lgkmcnt(0)
	v_pk_fma_f32 v[202:203], v[222:223], v[224:225], v[202:203] op_sel_hi:[0,1,1]
	v_pk_fma_f32 v[210:211], v[222:223], v[226:227], v[210:211] op_sel_hi:[0,1,1]
	v_pk_fma_f32 v[212:213], v[222:223], v[228:229], v[212:213] op_sel_hi:[0,1,1]
	v_pk_fma_f32 v[214:215], v[222:223], v[230:231], v[214:215] op_sel_hi:[0,1,1]
	v_cvt_pk_f32_fp8_e32 v[224:225], v104
	v_cvt_pk_f32_fp8_sdwa v[226:227], v104 src0_sel:WORD_1
	v_cvt_pk_f32_fp8_e32 v[228:229], v105
	v_cvt_pk_f32_fp8_sdwa v[230:231], v105 src0_sel:WORD_1
	v_pk_fma_f32 v[216:217], v[222:223], v[224:225], v[216:217] op_sel_hi:[0,1,1]
	v_pk_fma_f32 v[218:219], v[222:223], v[226:227], v[218:219] op_sel_hi:[0,1,1]
	v_pk_fma_f32 v[220:221], v[222:223], v[228:229], v[220:221] op_sel_hi:[0,1,1]
	v_pk_fma_f32 v[200:201], v[222:223], v[230:231], v[200:201] op_sel_hi:[0,1,1]
	ds_bpermute_b32 v222, v182, v191
	s_waitcnt vmcnt(5)
	v_cvt_pk_f32_fp8_e32 v[224:225], v106
	v_cvt_pk_f32_fp8_sdwa v[226:227], v106 src0_sel:WORD_1
	v_cvt_pk_f32_fp8_e32 v[228:229], v107
	v_cvt_pk_f32_fp8_sdwa v[230:231], v107 src0_sel:WORD_1
	s_waitcnt lgkmcnt(0)
; DI void axpy_fp8_row(f32x2 (&o)[8], float wgt, u32x4 v) {
;     const f32x2 w2 = {wgt, wgt};
; #pragma unroll
;     for (int j = 0; j < 4; ++j) {
;         const f32x2 lo = __builtin_amdgcn_cvt_pk_f32_fp8(v[j], false), hi = __builtin_amdgcn_cvt_pk_f32_fp8(v[j], true);
;         o[2 * j] = __builtin_elementwise_fma(w2, lo, o[2 * j]);
;         o[2 * j + 1] = __builtin_elementwise_fma(w2, hi, o[2 * j + 1]);
;     }
; }
	v_pk_fma_f32 v[202:203], v[222:223], v[224:225], v[202:203] op_sel_hi:[0,1,1]
	v_pk_fma_f32 v[210:211], v[222:223], v[226:227], v[210:211] op_sel_hi:[0,1,1]
	v_pk_fma_f32 v[212:213], v[222:223], v[228:229], v[212:213] op_sel_hi:[0,1,1]
	v_pk_fma_f32 v[214:215], v[222:223], v[230:231], v[214:215] op_sel_hi:[0,1,1]
	v_cvt_pk_f32_fp8_e32 v[224:225], v108
	v_cvt_pk_f32_fp8_sdwa v[226:227], v108 src0_sel:WORD_1
	v_cvt_pk_f32_fp8_e32 v[228:229], v109
	v_cvt_pk_f32_fp8_sdwa v[230:231], v109 src0_sel:WORD_1
	v_pk_fma_f32 v[216:217], v[222:223], v[224:225], v[216:217] op_sel_hi:[0,1,1]
	v_pk_fma_f32 v[218:219], v[222:223], v[226:227], v[218:219] op_sel_hi:[0,1,1]
	v_pk_fma_f32 v[220:221], v[222:223], v[228:229], v[220:221] op_sel_hi:[0,1,1]
	v_pk_fma_f32 v[200:201], v[222:223], v[230:231], v[200:201] op_sel_hi:[0,1,1]
	ds_bpermute_b32 v222, v183, v191
	s_waitcnt vmcnt(4)
	v_cvt_pk_f32_fp8_e32 v[224:225], v110
	v_cvt_pk_f32_fp8_sdwa v[226:227], v110 src0_sel:WORD_1
	v_cvt_pk_f32_fp8_e32 v[228:229], v111
	v_cvt_pk_f32_fp8_sdwa v[230:231], v111 src0_sel:WORD_1
	s_waitcnt lgkmcnt(0)
	v_pk_fma_f32 v[202:203], v[222:223], v[224:225], v[202:203] op_sel_hi:[0,1,1]
	v_pk_fma_f32 v[210:211], v[222:223], v[226:227], v[210:211] op_sel_hi:[0,1,1]
	v_pk_fma_f32 v[212:213], v[222:223], v[228:229], v[212:213] op_sel_hi:[0,1,1]
	v_pk_fma_f32 v[214:215], v[222:223], v[230:231], v[214:215] op_sel_hi:[0,1,1]
	v_cvt_pk_f32_fp8_e32 v[224:225], v112
	v_cvt_pk_f32_fp8_sdwa v[226:227], v112 src0_sel:WORD_1
	v_cvt_pk_f32_fp8_e32 v[228:229], v113
	v_cvt_pk_f32_fp8_sdwa v[230:231], v113 src0_sel:WORD_1
	v_pk_fma_f32 v[216:217], v[222:223], v[224:225], v[216:217] op_sel_hi:[0,1,1]
	v_pk_fma_f32 v[218:219], v[222:223], v[226:227], v[218:219] op_sel_hi:[0,1,1]
	v_pk_fma_f32 v[220:221], v[222:223], v[228:229], v[220:221] op_sel_hi:[0,1,1]
	v_pk_fma_f32 v[200:201], v[222:223], v[230:231], v[200:201] op_sel_hi:[0,1,1]
	ds_bpermute_b32 v222, v184, v191
	s_waitcnt vmcnt(3)
	v_cvt_pk_f32_fp8_e32 v[224:225], v114
	v_cvt_pk_f32_fp8_sdwa v[226:227], v114 src0_sel:WORD_1
	v_cvt_pk_f32_fp8_e32 v[228:229], v115
	v_cvt_pk_f32_fp8_sdwa v[230:231], v115 src0_sel:WORD_1
	s_waitcnt lgkmcnt(0)
	v_pk_fma_f32 v[202:203], v[222:223], v[224:225], v[202:203] op_sel_hi:[0,1,1]
	v_pk_fma_f32 v[210:211], v[222:223], v[226:227], v[210:211] op_sel_hi:[0,1,1]
	v_pk_fma_f32 v[212:213], v[222:223], v[228:229], v[212:213] op_sel_hi:[0,1,1]
	v_pk_fma_f32 v[214:215], v[222:223], v[230:231], v[214:215] op_sel_hi:[0,1,1]
	v_cvt_pk_f32_fp8_e32 v[224:225], v116
	v_cvt_pk_f32_fp8_sdwa v[226:227], v116 src0_sel:WORD_1
	v_cvt_pk_f32_fp8_e32 v[228:229], v117
	v_cvt_pk_f32_fp8_sdwa v[230:231], v117 src0_sel:WORD_1
	v_pk_fma_f32 v[216:217], v[222:223], v[224:225], v[216:217] op_sel_hi:[0,1,1]
	v_pk_fma_f32 v[218:219], v[222:223], v[226:227], v[218:219] op_sel_hi:[0,1,1]
	v_pk_fma_f32 v[220:221], v[222:223], v[228:229], v[220:221] op_sel_hi:[0,1,1]
	v_pk_fma_f32 v[200:201], v[222:223], v[230:231], v[200:201] op_sel_hi:[0,1,1]
	ds_bpermute_b32 v222, v185, v191
	s_waitcnt vmcnt(2)
	v_cvt_pk_f32_fp8_e32 v[224:225], v118
	v_cvt_pk_f32_fp8_sdwa v[226:227], v118 src0_sel:WORD_1
	v_cvt_pk_f32_fp8_e32 v[228:229], v119
	v_cvt_pk_f32_fp8_sdwa v[230:231], v119 src0_sel:WORD_1
	s_waitcnt lgkmcnt(0)
	v_pk_fma_f32 v[202:203], v[222:223], v[224:225], v[202:203] op_sel_hi:[0,1,1]
	v_pk_fma_f32 v[210:211], v[222:223], v[226:227], v[210:211] op_sel_hi:[0,1,1]
	v_pk_fma_f32 v[212:213], v[222:223], v[228:229], v[212:213] op_sel_hi:[0,1,1]
	v_pk_fma_f32 v[214:215], v[222:223], v[230:231], v[214:215] op_sel_hi:[0,1,1]
	v_cvt_pk_f32_fp8_e32 v[224:225], v120
	v_cvt_pk_f32_fp8_sdwa v[226:227], v120 src0_sel:WORD_1
	v_cvt_pk_f32_fp8_e32 v[228:229], v121
	v_cvt_pk_f32_fp8_sdwa v[230:231], v121 src0_sel:WORD_1
	v_pk_fma_f32 v[216:217], v[222:223], v[224:225], v[216:217] op_sel_hi:[0,1,1]
	v_pk_fma_f32 v[218:219], v[222:223], v[226:227], v[218:219] op_sel_hi:[0,1,1]
	v_pk_fma_f32 v[220:221], v[222:223], v[228:229], v[220:221] op_sel_hi:[0,1,1]
	v_pk_fma_f32 v[200:201], v[222:223], v[230:231], v[200:201] op_sel_hi:[0,1,1]
	ds_bpermute_b32 v222, v186, v191
	s_waitcnt vmcnt(1)
	v_cvt_pk_f32_fp8_e32 v[224:225], v122
	v_cvt_pk_f32_fp8_sdwa v[226:227], v122 src0_sel:WORD_1
	v_cvt_pk_f32_fp8_e32 v[228:229], v123
	v_cvt_pk_f32_fp8_sdwa v[230:231], v123 src0_sel:WORD_1
	s_waitcnt lgkmcnt(0)
	v_pk_fma_f32 v[202:203], v[222:223], v[224:225], v[202:203] op_sel_hi:[0,1,1]
	v_pk_fma_f32 v[210:211], v[222:223], v[226:227], v[210:211] op_sel_hi:[0,1,1]
	v_pk_fma_f32 v[212:213], v[222:223], v[228:229], v[212:213] op_sel_hi:[0,1,1]
	v_pk_fma_f32 v[214:215], v[222:223], v[230:231], v[214:215] op_sel_hi:[0,1,1]
	v_cvt_pk_f32_fp8_e32 v[224:225], v124
	v_cvt_pk_f32_fp8_sdwa v[226:227], v124 src0_sel:WORD_1
	v_cvt_pk_f32_fp8_e32 v[228:229], v125
	v_cvt_pk_f32_fp8_sdwa v[230:231], v125 src0_sel:WORD_1
	v_pk_fma_f32 v[216:217], v[222:223], v[224:225], v[216:217] op_sel_hi:[0,1,1]
	v_pk_fma_f32 v[218:219], v[222:223], v[226:227], v[218:219] op_sel_hi:[0,1,1]
	v_pk_fma_f32 v[220:221], v[222:223], v[228:229], v[220:221] op_sel_hi:[0,1,1]
	v_pk_fma_f32 v[200:201], v[222:223], v[230:231], v[200:201] op_sel_hi:[0,1,1]
	ds_bpermute_b32 v222, v187, v191
	s_waitcnt vmcnt(0)
	v_cvt_pk_f32_fp8_e32 v[224:225], v126
	v_cvt_pk_f32_fp8_sdwa v[226:227], v126 src0_sel:WORD_1
	v_cvt_pk_f32_fp8_e32 v[228:229], v127
	v_cvt_pk_f32_fp8_sdwa v[230:231], v127 src0_sel:WORD_1
	s_waitcnt lgkmcnt(0)
; #define V_ISSUE(SEG, E0, E1) { _Pragma("unroll") for (int b = 0; b < 16; ++b) { const int e = __shfl((b < 8) ? (E0) : (E1), (b & 7) * 8 + grp); SEG[b] = *(const u32x4*)(vb + (size_t)e * DM); } }
; DI void peer_v_phase(const bf16_t* __restrict__ x1, const int* __restrict__ eidx, const float* __restrict__ wgt, const unsigned char* __restrict__ V8, bf16_t* __restrict__ y) {
;     ...
;         {
;             const int e0 = eidx[(size_t)t * 128 + lane], e1 = eidx[(size_t)t * 128 + 64 + lane];
;             w0 = wgt[(size_t)t * 128 + lane]; w1 = wgt[(size_t)t * 128 + 64 + lane];
;             V_ISSUE(sa, e0, e1)
;             if (t + step < T_TOK) { e0n = eidx[(size_t)(t + step) * 128 + lane]; e1n = eidx[(size_t)(t + step) * 128 + 64 + lane]; }
;         }
;         for (; t < T_TOK; t += 2 * step) {
;             int e0nn = 0, e1nn = 0;
;             const bool n1 = t + step < T_TOK, n2 = t + 2 * step < T_TOK, n3 = t + 3 * step < T_TOK;
;             if (n1) { V_ISSUE(sb, e0n, e1n) w0n = wgt[(size_t)(t + step) * 128 + lane]; w1n = wgt[(size_t)(t + step) * 128 + 64 + lane]; }
;             if (n2) { e0nn = eidx[(size_t)(t + 2 * step) * 128 + lane]; e1nn = eidx[(size_t)(t + 2 * step) * 128 + 64 + lane]; }
;             V_COMPUTE(sa, t)
;             if (n1) {
;                 w0 = w0n; w1 = w1n;
;                 if (n2) { V_ISSUE(sa, e0nn, e1nn) w0n = wgt[(size_t)(t + 2 * step) * 128 + lane]; w1n = wgt[(size_t)(t + 2 * step) * 128 + 64 + lane]; }
	v_pk_fma_f32 v[202:203], v[222:223], v[224:225], v[202:203] op_sel_hi:[0,1,1]
	v_cvt_pk_f32_fp8_e32 v[224:225], v128
	v_pk_fma_f32 v[210:211], v[222:223], v[226:227], v[210:211] op_sel_hi:[0,1,1]
	v_pk_fma_f32 v[212:213], v[222:223], v[228:229], v[212:213] op_sel_hi:[0,1,1]
	v_pk_fma_f32 v[214:215], v[222:223], v[230:231], v[214:215] op_sel_hi:[0,1,1]
	v_cvt_pk_f32_fp8_sdwa v[226:227], v128 src0_sel:WORD_1
	v_cvt_pk_f32_fp8_e32 v[228:229], v129
	v_cvt_pk_f32_fp8_sdwa v[230:231], v129 src0_sel:WORD_1
	v_pk_fma_f32 v[216:217], v[222:223], v[224:225], v[216:217] op_sel_hi:[0,1,1]
	v_cndmask_b32_e64 v167, v202, v216, s[12:13]
	v_pk_fma_f32 v[218:219], v[222:223], v[226:227], v[218:219] op_sel_hi:[0,1,1]
	v_pk_fma_f32 v[220:221], v[222:223], v[228:229], v[220:221] op_sel_hi:[0,1,1]
	v_pk_fma_f32 v[200:201], v[222:223], v[230:231], v[200:201] op_sel_hi:[0,1,1]
	ds_bpermute_b32 v222, v173, v167
	v_cndmask_b32_e64 v167, v203, v217, s[12:13]
	ds_bpermute_b32 v223, v173, v167
	v_cndmask_b32_e64 v167, v210, v218, s[12:13]
	ds_bpermute_b32 v224, v173, v167
	v_cndmask_b32_e64 v167, v211, v219, s[12:13]
	ds_bpermute_b32 v225, v173, v167
	v_cndmask_b32_e64 v167, v212, v220, s[12:13]
	ds_bpermute_b32 v226, v173, v167
	v_cndmask_b32_e64 v167, v213, v221, s[12:13]
	ds_bpermute_b32 v227, v173, v167
	v_cndmask_b32_e64 v167, v214, v200, s[12:13]
	ds_bpermute_b32 v228, v173, v167
	v_cndmask_b32_e64 v167, v215, v201, s[12:13]
	ds_bpermute_b32 v229, v173, v167
	s_setprio 0
	v_ashrrev_i32_e32 v167, 31, v166
	v_lshlrev_b64 v[230:231], 11, v[166:167]
	v_lshl_add_u64 v[232:233], v[160:161], 0, v[230:231]
	global_load_dword v167, v[232:233], off
	v_cndmask_b32_e64 v203, v217, v203, s[12:13]
	v_cndmask_b32_e64 v202, v216, v202, s[12:13]
	v_cndmask_b32_e64 v211, v219, v211, s[12:13]
	v_cndmask_b32_e64 v210, v218, v210, s[12:13]
	v_cndmask_b32_e64 v213, v221, v213, s[12:13]
	v_cndmask_b32_e64 v212, v220, v212, s[12:13]
	v_cndmask_b32_e64 v201, v201, v215, s[12:13]
	v_cndmask_b32_e64 v200, v200, v214, s[12:13]
	s_waitcnt lgkmcnt(6)
	v_pk_add_f32 v[202:203], v[202:203], v[222:223]
	s_waitcnt lgkmcnt(4)
	v_pk_add_f32 v[210:211], v[210:211], v[224:225]
	s_waitcnt lgkmcnt(2)
	v_pk_add_f32 v[212:213], v[212:213], v[226:227]
	s_waitcnt lgkmcnt(0)
	v_pk_add_f32 v[200:201], v[200:201], v[228:229]
	v_cndmask_b32_e64 v214, v202, v212, s[14:15]
	v_cndmask_b32_e64 v215, v213, v203, s[14:15]
	v_cndmask_b32_e64 v203, v203, v213, s[14:15]
	v_cndmask_b32_e64 v213, v210, v200, s[14:15]
	v_cndmask_b32_e64 v219, v211, v201, s[14:15]
	ds_bpermute_b32 v216, v175, v214
	ds_bpermute_b32 v217, v175, v203
	ds_bpermute_b32 v218, v175, v213
	ds_bpermute_b32 v219, v175, v219
	v_cndmask_b32_e64 v214, v212, v202, s[14:15]
	v_cndmask_b32_e64 v201, v201, v211, s[14:15]
	v_cndmask_b32_e64 v200, v200, v210, s[14:15]
	s_waitcnt lgkmcnt(2)
	v_pk_add_f32 v[202:203], v[214:215], v[216:217]
	s_waitcnt lgkmcnt(0)
	v_pk_add_f32 v[200:201], v[200:201], v[218:219]
	s_nop 0
	v_cndmask_b32_e64 v210, v202, v200, s[16:17]
	v_cndmask_b32_e64 v211, v203, v201, s[16:17]
	ds_bpermute_b32 v210, v192, v210
	ds_bpermute_b32 v211, v192, v211
	v_cndmask_b32_e64 v201, v201, v203, s[16:17]
	v_cndmask_b32_e64 v200, v200, v202, s[16:17]
	s_waitcnt lgkmcnt(0)
	v_pk_add_f32 v[200:201], v[200:201], v[210:211]
	s_waitcnt vmcnt(0)
	v_lshlrev_b32_e32 v202, 16, v167
	v_and_b32_e32 v203, 0xffff0000, v167
	v_pk_fma_f32 v[200:201], v[202:203], s[58:59], v[200:201] op_sel_hi:[1,0,1]
	s_nop 0
	v_cvt_pk_bf16_f32 v167, v200, v201
	v_lshl_add_u64 v[200:201], v[162:163], 0, v[230:231]
	global_store_dword v[200:201], v167, off
	s_and_saveexec_b64 s[76:77], s[18:19]
	s_cbranch_execz .LBB0_659
	v_mov_b32_e32 v191, v132
	v_mov_b32_e32 v189, v198
	s_and_saveexec_b64 s[0:1], s[20:21]
	s_cbranch_execz .LBB0_667
	ds_bpermute_b32 v66, v131, v199
	ds_bpermute_b32 v68, v149, v199
	ds_bpermute_b32 v74, v182, v199
	ds_bpermute_b32 v76, v183, v199
	ds_bpermute_b32 v82, v184, v199
	ds_bpermute_b32 v84, v185, v199
	ds_bpermute_b32 v90, v186, v199
	ds_bpermute_b32 v92, v187, v199
	ds_bpermute_b32 v98, v131, v169
	ds_bpermute_b32 v100, v149, v169
	ds_bpermute_b32 v106, v182, v169
	ds_bpermute_b32 v108, v183, v169
	ds_bpermute_b32 v114, v184, v169
	ds_bpermute_b32 v116, v185, v169
	ds_bpermute_b32 v122, v186, v169
	ds_bpermute_b32 v124, v187, v169
	s_waitcnt lgkmcnt(0)
	v_ashrrev_i32_e32 v169, 31, v168
	v_lshl_add_u32 v66, v66, 7, v252
	v_lshl_add_u32 v68, v68, 7, v252
	v_lshl_add_u32 v74, v74, 7, v252
	v_lshl_add_u32 v76, v76, 7, v252
	v_lshl_add_u32 v82, v82, 7, v252
	v_lshl_add_u32 v84, v84, 7, v252
	v_lshl_add_u32 v90, v90, 7, v252
	v_lshl_add_u32 v92, v92, 7, v252
	v_lshl_add_u32 v98, v98, 7, v252
	v_lshl_add_u32 v100, v100, 7, v252
	v_lshl_add_u32 v106, v106, 7, v252
	v_lshl_add_u32 v108, v108, 7, v252
	v_lshl_add_u32 v114, v114, 7, v252
	v_lshl_add_u32 v116, v116, 7, v252
	v_lshl_add_u32 v122, v122, 7, v252
	v_lshl_add_u32 v124, v124, 7, v252
	v_lshlrev_b64 v[168:169], 9, v[168:169]
	v_mov_b32_e32 v70, v68
	v_mov_b32_e32 v78, v76
	v_mov_b32_e32 v86, v84
	v_mov_b32_e32 v94, v92
	v_mov_b32_e32 v102, v100
	v_mov_b32_e32 v110, v108
	v_mov_b32_e32 v118, v116
	v_mov_b32_e32 v126, v124
	v_lshl_add_u64 v[168:169], v[154:155], 0, v[168:169]
	global_load_dwordx4 v[66:69], v66, s[98:99]
	s_nop 0
	global_load_dwordx4 v[70:73], v70, s[98:99]
	s_nop 0
	global_load_dwordx4 v[74:77], v74, s[98:99]
	s_nop 0
	global_load_dwordx4 v[78:81], v78, s[98:99]
	s_nop 0
	global_load_dwordx4 v[82:85], v82, s[98:99]
	s_nop 0
	global_load_dwordx4 v[86:89], v86, s[98:99]
	s_nop 0
	global_load_dwordx4 v[90:93], v90, s[98:99]
	s_nop 0
	global_load_dwordx4 v[94:97], v94, s[98:99]
	s_nop 0
	global_load_dwordx4 v[98:101], v98, s[98:99]
	s_nop 0
	global_load_dwordx4 v[102:105], v102, s[98:99]
	s_nop 0
	global_load_dwordx4 v[106:109], v106, s[98:99]
	s_nop 0
	global_load_dwordx4 v[110:113], v110, s[98:99]
	s_nop 0
	global_load_dwordx4 v[114:117], v114, s[98:99]
	s_nop 0
	global_load_dwordx4 v[118:121], v118, s[98:99]
	s_nop 0
	global_load_dwordx4 v[122:125], v122, s[98:99]
	s_nop 0
	global_load_dwordx4 v[126:129], v126, s[98:99]
	s_nop 0
	global_load_dword v189, v[168:169], off
	global_load_dword v191, v[168:169], off offset:256

; #define U_ISSUE(SEG, E0, E1) { _Pragma("unroll") for (int b = 0; b < 16; ++b) { const int e = __shfl((b < 8) ? (E0) : (E1), (b & 7) * 8 + grp); SEG[b] = *(const u32x4*)(ub + (size_t)e * DM); } }
; DI void peer_u_phase(const bf16_t* __restrict__ x1, const int* __restrict__ eidx, const unsigned char* __restrict__ U8, float* __restrict__ ph) {
;     ...
;     for (int j_ = sm.j0; j_ < 8 * REP_PU; j_ += sm.jstep) {
;         const int j = j_ & 7;
;         const unsigned char* ub = U8 + 128 * j + 16 * l8;
;         const bf16_t* xb_ = x1 + 128 * j + 16 * l8;
;         float* pj = ph + (size_t)j * T_TOK * 128;
;         const int step = sm.nslot;
;         int t = sm.wslot;
;         if (t >= T_TOK) continue;
;         u32x4 sa[16], sb[16];
;         int e0n = 0, e1n = 0;
;         u32x4 xa, xb, xan, xbn;
;     ...
;         {
;             const int e0 = eidx[(size_t)t * 128 + lane], e1 = eidx[(size_t)t * 128 + 64 + lane];
;             xa = *(const u32x4*)(xb_ + (size_t)t * DM); xb = *(const u32x4*)(xb_ + (size_t)t * DM + 8);
;             U_ISSUE(sa, e0, e1)
;             if (t + step < T_TOK) { e0n = eidx[(size_t)(t + step) * 128 + lane]; e1n = eidx[(size_t)(t + step) * 128 + 64 + lane]; }
;         }
.LBB0_1223:
	s_and_saveexec_b64 s[18:19], vcc
	s_cbranch_execz .LBB0_1222
	global_load_dword v79, v[156:157], off
	global_load_dword v81, v[156:157], off offset:256
	s_lshl_b32 s2, s24, 21
	v_lshl_add_u64 v[166:167], v[152:153], 0, s[2:3]
	v_and_b32_e32 v252, 7, v172
	v_lshlrev_b32_e32 v252, 4, v252
	v_readfirstlane_b32 s98, v166
	v_readfirstlane_b32 s99, v167
	s_lshl_b32 s2, s24, 8
	v_lshl_add_u64 v[168:169], v[154:155], 0, s[2:3]
	v_lshl_add_u64 v[76:77], v[168:169], 0, v[158:159]
	global_load_dwordx4 v[72:75], v[76:77], off
	v_mov_b32_e32 v200, 0
	v_mov_b32_e32 v199, 0
	s_waitcnt vmcnt(2)
	ds_bpermute_b32 v78, v149, v79
	ds_bpermute_b32 v80, v151, v79
	ds_bpermute_b32 v82, v187, v79
	ds_bpermute_b32 v84, v188, v79
	ds_bpermute_b32 v86, v189, v79
	ds_bpermute_b32 v88, v190, v79
	ds_bpermute_b32 v90, v191, v79
	ds_bpermute_b32 v92, v198, v79
	s_waitcnt vmcnt(1)
	ds_bpermute_b32 v94, v149, v81
	ds_bpermute_b32 v96, v151, v81
	ds_bpermute_b32 v98, v187, v81
	ds_bpermute_b32 v100, v188, v81
	ds_bpermute_b32 v102, v189, v81
	ds_bpermute_b32 v104, v190, v81
	ds_bpermute_b32 v106, v191, v81
	ds_bpermute_b32 v108, v198, v81
	s_waitcnt lgkmcnt(0)
	v_lshl_add_u32 v78, v78, 7, v252
	v_lshl_add_u32 v80, v80, 7, v252
	v_lshl_add_u32 v82, v82, 7, v252
	v_lshl_add_u32 v84, v84, 7, v252
	v_lshl_add_u32 v86, v86, 7, v252
	v_lshl_add_u32 v88, v88, 7, v252
	v_lshl_add_u32 v90, v90, 7, v252
	v_lshl_add_u32 v92, v92, 7, v252
	v_lshl_add_u32 v94, v94, 7, v252
	v_lshl_add_u32 v96, v96, 7, v252
	v_lshl_add_u32 v98, v98, 7, v252
	v_lshl_add_u32 v100, v100, 7, v252
	v_lshl_add_u32 v102, v102, 7, v252
	v_lshl_add_u32 v104, v104, 7, v252
	v_lshl_add_u32 v106, v106, 7, v252
	v_lshl_add_u32 v108, v108, 7, v252
	v_mov_b32_e32 v110, v82
	v_mov_b32_e32 v112, v84
	v_mov_b32_e32 v114, v86
	v_mov_b32_e32 v116, v88
	v_mov_b32_e32 v118, v90
	v_mov_b32_e32 v120, v92
	v_mov_b32_e32 v122, v94
	v_mov_b32_e32 v124, v96
	v_mov_b32_e32 v126, v98
	v_mov_b32_e32 v128, v100
	v_mov_b32_e32 v130, v102
	v_mov_b32_e32 v132, v104
	v_mov_b32_e32 v134, v106
	v_mov_b32_e32 v136, v108
	global_load_dwordx4 v[140:143], v[76:77], off offset:16
	s_nop 0
	global_load_dwordx4 v[76:79], v78, s[98:99]
	s_nop 0
	global_load_dwordx4 v[80:83], v80, s[98:99]
	s_nop 0
	global_load_dwordx4 v[84:87], v110, s[98:99]
	global_load_dwordx4 v[88:91], v112, s[98:99]
	global_load_dwordx4 v[92:95], v114, s[98:99]
	global_load_dwordx4 v[96:99], v116, s[98:99]
	global_load_dwordx4 v[100:103], v118, s[98:99]
	global_load_dwordx4 v[104:107], v120, s[98:99]
	global_load_dwordx4 v[108:111], v122, s[98:99]
	s_nop 0
	global_load_dwordx4 v[112:115], v124, s[98:99]
	global_load_dwordx4 v[116:119], v126, s[98:99]
	global_load_dwordx4 v[120:123], v128, s[98:99]
	s_nop 0
	global_load_dwordx4 v[124:127], v130, s[98:99]
	s_nop 0
	global_load_dwordx4 v[128:131], v132, s[98:99]
	s_nop 0
	global_load_dwordx4 v[132:135], v134, s[98:99]
	s_nop 0
	global_load_dwordx4 v[136:139], v136, s[98:99]
	s_and_saveexec_b64 s[0:1], s[6:7]
	s_cbranch_execz .LBB0_1226
	global_load_dword v199, v[160:161], off
	global_load_dword v200, v[160:161], off offset:256

; #define U_ISSUE(SEG, E0, E1) { _Pragma("unroll") for (int b = 0; b < 16; ++b) { const int e = __shfl((b < 8) ? (E0) : (E1), (b & 7) * 8 + grp); SEG[b] = *(const u32x4*)(ub + (size_t)e * DM); } }
; DI void peer_u_phase(const bf16_t* __restrict__ x1, const int* __restrict__ eidx, const unsigned char* __restrict__ U8, float* __restrict__ ph) {
;     ...
;         {
;             const int e0 = eidx[(size_t)t * 128 + lane], e1 = eidx[(size_t)t * 128 + 64 + lane];
;             xa = *(const u32x4*)(xb_ + (size_t)t * DM); xb = *(const u32x4*)(xb_ + (size_t)t * DM + 8);
;             U_ISSUE(sa, e0, e1)
;             if (t + step < T_TOK) { e0n = eidx[(size_t)(t + step) * 128 + lane]; e1n = eidx[(size_t)(t + step) * 128 + 64 + lane]; }
;         }
;         for (; t < T_TOK; t += 2 * step) {
;             int e0nn = 0, e1nn = 0;
;             const bool n1 = t + step < T_TOK, n2 = t + 2 * step < T_TOK, n3 = t + 3 * step < T_TOK;
;             if (n1) { U_ISSUE(sb, e0n, e1n) xan = *(const u32x4*)(xb_ + (size_t)(t + step) * DM); xbn = *(const u32x4*)(xb_ + (size_t)(t + step) * DM + 8); }
;             if (n2) { e0nn = eidx[(size_t)(t + 2 * step) * 128 + lane]; e1nn = eidx[(size_t)(t + 2 * step) * 128 + 64 + lane]; }
.LBB0_1229:
	v_add_u32_e32 v180, s54, v182
	v_cmp_gt_i32_e64 s[14:15], s22, v180
	v_ashrrev_i32_e32 v181, 31, v180
	s_and_saveexec_b64 s[0:1], s[14:15]
	s_cbranch_execz .LBB0_1231
	s_waitcnt vmcnt(1)
	ds_bpermute_b32 v0, v149, v199
	ds_bpermute_b32 v2, v151, v199
	ds_bpermute_b32 v8, v187, v199
	ds_bpermute_b32 v10, v188, v199
	ds_bpermute_b32 v16, v189, v199
	ds_bpermute_b32 v18, v190, v199
	ds_bpermute_b32 v24, v191, v199
	ds_bpermute_b32 v26, v198, v199
	s_waitcnt vmcnt(0)
	ds_bpermute_b32 v32, v149, v200
	ds_bpermute_b32 v34, v151, v200
	ds_bpermute_b32 v40, v187, v200
	ds_bpermute_b32 v42, v188, v200
	ds_bpermute_b32 v48, v189, v200
	ds_bpermute_b32 v50, v190, v200
	ds_bpermute_b32 v56, v191, v200
	ds_bpermute_b32 v58, v198, v200
	s_waitcnt lgkmcnt(0)
	v_lshl_add_u32 v0, v0, 7, v252
	v_lshl_add_u32 v2, v2, 7, v252
	v_lshl_add_u32 v8, v8, 7, v252
	v_lshl_add_u32 v10, v10, 7, v252
	v_lshl_add_u32 v16, v16, 7, v252
	v_lshl_add_u32 v18, v18, 7, v252
	v_lshl_add_u32 v24, v24, 7, v252
	v_lshl_add_u32 v26, v26, 7, v252
	v_lshl_add_u32 v32, v32, 7, v252
	v_lshl_add_u32 v34, v34, 7, v252
	v_lshl_add_u32 v40, v40, 7, v252
	v_lshl_add_u32 v42, v42, 7, v252
	v_lshl_add_u32 v48, v48, 7, v252
	v_lshl_add_u32 v50, v50, 7, v252
	v_lshl_add_u32 v56, v56, 7, v252
	v_lshl_add_u32 v58, v58, 7, v252
	v_lshlrev_b64 v[64:65], 11, v[180:181]
	v_lshl_add_u64 v[64:65], v[168:169], 0, v[64:65]
	global_load_dwordx4 v[4:7], v0, s[98:99]
	s_nop 0
	global_load_dwordx4 v[0:3], v2, s[98:99]
	s_nop 0
	global_load_dwordx4 v[12:15], v8, s[98:99]
	s_nop 0
	global_load_dwordx4 v[8:11], v10, s[98:99]
	s_nop 0
	global_load_dwordx4 v[20:23], v16, s[98:99]
	s_nop 0
	global_load_dwordx4 v[16:19], v18, s[98:99]
	s_nop 0
	global_load_dwordx4 v[28:31], v24, s[98:99]
	s_nop 0
	global_load_dwordx4 v[24:27], v26, s[98:99]
	s_nop 0
	global_load_dwordx4 v[36:39], v32, s[98:99]
	s_nop 0
	global_load_dwordx4 v[32:35], v34, s[98:99]
	s_nop 0
	global_load_dwordx4 v[44:47], v40, s[98:99]
	s_nop 0
	global_load_dwordx4 v[40:43], v42, s[98:99]
	s_nop 0
	global_load_dwordx4 v[52:55], v48, s[98:99]
	s_nop 0
	global_load_dwordx4 v[48:51], v50, s[98:99]
	s_nop 0
	global_load_dwordx4 v[60:63], v56, s[98:99]
	s_nop 0
	global_load_dwordx4 v[56:59], v58, s[98:99]
	s_nop 0
	global_load_dwordx4 v[68:71], v[64:65], off offset:16
	s_nop 0
	global_load_dwordx4 v[64:67], v[64:65], off

; DI float dot16(const unsigned (&a)[8], u32x4 b0, u32x4 b1) {
;     float acc;
;     asm volatile("v_dot2_f32_bf16 %0, %1, %9, 0\n\tv_dot2_f32_bf16 %0, %2, %10, %0\n\tv_dot2_f32_bf16 %0, %3, %11, %0\n\tv_dot2_f32_bf16 %0, %4, %12, %0\n\t"
;                  "v_dot2_f32_bf16 %0, %5, %13, %0\n\tv_dot2_f32_bf16 %0, %6, %14, %0\n\tv_dot2_f32_bf16 %0, %7, %15, %0\n\tv_dot2_f32_bf16 %0, %8, %16, %0\n\ts_nop 2"
;                  : "=&v"(acc)
;                  : "v"(a[0]), "v"(a[1]), "v"(a[2]), "v"(a[3]), "v"(a[4]), "v"(a[5]), "v"(a[6]), "v"(a[7]),
;                    "v"(b0.x), "v"(b0.y), "v"(b0.z), "v"(b0.w), "v"(b1.x), "v"(b1.y), "v"(b1.z), "v"(b1.w));
;     return acc;
; }
; DI float dot_fp8_row(u32x4 u, u32x4 xa, u32x4 xb) {
;     unsigned a[8];
; #pragma unroll
;     for (int j = 0; j < 4; ++j) {
;         a[2 * j] = __builtin_bit_cast(unsigned, __builtin_amdgcn_cvt_scalef32_pk_bf16_fp8(u[j], 1.0f, false));
;         a[2 * j + 1] = __builtin_bit_cast(unsigned, __builtin_amdgcn_cvt_scalef32_pk_bf16_fp8(u[j], 1.0f, true));
;     }
;     return dot16(a, xa, xb);
; }
.LBB0_1233:
	s_or_b64 exec, exec, s[0:1]
	s_setprio 1
	s_waitcnt vmcnt(15)
	v_cvt_scalef32_pk_bf16_fp8 v203, v77, 1.0
	v_cvt_scalef32_pk_bf16_fp8 v183, v76, 1.0
	v_cvt_scalef32_pk_bf16_fp8 v202, v76, 1.0 op_sel:[1,0,0]
	v_cvt_scalef32_pk_bf16_fp8 v204, v77, 1.0 op_sel:[1,0,0]
	v_cvt_scalef32_pk_bf16_fp8 v205, v78, 1.0
	v_cvt_scalef32_pk_bf16_fp8 v206, v78, 1.0 op_sel:[1,0,0]
	v_cvt_scalef32_pk_bf16_fp8 v207, v79, 1.0
	v_cvt_scalef32_pk_bf16_fp8 v208, v79, 1.0 op_sel:[1,0,0]
	v_dot2_f32_bf16 v209, v183, v72, 0
	v_dot2_f32_bf16 v209, v202, v73, v209
	v_dot2_f32_bf16 v209, v203, v74, v209
	v_dot2_f32_bf16 v209, v204, v75, v209
	v_dot2_f32_bf16 v209, v205, v140, v209
	v_dot2_f32_bf16 v209, v206, v141, v209
	v_dot2_f32_bf16 v209, v207, v142, v209
	v_dot2_f32_bf16 v209, v208, v143, v209
	s_nop 2
	s_waitcnt vmcnt(14)
	v_cvt_scalef32_pk_bf16_fp8 v203, v81, 1.0
	v_cvt_scalef32_pk_bf16_fp8 v183, v80, 1.0
	v_cvt_scalef32_pk_bf16_fp8 v202, v80, 1.0 op_sel:[1,0,0]
	v_cvt_scalef32_pk_bf16_fp8 v204, v81, 1.0 op_sel:[1,0,0]
	v_cvt_scalef32_pk_bf16_fp8 v205, v82, 1.0
	v_cvt_scalef32_pk_bf16_fp8 v206, v82, 1.0 op_sel:[1,0,0]
	v_cvt_scalef32_pk_bf16_fp8 v207, v83, 1.0
	v_cvt_scalef32_pk_bf16_fp8 v208, v83, 1.0 op_sel:[1,0,0]
	v_dot2_f32_bf16 v210, v183, v72, 0
	v_dot2_f32_bf16 v210, v202, v73, v210
	v_dot2_f32_bf16 v210, v203, v74, v210
	v_dot2_f32_bf16 v210, v204, v75, v210
	v_dot2_f32_bf16 v210, v205, v140, v210
	v_dot2_f32_bf16 v210, v206, v141, v210
	v_dot2_f32_bf16 v210, v207, v142, v210
	v_dot2_f32_bf16 v210, v208, v143, v210
	s_nop 2
	s_waitcnt vmcnt(13)
	v_cvt_scalef32_pk_bf16_fp8 v203, v85, 1.0
	v_cvt_scalef32_pk_bf16_fp8 v183, v84, 1.0
	v_cvt_scalef32_pk_bf16_fp8 v202, v84, 1.0 op_sel:[1,0,0]
	v_cvt_scalef32_pk_bf16_fp8 v204, v85, 1.0 op_sel:[1,0,0]
	v_cvt_scalef32_pk_bf16_fp8 v205, v86, 1.0
	v_cvt_scalef32_pk_bf16_fp8 v206, v86, 1.0 op_sel:[1,0,0]
	v_cvt_scalef32_pk_bf16_fp8 v207, v87, 1.0
	v_cvt_scalef32_pk_bf16_fp8 v208, v87, 1.0 op_sel:[1,0,0]
	v_dot2_f32_bf16 v211, v183, v72, 0
	v_dot2_f32_bf16 v211, v202, v73, v211
	v_dot2_f32_bf16 v211, v203, v74, v211
	v_dot2_f32_bf16 v211, v204, v75, v211
	v_dot2_f32_bf16 v211, v205, v140, v211
	v_dot2_f32_bf16 v211, v206, v141, v211
	v_dot2_f32_bf16 v211, v207, v142, v211
	v_dot2_f32_bf16 v211, v208, v143, v211
	s_nop 2
	s_waitcnt vmcnt(12)
	v_cvt_scalef32_pk_bf16_fp8 v203, v89, 1.0
	v_cvt_scalef32_pk_bf16_fp8 v183, v88, 1.0
	v_cvt_scalef32_pk_bf16_fp8 v202, v88, 1.0 op_sel:[1,0,0]
	v_cvt_scalef32_pk_bf16_fp8 v204, v89, 1.0 op_sel:[1,0,0]
	v_cvt_scalef32_pk_bf16_fp8 v205, v90, 1.0
	v_cvt_scalef32_pk_bf16_fp8 v206, v90, 1.0 op_sel:[1,0,0]
	v_cvt_scalef32_pk_bf16_fp8 v207, v91, 1.0
	v_cvt_scalef32_pk_bf16_fp8 v208, v91, 1.0 op_sel:[1,0,0]
	v_dot2_f32_bf16 v212, v183, v72, 0
	v_dot2_f32_bf16 v212, v202, v73, v212
	v_dot2_f32_bf16 v212, v203, v74, v212
	v_dot2_f32_bf16 v212, v204, v75, v212
	v_dot2_f32_bf16 v212, v205, v140, v212
	v_dot2_f32_bf16 v212, v206, v141, v212
	v_dot2_f32_bf16 v212, v207, v142, v212
	v_dot2_f32_bf16 v212, v208, v143, v212
	s_nop 2
	s_waitcnt vmcnt(11)
	v_cvt_scalef32_pk_bf16_fp8 v203, v93, 1.0
	v_cvt_scalef32_pk_bf16_fp8 v183, v92, 1.0
	v_cvt_scalef32_pk_bf16_fp8 v202, v92, 1.0 op_sel:[1,0,0]
	v_cvt_scalef32_pk_bf16_fp8 v204, v93, 1.0 op_sel:[1,0,0]
	v_cvt_scalef32_pk_bf16_fp8 v205, v94, 1.0
	v_cvt_scalef32_pk_bf16_fp8 v206, v94, 1.0 op_sel:[1,0,0]
	v_cvt_scalef32_pk_bf16_fp8 v207, v95, 1.0
	v_cvt_scalef32_pk_bf16_fp8 v208, v95, 1.0 op_sel:[1,0,0]
	v_dot2_f32_bf16 v213, v183, v72, 0
	v_dot2_f32_bf16 v213, v202, v73, v213
	v_dot2_f32_bf16 v213, v203, v74, v213
	v_dot2_f32_bf16 v213, v204, v75, v213
	v_dot2_f32_bf16 v213, v205, v140, v213
	v_dot2_f32_bf16 v213, v206, v141, v213
	v_dot2_f32_bf16 v213, v207, v142, v213
	v_dot2_f32_bf16 v213, v208, v143, v213
	s_nop 2
	s_waitcnt vmcnt(10)
	v_cvt_scalef32_pk_bf16_fp8 v203, v97, 1.0
	v_cvt_scalef32_pk_bf16_fp8 v183, v96, 1.0
	v_cvt_scalef32_pk_bf16_fp8 v202, v96, 1.0 op_sel:[1,0,0]
	v_cvt_scalef32_pk_bf16_fp8 v204, v97, 1.0 op_sel:[1,0,0]
	v_cvt_scalef32_pk_bf16_fp8 v205, v98, 1.0
	v_cvt_scalef32_pk_bf16_fp8 v206, v98, 1.0 op_sel:[1,0,0]
	v_cvt_scalef32_pk_bf16_fp8 v207, v99, 1.0
	v_cvt_scalef32_pk_bf16_fp8 v208, v99, 1.0 op_sel:[1,0,0]
	v_dot2_f32_bf16 v214, v183, v72, 0
	v_dot2_f32_bf16 v214, v202, v73, v214
	v_dot2_f32_bf16 v214, v203, v74, v214
	v_dot2_f32_bf16 v214, v204, v75, v214
	v_dot2_f32_bf16 v214, v205, v140, v214
	v_dot2_f32_bf16 v214, v206, v141, v214
	v_dot2_f32_bf16 v214, v207, v142, v214
	v_dot2_f32_bf16 v214, v208, v143, v214
	s_nop 2
	s_waitcnt vmcnt(9)
	v_cvt_scalef32_pk_bf16_fp8 v203, v101, 1.0
	v_cvt_scalef32_pk_bf16_fp8 v183, v100, 1.0
	v_cvt_scalef32_pk_bf16_fp8 v202, v100, 1.0 op_sel:[1,0,0]
	v_cvt_scalef32_pk_bf16_fp8 v204, v101, 1.0 op_sel:[1,0,0]
	v_cvt_scalef32_pk_bf16_fp8 v205, v102, 1.0
	v_cvt_scalef32_pk_bf16_fp8 v206, v102, 1.0 op_sel:[1,0,0]
	v_cvt_scalef32_pk_bf16_fp8 v207, v103, 1.0
	v_cvt_scalef32_pk_bf16_fp8 v208, v103, 1.0 op_sel:[1,0,0]
	v_dot2_f32_bf16 v215, v183, v72, 0
	v_dot2_f32_bf16 v215, v202, v73, v215
	v_dot2_f32_bf16 v215, v203, v74, v215
	v_dot2_f32_bf16 v215, v204, v75, v215
	v_dot2_f32_bf16 v215, v205, v140, v215
	v_dot2_f32_bf16 v215, v206, v141, v215
	v_dot2_f32_bf16 v215, v207, v142, v215
	v_dot2_f32_bf16 v215, v208, v143, v215
	s_nop 2
	s_waitcnt vmcnt(8)
; DI float dot16(const unsigned (&a)[8], u32x4 b0, u32x4 b1) {
;     float acc;
;     asm volatile("v_dot2_f32_bf16 %0, %1, %9, 0\n\tv_dot2_f32_bf16 %0, %2, %10, %0\n\tv_dot2_f32_bf16 %0, %3, %11, %0\n\tv_dot2_f32_bf16 %0, %4, %12, %0\n\t"
;                  "v_dot2_f32_bf16 %0, %5, %13, %0\n\tv_dot2_f32_bf16 %0, %6, %14, %0\n\tv_dot2_f32_bf16 %0, %7, %15, %0\n\tv_dot2_f32_bf16 %0, %8, %16, %0\n\ts_nop 2"
;                  : "=&v"(acc)
;                  : "v"(a[0]), "v"(a[1]), "v"(a[2]), "v"(a[3]), "v"(a[4]), "v"(a[5]), "v"(a[6]), "v"(a[7]),
;                    "v"(b0.x), "v"(b0.y), "v"(b0.z), "v"(b0.w), "v"(b1.x), "v"(b1.y), "v"(b1.z), "v"(b1.w));
;     return acc;
; }
; DI float dot_fp8_row(u32x4 u, u32x4 xa, u32x4 xb) {
;     unsigned a[8];
; #pragma unroll
;     for (int j = 0; j < 4; ++j) {
;         a[2 * j] = __builtin_bit_cast(unsigned, __builtin_amdgcn_cvt_scalef32_pk_bf16_fp8(u[j], 1.0f, false));
;         a[2 * j + 1] = __builtin_bit_cast(unsigned, __builtin_amdgcn_cvt_scalef32_pk_bf16_fp8(u[j], 1.0f, true));
;     }
;     return dot16(a, xa, xb);
; }
	v_cvt_scalef32_pk_bf16_fp8 v203, v105, 1.0
	v_cvt_scalef32_pk_bf16_fp8 v183, v104, 1.0
	v_cvt_scalef32_pk_bf16_fp8 v202, v104, 1.0 op_sel:[1,0,0]
	v_cvt_scalef32_pk_bf16_fp8 v204, v105, 1.0 op_sel:[1,0,0]
	v_cvt_scalef32_pk_bf16_fp8 v205, v106, 1.0
	v_cvt_scalef32_pk_bf16_fp8 v206, v106, 1.0 op_sel:[1,0,0]
	v_cvt_scalef32_pk_bf16_fp8 v208, v107, 1.0
	v_cvt_scalef32_pk_bf16_fp8 v216, v107, 1.0 op_sel:[1,0,0]
	v_dot2_f32_bf16 v217, v183, v72, 0
	v_dot2_f32_bf16 v217, v202, v73, v217
	v_dot2_f32_bf16 v217, v203, v74, v217
	v_dot2_f32_bf16 v217, v204, v75, v217
	v_dot2_f32_bf16 v217, v205, v140, v217
	v_dot2_f32_bf16 v217, v206, v141, v217
	v_dot2_f32_bf16 v217, v208, v142, v217
	v_dot2_f32_bf16 v217, v216, v143, v217
	s_nop 2
	v_cndmask_b32_e64 v203, v210, v214, s[8:9]
	ds_bpermute_b32 v203, v193, v203
	v_cndmask_b32_e64 v204, v211, v215, s[8:9]
	ds_bpermute_b32 v204, v193, v204
	v_cndmask_b32_e64 v205, v212, v217, s[8:9]
	v_cndmask_b32_e64 v207, v209, v213, s[8:9]
	ds_bpermute_b32 v205, v193, v205
	ds_bpermute_b32 v207, v193, v207
	v_cndmask_b32_e64 v202, v214, v210, s[8:9]
	s_waitcnt lgkmcnt(3)
	v_add_f32_e32 v202, v202, v203
	v_cndmask_b32_e64 v203, v215, v211, s[8:9]
	s_waitcnt lgkmcnt(2)
	v_add_f32_e32 v203, v203, v204
	v_cndmask_b32_e64 v204, v217, v212, s[8:9]
	v_cndmask_b32_e64 v183, v213, v209, s[8:9]
	s_waitcnt lgkmcnt(1)
	v_add_f32_e32 v204, v204, v205
	s_waitcnt lgkmcnt(0)
	v_add_f32_e32 v183, v183, v207
	v_cndmask_b32_e64 v206, v202, v204, s[10:11]
	v_cndmask_b32_e64 v205, v183, v203, s[10:11]
	ds_bpermute_b32 v206, v194, v206
	ds_bpermute_b32 v205, v194, v205
	v_cndmask_b32_e64 v202, v204, v202, s[10:11]
	v_cndmask_b32_e64 v183, v203, v183, s[10:11]
	s_waitcnt vmcnt(7)
	v_cvt_scalef32_pk_bf16_fp8 v204, v108, 1.0
	s_waitcnt lgkmcnt(1)
	v_add_f32_e32 v202, v202, v206
	v_cvt_scalef32_pk_bf16_fp8 v206, v109, 1.0
	s_waitcnt lgkmcnt(0)
	v_add_f32_e32 v183, v183, v205
	v_cvt_scalef32_pk_bf16_fp8 v205, v108, 1.0 op_sel:[1,0,0]
	v_cvt_scalef32_pk_bf16_fp8 v207, v109, 1.0 op_sel:[1,0,0]
	v_cvt_scalef32_pk_bf16_fp8 v208, v110, 1.0
	v_cvt_scalef32_pk_bf16_fp8 v209, v110, 1.0 op_sel:[1,0,0]
	v_cvt_scalef32_pk_bf16_fp8 v210, v111, 1.0
	v_cvt_scalef32_pk_bf16_fp8 v211, v111, 1.0 op_sel:[1,0,0]
	v_dot2_f32_bf16 v212, v204, v72, 0
	v_dot2_f32_bf16 v212, v205, v73, v212
	v_dot2_f32_bf16 v212, v206, v74, v212
	v_dot2_f32_bf16 v212, v207, v75, v212
	v_dot2_f32_bf16 v212, v208, v140, v212
	v_dot2_f32_bf16 v212, v209, v141, v212
	v_dot2_f32_bf16 v212, v210, v142, v212
	v_dot2_f32_bf16 v212, v211, v143, v212
	s_nop 2
	s_waitcnt vmcnt(6)
	v_cvt_scalef32_pk_bf16_fp8 v206, v113, 1.0
	v_cvt_scalef32_pk_bf16_fp8 v204, v112, 1.0
	v_cvt_scalef32_pk_bf16_fp8 v205, v112, 1.0 op_sel:[1,0,0]
	v_cvt_scalef32_pk_bf16_fp8 v207, v113, 1.0 op_sel:[1,0,0]
	v_cvt_scalef32_pk_bf16_fp8 v208, v114, 1.0
	v_cvt_scalef32_pk_bf16_fp8 v209, v114, 1.0 op_sel:[1,0,0]
	v_cvt_scalef32_pk_bf16_fp8 v210, v115, 1.0
	v_cvt_scalef32_pk_bf16_fp8 v211, v115, 1.0 op_sel:[1,0,0]
	v_dot2_f32_bf16 v213, v204, v72, 0
	v_dot2_f32_bf16 v213, v205, v73, v213
	v_dot2_f32_bf16 v213, v206, v74, v213
	v_dot2_f32_bf16 v213, v207, v75, v213
	v_dot2_f32_bf16 v213, v208, v140, v213
	v_dot2_f32_bf16 v213, v209, v141, v213
	v_dot2_f32_bf16 v213, v210, v142, v213
	v_dot2_f32_bf16 v213, v211, v143, v213
	s_nop 2
	s_waitcnt vmcnt(5)
	v_cvt_scalef32_pk_bf16_fp8 v206, v117, 1.0
	v_cvt_scalef32_pk_bf16_fp8 v204, v116, 1.0
	v_cvt_scalef32_pk_bf16_fp8 v205, v116, 1.0 op_sel:[1,0,0]
	v_cvt_scalef32_pk_bf16_fp8 v207, v117, 1.0 op_sel:[1,0,0]
	v_cvt_scalef32_pk_bf16_fp8 v208, v118, 1.0
	v_cvt_scalef32_pk_bf16_fp8 v209, v118, 1.0 op_sel:[1,0,0]
	v_cvt_scalef32_pk_bf16_fp8 v210, v119, 1.0
	v_cvt_scalef32_pk_bf16_fp8 v211, v119, 1.0 op_sel:[1,0,0]
	v_dot2_f32_bf16 v214, v204, v72, 0
	v_dot2_f32_bf16 v214, v205, v73, v214
	v_dot2_f32_bf16 v214, v206, v74, v214
	v_dot2_f32_bf16 v214, v207, v75, v214
	v_dot2_f32_bf16 v214, v208, v140, v214
	v_dot2_f32_bf16 v214, v209, v141, v214
	v_dot2_f32_bf16 v214, v210, v142, v214
	v_dot2_f32_bf16 v214, v211, v143, v214
	s_nop 2
	s_waitcnt vmcnt(4)
	v_cvt_scalef32_pk_bf16_fp8 v206, v121, 1.0
	v_cvt_scalef32_pk_bf16_fp8 v204, v120, 1.0
	v_cvt_scalef32_pk_bf16_fp8 v205, v120, 1.0 op_sel:[1,0,0]
	v_cvt_scalef32_pk_bf16_fp8 v207, v121, 1.0 op_sel:[1,0,0]
	v_cvt_scalef32_pk_bf16_fp8 v208, v122, 1.0
	v_cvt_scalef32_pk_bf16_fp8 v209, v122, 1.0 op_sel:[1,0,0]
	v_cvt_scalef32_pk_bf16_fp8 v210, v123, 1.0
	v_cvt_scalef32_pk_bf16_fp8 v211, v123, 1.0 op_sel:[1,0,0]
	v_dot2_f32_bf16 v215, v204, v72, 0
	v_dot2_f32_bf16 v215, v205, v73, v215
	v_dot2_f32_bf16 v215, v206, v74, v215
	v_dot2_f32_bf16 v215, v207, v75, v215
	v_dot2_f32_bf16 v215, v208, v140, v215
	v_dot2_f32_bf16 v215, v209, v141, v215
	v_dot2_f32_bf16 v215, v210, v142, v215
	v_dot2_f32_bf16 v215, v211, v143, v215
	s_nop 2
	s_waitcnt vmcnt(3)
	v_cvt_scalef32_pk_bf16_fp8 v206, v125, 1.0
	v_cvt_scalef32_pk_bf16_fp8 v204, v124, 1.0
	v_cvt_scalef32_pk_bf16_fp8 v205, v124, 1.0 op_sel:[1,0,0]
	v_cvt_scalef32_pk_bf16_fp8 v207, v125, 1.0 op_sel:[1,0,0]
	v_cvt_scalef32_pk_bf16_fp8 v208, v126, 1.0
	v_cvt_scalef32_pk_bf16_fp8 v209, v126, 1.0 op_sel:[1,0,0]
	v_cvt_scalef32_pk_bf16_fp8 v210, v127, 1.0
	v_cvt_scalef32_pk_bf16_fp8 v211, v127, 1.0 op_sel:[1,0,0]
	v_dot2_f32_bf16 v216, v204, v72, 0
	v_dot2_f32_bf16 v216, v205, v73, v216
	v_dot2_f32_bf16 v216, v206, v74, v216
	v_dot2_f32_bf16 v216, v207, v75, v216
	v_dot2_f32_bf16 v216, v208, v140, v216
	v_dot2_f32_bf16 v216, v209, v141, v216
	v_dot2_f32_bf16 v216, v210, v142, v216
	v_dot2_f32_bf16 v216, v211, v143, v216
	s_nop 2
	s_waitcnt vmcnt(2)
; #define U_ISSUE(SEG, E0, E1) { _Pragma("unroll") for (int b = 0; b < 16; ++b) { const int e = __shfl((b < 8) ? (E0) : (E1), (b & 7) * 8 + grp); SEG[b] = *(const u32x4*)(ub + (size_t)e * DM); } }
; DI void peer_u_phase(const bf16_t* __restrict__ x1, const int* __restrict__ eidx, const unsigned char* __restrict__ U8, float* __restrict__ ph) {
;     ...
;             if (n1) {
;                 xa = xan; xb = xbn;
;                 if (n2) { U_ISSUE(sa, e0nn, e1nn) xan = *(const u32x4*)(xb_ + (size_t)(t + 2 * step) * DM); xbn = *(const u32x4*)(xb_ + (size_t)(t + 2 * step) * DM + 8); }
	v_cvt_scalef32_pk_bf16_fp8 v206, v129, 1.0
	v_cvt_scalef32_pk_bf16_fp8 v204, v128, 1.0
	v_cvt_scalef32_pk_bf16_fp8 v205, v128, 1.0 op_sel:[1,0,0]
	v_cvt_scalef32_pk_bf16_fp8 v207, v129, 1.0 op_sel:[1,0,0]
	v_cvt_scalef32_pk_bf16_fp8 v208, v130, 1.0
	v_cvt_scalef32_pk_bf16_fp8 v209, v130, 1.0 op_sel:[1,0,0]
	v_cvt_scalef32_pk_bf16_fp8 v210, v131, 1.0
	v_cvt_scalef32_pk_bf16_fp8 v211, v131, 1.0 op_sel:[1,0,0]
	v_dot2_f32_bf16 v217, v204, v72, 0
	v_dot2_f32_bf16 v217, v205, v73, v217
	v_dot2_f32_bf16 v217, v206, v74, v217
	v_dot2_f32_bf16 v217, v207, v75, v217
	v_dot2_f32_bf16 v217, v208, v140, v217
	v_dot2_f32_bf16 v217, v209, v141, v217
	v_dot2_f32_bf16 v217, v210, v142, v217
	v_dot2_f32_bf16 v217, v211, v143, v217
	s_nop 2
	s_waitcnt vmcnt(1)
	v_cvt_scalef32_pk_bf16_fp8 v206, v133, 1.0
	v_cvt_scalef32_pk_bf16_fp8 v204, v132, 1.0
	v_cvt_scalef32_pk_bf16_fp8 v205, v132, 1.0 op_sel:[1,0,0]
	v_cvt_scalef32_pk_bf16_fp8 v207, v133, 1.0 op_sel:[1,0,0]
	v_cvt_scalef32_pk_bf16_fp8 v208, v134, 1.0
	v_cvt_scalef32_pk_bf16_fp8 v209, v134, 1.0 op_sel:[1,0,0]
	v_cvt_scalef32_pk_bf16_fp8 v210, v135, 1.0
	v_cvt_scalef32_pk_bf16_fp8 v211, v135, 1.0 op_sel:[1,0,0]
	v_dot2_f32_bf16 v218, v204, v72, 0
	v_dot2_f32_bf16 v218, v205, v73, v218
	v_dot2_f32_bf16 v218, v206, v74, v218
	v_dot2_f32_bf16 v218, v207, v75, v218
	v_dot2_f32_bf16 v218, v208, v140, v218
	v_dot2_f32_bf16 v218, v209, v141, v218
	v_dot2_f32_bf16 v218, v210, v142, v218
	v_dot2_f32_bf16 v218, v211, v143, v218
	s_nop 2
	s_waitcnt vmcnt(0)
	v_cvt_scalef32_pk_bf16_fp8 v206, v137, 1.0
	v_cvt_scalef32_pk_bf16_fp8 v204, v136, 1.0
	v_cvt_scalef32_pk_bf16_fp8 v205, v136, 1.0 op_sel:[1,0,0]
	v_cvt_scalef32_pk_bf16_fp8 v207, v137, 1.0 op_sel:[1,0,0]
	v_cvt_scalef32_pk_bf16_fp8 v208, v138, 1.0
	v_cvt_scalef32_pk_bf16_fp8 v209, v138, 1.0 op_sel:[1,0,0]
	v_cvt_scalef32_pk_bf16_fp8 v211, v139, 1.0
	v_cvt_scalef32_pk_bf16_fp8 v219, v139, 1.0 op_sel:[1,0,0]
	v_dot2_f32_bf16 v220, v204, v72, 0
	v_dot2_f32_bf16 v220, v205, v73, v220
	v_dot2_f32_bf16 v220, v206, v74, v220
	v_dot2_f32_bf16 v220, v207, v75, v220
	v_dot2_f32_bf16 v220, v208, v140, v220
	v_dot2_f32_bf16 v220, v209, v141, v220
	v_dot2_f32_bf16 v220, v211, v142, v220
	v_dot2_f32_bf16 v220, v219, v143, v220
	s_nop 2
	v_cndmask_b32_e64 v206, v213, v217, s[8:9]
	ds_bpermute_b32 v206, v193, v206
	v_cndmask_b32_e64 v207, v214, v218, s[8:9]
	v_cndmask_b32_e64 v210, v212, v216, s[8:9]
	ds_bpermute_b32 v207, v193, v207
	v_cndmask_b32_e64 v208, v215, v220, s[8:9]
	ds_bpermute_b32 v210, v193, v210
	ds_bpermute_b32 v208, v193, v208
	v_cndmask_b32_e64 v205, v217, v213, s[8:9]
	s_waitcnt lgkmcnt(3)
	v_add_f32_e32 v205, v205, v206
	v_cndmask_b32_e64 v206, v218, v214, s[8:9]
	v_cndmask_b32_e64 v204, v216, v212, s[8:9]
	s_waitcnt lgkmcnt(2)
	v_add_f32_e32 v206, v206, v207
	v_cndmask_b32_e64 v207, v220, v215, s[8:9]
	s_waitcnt lgkmcnt(1)
	v_add_f32_e32 v204, v204, v210
	s_waitcnt lgkmcnt(0)
	v_add_f32_e32 v207, v207, v208
	v_cndmask_b32_e64 v208, v204, v206, s[10:11]
	v_cndmask_b32_e64 v209, v205, v207, s[10:11]
	ds_bpermute_b32 v208, v194, v208
	ds_bpermute_b32 v209, v194, v209
	v_cndmask_b32_e64 v204, v206, v204, s[10:11]
	v_cndmask_b32_e64 v205, v207, v205, s[10:11]
	v_cndmask_b32_e64 v203, v183, v202, s[12:13]
	s_waitcnt lgkmcnt(1)
	v_add_f32_e32 v204, v204, v208
	s_waitcnt lgkmcnt(0)
	v_add_f32_e32 v205, v205, v209
	ds_bpermute_b32 v203, v195, v203
	v_cndmask_b32_e64 v206, v204, v205, s[12:13]
	ds_bpermute_b32 v206, v195, v206
	v_cndmask_b32_e64 v183, v202, v183, s[12:13]
	s_waitcnt lgkmcnt(1)
	v_add_f32_e32 v207, v183, v203
	v_cndmask_b32_e64 v183, v205, v204, s[12:13]
	s_waitcnt lgkmcnt(0)
	v_add_f32_e32 v204, v183, v206
	s_setprio 0
	v_ashrrev_i32_e32 v183, 31, v182
	v_lshlrev_b64 v[202:203], 9, v[182:183]
	v_lshl_add_u64 v[202:203], v[178:179], 0, v[202:203]
	global_store_dword v[202:203], v207, off
	global_store_dword v[202:203], v204, off offset:256
	s_and_saveexec_b64 s[36:37], s[14:15]
	s_cbranch_execz .LBB0_1228
	v_mov_b64_e32 v[142:143], v[70:71]
	v_mov_b64_e32 v[74:75], v[66:67]
	v_mov_b64_e32 v[140:141], v[68:69]
	v_mov_b64_e32 v[72:73], v[64:65]
	s_and_saveexec_b64 s[0:1], s[16:17]
	s_cbranch_execz .LBB0_1236
	ds_bpermute_b32 v72, v149, v201
	ds_bpermute_b32 v74, v151, v201
	ds_bpermute_b32 v84, v187, v201
	ds_bpermute_b32 v86, v188, v201
	ds_bpermute_b32 v92, v189, v201
	s_waitcnt lgkmcnt(4)
	ds_bpermute_b32 v94, v190, v201
	s_waitcnt lgkmcnt(4)
	v_lshl_add_u32 v72, v72, 7, v252
	ds_bpermute_b32 v100, v191, v201
	v_lshl_add_u32 v74, v74, 7, v252
	s_waitcnt lgkmcnt(4)
	ds_bpermute_b32 v102, v198, v201
	global_load_dwordx4 v[76:79], v72, s[98:99]
	global_load_dwordx4 v[80:83], v74, s[98:99]
	v_lshl_add_u32 v72, v84, 7, v252
	s_waitcnt lgkmcnt(4)
	ds_bpermute_b32 v108, v149, v185
	v_lshl_add_u32 v74, v86, 7, v252
	s_waitcnt lgkmcnt(4)
	ds_bpermute_b32 v110, v151, v185
	global_load_dwordx4 v[84:87], v72, s[98:99]
	global_load_dwordx4 v[88:91], v74, s[98:99]
	v_lshl_add_u32 v72, v92, 7, v252
	s_waitcnt lgkmcnt(4)
	ds_bpermute_b32 v116, v187, v185
	v_lshl_add_u32 v74, v94, 7, v252
	s_waitcnt lgkmcnt(4)
	ds_bpermute_b32 v118, v188, v185
	global_load_dwordx4 v[92:95], v72, s[98:99]
	global_load_dwordx4 v[96:99], v74, s[98:99]
	v_lshl_add_u32 v72, v100, 7, v252
	s_waitcnt lgkmcnt(4)
	ds_bpermute_b32 v124, v189, v185
	v_lshl_add_u32 v74, v102, 7, v252
	s_waitcnt lgkmcnt(4)
	ds_bpermute_b32 v126, v190, v185
	global_load_dwordx4 v[100:103], v72, s[98:99]
	global_load_dwordx4 v[104:107], v74, s[98:99]
	v_lshl_add_u32 v72, v108, 7, v252
	s_waitcnt lgkmcnt(4)
	ds_bpermute_b32 v132, v191, v185
	v_lshl_add_u32 v74, v110, 7, v252
	s_waitcnt lgkmcnt(4)
	ds_bpermute_b32 v134, v198, v185
	global_load_dwordx4 v[108:111], v72, s[98:99]
	global_load_dwordx4 v[112:115], v74, s[98:99]
	v_lshl_add_u32 v72, v116, 7, v252
	s_waitcnt lgkmcnt(4)
	v_lshl_add_u32 v74, v118, 7, v252
	s_waitcnt lgkmcnt(3)
	global_load_dwordx4 v[116:119], v72, s[98:99]
	global_load_dwordx4 v[120:123], v74, s[98:99]
	v_lshl_add_u32 v72, v124, 7, v252
	s_waitcnt lgkmcnt(2)
	v_lshl_add_u32 v74, v126, 7, v252
	s_waitcnt lgkmcnt(1)
	global_load_dwordx4 v[124:127], v72, s[98:99]
	global_load_dwordx4 v[128:131], v74, s[98:99]
	v_lshl_add_u32 v72, v132, 7, v252
	s_waitcnt lgkmcnt(0)
	v_lshl_add_u32 v74, v134, 7, v252
	v_ashrrev_i32_e32 v185, 31, v184
	global_load_dwordx4 v[132:135], v72, s[98:99]
	global_load_dwordx4 v[136:139], v74, s[98:99]
	v_lshlrev_b64 v[72:73], 11, v[184:185]
	v_lshl_add_u64 v[72:73], v[168:169], 0, v[72:73]
	global_load_dwordx4 v[140:143], v[72:73], off offset:16
	s_nop 0
	global_load_dwordx4 v[72:75], v[72:73], off

; #define V_ISSUE(SEG, E0, E1) { _Pragma("unroll") for (int b = 0; b < 16; ++b) { const int e = __shfl((b < 8) ? (E0) : (E1), (b & 7) * 8 + grp); SEG[b] = *(const u32x4*)(vb + (size_t)e * DM); } }
; DI void peer_v_phase(const bf16_t* __restrict__ x1, const int* __restrict__ eidx, const float* __restrict__ wgt, const unsigned char* __restrict__ V8, bf16_t* __restrict__ y) {
;     ...
;     for (int j_ = sm.j0; j_ < 8 * REP_PV; j_ += sm.jstep) {
;         const int j = j_ & 7;
;         const unsigned char* vb = V8 + 128 * j + 16 * l8;
;         const int col = 128 * j + 16 * l8 + 2 * grp;
;         const int step = sm.nslot;
;         int t = sm.wslot;
;         if (t >= T_TOK) continue;
;         u32x4 sa[16], sb[16];
;         int e0n = 0, e1n = 0;
;         float w0, w1, w0n = 0.f, w1n = 0.f;
;     ...
;         {
;             const int e0 = eidx[(size_t)t * 128 + lane], e1 = eidx[(size_t)t * 128 + 64 + lane];
;             w0 = wgt[(size_t)t * 128 + lane]; w1 = wgt[(size_t)t * 128 + 64 + lane];
;             V_ISSUE(sa, e0, e1)
;             if (t + step < T_TOK) { e0n = eidx[(size_t)(t + step) * 128 + lane]; e1n = eidx[(size_t)(t + step) * 128 + 64 + lane]; }
;         }
.LBB0_1352:
	s_and_saveexec_b64 s[20:21], vcc
	s_cbranch_execz .LBB0_1351
	global_load_dword v65, v[134:135], off
	global_load_dword v67, v[136:137], off
	s_lshl_b32 s16, s5, 21
	v_lshl_add_u64 v[152:153], v[132:133], 0, s[16:17]
	s_lshl_b32 s16, s5, 7
	v_and_b32_e32 v252, 7, v172
	v_lshlrev_b32_e32 v252, 4, v252
	v_readfirstlane_b32 s98, v152
	v_readfirstlane_b32 s99, v153
	global_load_dword v177, v[138:139], off
	global_load_dword v179, v[140:141], off
	v_mov_b32_e32 v180, 0
	v_mov_b32_e32 v178, 0
	v_mov_b32_e32 v176, 0
	s_waitcnt vmcnt(3)
	ds_bpermute_b32 v64, v129, v65
	ds_bpermute_b32 v66, v164, v65
	ds_bpermute_b32 v68, v165, v65
	ds_bpermute_b32 v70, v166, v65
	ds_bpermute_b32 v72, v167, v65
	ds_bpermute_b32 v74, v168, v65
	ds_bpermute_b32 v76, v169, v65
	ds_bpermute_b32 v78, v174, v65
	s_waitcnt vmcnt(2)
	ds_bpermute_b32 v80, v129, v67
	ds_bpermute_b32 v82, v164, v67
	ds_bpermute_b32 v84, v165, v67
	ds_bpermute_b32 v86, v166, v67
	ds_bpermute_b32 v88, v167, v67
	ds_bpermute_b32 v90, v168, v67
	ds_bpermute_b32 v92, v169, v67
	ds_bpermute_b32 v94, v174, v67
	s_waitcnt lgkmcnt(0)
	v_lshl_add_u32 v64, v64, 7, v252
	v_lshl_add_u32 v66, v66, 7, v252
	v_lshl_add_u32 v68, v68, 7, v252
	v_lshl_add_u32 v70, v70, 7, v252
	v_lshl_add_u32 v72, v72, 7, v252
	v_lshl_add_u32 v74, v74, 7, v252
	v_lshl_add_u32 v76, v76, 7, v252
	v_lshl_add_u32 v78, v78, 7, v252
	v_lshl_add_u32 v80, v80, 7, v252
	v_lshl_add_u32 v82, v82, 7, v252
	v_lshl_add_u32 v84, v84, 7, v252
	v_lshl_add_u32 v86, v86, 7, v252
	v_lshl_add_u32 v88, v88, 7, v252
	v_lshl_add_u32 v90, v90, 7, v252
	v_lshl_add_u32 v92, v92, 7, v252
	v_lshl_add_u32 v94, v94, 7, v252
	v_mov_b32_e32 v96, v66
	v_mov_b32_e32 v98, v68
	v_mov_b32_e32 v100, v70
	v_mov_b32_e32 v102, v72
	v_mov_b32_e32 v104, v74
	v_mov_b32_e32 v106, v76
	v_mov_b32_e32 v108, v78
	v_mov_b32_e32 v110, v80
	v_mov_b32_e32 v112, v82
	v_mov_b32_e32 v114, v84
	v_mov_b32_e32 v116, v86
	v_mov_b32_e32 v118, v88
	v_mov_b32_e32 v120, v90
	v_mov_b32_e32 v122, v92
	v_mov_b32_e32 v124, v94
	global_load_dwordx4 v[64:67], v64, s[98:99]
	s_nop 0
	global_load_dwordx4 v[68:71], v96, s[98:99]
	global_load_dwordx4 v[72:75], v98, s[98:99]
	global_load_dwordx4 v[76:79], v100, s[98:99]
	global_load_dwordx4 v[80:83], v102, s[98:99]
	global_load_dwordx4 v[84:87], v104, s[98:99]
	global_load_dwordx4 v[88:91], v106, s[98:99]
	global_load_dwordx4 v[92:95], v108, s[98:99]
	global_load_dwordx4 v[96:99], v110, s[98:99]
	s_nop 0
	global_load_dwordx4 v[100:103], v112, s[98:99]
	global_load_dwordx4 v[104:107], v114, s[98:99]
	global_load_dwordx4 v[108:111], v116, s[98:99]
	s_nop 0
	global_load_dwordx4 v[112:115], v118, s[98:99]
	s_nop 0
	global_load_dwordx4 v[116:119], v120, s[98:99]
	s_nop 0
	global_load_dwordx4 v[120:123], v122, s[98:99]
	s_nop 0
	global_load_dwordx4 v[124:127], v124, s[98:99]
	s_and_saveexec_b64 s[0:1], s[2:3]
	s_cbranch_execz .LBB0_1355
	global_load_dword v176, v[142:143], off
	global_load_dword v178, v[142:143], off offset:256

; #define V_ISSUE(SEG, E0, E1) { _Pragma("unroll") for (int b = 0; b < 16; ++b) { const int e = __shfl((b < 8) ? (E0) : (E1), (b & 7) * 8 + grp); SEG[b] = *(const u32x4*)(vb + (size_t)e * DM); } }
; DI void peer_v_phase(const bf16_t* __restrict__ x1, const int* __restrict__ eidx, const float* __restrict__ wgt, const unsigned char* __restrict__ V8, bf16_t* __restrict__ y) {
;     ...
;         {
;             const int e0 = eidx[(size_t)t * 128 + lane], e1 = eidx[(size_t)t * 128 + 64 + lane];
;             w0 = wgt[(size_t)t * 128 + lane]; w1 = wgt[(size_t)t * 128 + 64 + lane];
;             V_ISSUE(sa, e0, e1)
;             if (t + step < T_TOK) { e0n = eidx[(size_t)(t + step) * 128 + lane]; e1n = eidx[(size_t)(t + step) * 128 + 64 + lane]; }
;         }
;         for (; t < T_TOK; t += 2 * step) {
;             int e0nn = 0, e1nn = 0;
;             const bool n1 = t + step < T_TOK, n2 = t + 2 * step < T_TOK, n3 = t + 3 * step < T_TOK;
;             if (n1) { V_ISSUE(sb, e0n, e1n) w0n = wgt[(size_t)(t + step) * 128 + lane]; w1n = wgt[(size_t)(t + step) * 128 + 64 + lane]; }
;             if (n2) { e0nn = eidx[(size_t)(t + 2 * step) * 128 + lane]; e1nn = eidx[(size_t)(t + 2 * step) * 128 + 64 + lane]; }
.LBB0_1358:
	v_add_u32_e32 v158, s54, v160
	v_cmp_gt_i32_e64 s[12:13], s19, v158
	v_ashrrev_i32_e32 v159, 31, v158
	s_and_saveexec_b64 s[0:1], s[12:13]
	s_cbranch_execz .LBB0_1360
	s_waitcnt vmcnt(1)
	ds_bpermute_b32 v0, v129, v176
	ds_bpermute_b32 v2, v164, v176
	ds_bpermute_b32 v8, v165, v176
	ds_bpermute_b32 v10, v166, v176
	ds_bpermute_b32 v16, v167, v176
	ds_bpermute_b32 v18, v168, v176
	ds_bpermute_b32 v24, v169, v176
	ds_bpermute_b32 v26, v174, v176
	s_waitcnt vmcnt(0)
	ds_bpermute_b32 v32, v129, v178
	ds_bpermute_b32 v34, v164, v178
	ds_bpermute_b32 v40, v165, v178
	ds_bpermute_b32 v42, v166, v178
	ds_bpermute_b32 v48, v167, v178
	ds_bpermute_b32 v50, v168, v178
	ds_bpermute_b32 v56, v169, v178
	ds_bpermute_b32 v58, v174, v178
	s_waitcnt lgkmcnt(0)
	v_lshl_add_u32 v0, v0, 7, v252
	v_lshl_add_u32 v2, v2, 7, v252
	v_lshl_add_u32 v8, v8, 7, v252
	v_lshl_add_u32 v10, v10, 7, v252
	v_lshl_add_u32 v16, v16, 7, v252
	v_lshl_add_u32 v18, v18, 7, v252
	v_lshl_add_u32 v24, v24, 7, v252
	v_lshl_add_u32 v26, v26, 7, v252
	v_lshl_add_u32 v32, v32, 7, v252
	v_lshl_add_u32 v34, v34, 7, v252
	v_lshl_add_u32 v40, v40, 7, v252
	v_lshl_add_u32 v42, v42, 7, v252
	v_lshl_add_u32 v48, v48, 7, v252
	v_lshl_add_u32 v50, v50, 7, v252
	v_lshl_add_u32 v56, v56, 7, v252
	v_lshl_add_u32 v58, v58, 7, v252
	v_lshlrev_b64 v[162:163], 9, v[158:159]
	v_mov_b32_e32 v20, v18
	v_mov_b32_e32 v28, v26
	v_mov_b32_e32 v36, v34
	v_mov_b32_e32 v44, v42
	v_mov_b32_e32 v52, v50
	v_mov_b32_e32 v60, v58
	v_lshl_add_u64 v[162:163], v[144:145], 0, v[162:163]
	global_load_dwordx4 v[4:7], v0, s[98:99]
	s_nop 0
	global_load_dwordx4 v[0:3], v2, s[98:99]
	s_nop 0
	global_load_dwordx4 v[12:15], v8, s[98:99]
	s_nop 0
	global_load_dwordx4 v[8:11], v10, s[98:99]
	s_nop 0
	global_load_dwordx4 v[16:19], v16, s[98:99]
	s_nop 0
	global_load_dwordx4 v[20:23], v20, s[98:99]
	s_nop 0
	global_load_dwordx4 v[24:27], v24, s[98:99]
	s_nop 0
	global_load_dwordx4 v[28:31], v28, s[98:99]
	s_nop 0
	global_load_dwordx4 v[32:35], v32, s[98:99]
	s_nop 0
	global_load_dwordx4 v[36:39], v36, s[98:99]
	s_nop 0
	global_load_dwordx4 v[40:43], v40, s[98:99]
	s_nop 0
	global_load_dwordx4 v[44:47], v44, s[98:99]
	s_nop 0
	global_load_dwordx4 v[48:51], v48, s[98:99]
	s_nop 0
	global_load_dwordx4 v[52:55], v52, s[98:99]
	s_nop 0
	global_load_dwordx4 v[56:59], v56, s[98:99]
	s_nop 0
	global_load_dwordx4 v[60:63], v60, s[98:99]
	s_nop 0
	global_load_dword v180, v[162:163], off
	global_load_dword v130, v[162:163], off offset:256

; DI void axpy_fp8_row(f32x2 (&o)[8], float wgt, u32x4 v) {
;     const f32x2 w2 = {wgt, wgt};
; #pragma unroll
;     for (int j = 0; j < 4; ++j) {
;         const f32x2 lo = __builtin_amdgcn_cvt_pk_f32_fp8(v[j], false), hi = __builtin_amdgcn_cvt_pk_f32_fp8(v[j], true);
;         o[2 * j] = __builtin_elementwise_fma(w2, lo, o[2 * j]);
;         o[2 * j + 1] = __builtin_elementwise_fma(w2, hi, o[2 * j + 1]);
;     }
; }
.LBB0_1362:
	s_or_b64 exec, exec, s[0:1]
	s_setprio 1
	s_waitcnt vmcnt(17)
	ds_bpermute_b32 v182, v129, v177
	s_waitcnt vmcnt(15)
	v_cvt_pk_f32_fp8_e32 v[184:185], v64
	v_cvt_pk_f32_fp8_sdwa v[188:189], v64 src0_sel:WORD_1
	v_cvt_pk_f32_fp8_e32 v[190:191], v65
	v_cvt_pk_f32_fp8_sdwa v[198:199], v65 src0_sel:WORD_1
	v_cvt_pk_f32_fp8_e32 v[200:201], v66
	v_cvt_pk_f32_fp8_sdwa v[202:203], v66 src0_sel:WORD_1
	v_cvt_pk_f32_fp8_e32 v[204:205], v67
	v_cvt_pk_f32_fp8_sdwa v[206:207], v67 src0_sel:WORD_1
	ds_bpermute_b32 v196, v164, v177
	s_waitcnt lgkmcnt(1)
	v_pk_fma_f32 v[184:185], v[182:183], v[184:185], 0 op_sel_hi:[0,1,0]
	v_pk_fma_f32 v[188:189], v[182:183], v[188:189], 0 op_sel_hi:[0,1,0]
	v_pk_fma_f32 v[190:191], v[182:183], v[190:191], 0 op_sel_hi:[0,1,0]
	v_pk_fma_f32 v[198:199], v[182:183], v[198:199], 0 op_sel_hi:[0,1,0]
	v_pk_fma_f32 v[200:201], v[182:183], v[200:201], 0 op_sel_hi:[0,1,0]
	v_pk_fma_f32 v[202:203], v[182:183], v[202:203], 0 op_sel_hi:[0,1,0]
	v_pk_fma_f32 v[204:205], v[182:183], v[204:205], 0 op_sel_hi:[0,1,0]
	v_pk_fma_f32 v[182:183], v[182:183], v[206:207], 0 op_sel_hi:[0,1,0]
	s_waitcnt vmcnt(14)
	v_cvt_pk_f32_fp8_e32 v[206:207], v68
	v_cvt_pk_f32_fp8_sdwa v[208:209], v68 src0_sel:WORD_1
	v_cvt_pk_f32_fp8_e32 v[210:211], v69
	v_cvt_pk_f32_fp8_sdwa v[212:213], v69 src0_sel:WORD_1
	s_waitcnt lgkmcnt(0)
	v_pk_fma_f32 v[184:185], v[196:197], v[206:207], v[184:185] op_sel_hi:[0,1,1]
	v_pk_fma_f32 v[188:189], v[196:197], v[208:209], v[188:189] op_sel_hi:[0,1,1]
	v_pk_fma_f32 v[190:191], v[196:197], v[210:211], v[190:191] op_sel_hi:[0,1,1]
	v_pk_fma_f32 v[198:199], v[196:197], v[212:213], v[198:199] op_sel_hi:[0,1,1]
	v_cvt_pk_f32_fp8_e32 v[206:207], v70
	v_cvt_pk_f32_fp8_sdwa v[208:209], v70 src0_sel:WORD_1
	v_cvt_pk_f32_fp8_e32 v[210:211], v71
	v_cvt_pk_f32_fp8_sdwa v[212:213], v71 src0_sel:WORD_1
	v_pk_fma_f32 v[200:201], v[196:197], v[206:207], v[200:201] op_sel_hi:[0,1,1]
	v_pk_fma_f32 v[202:203], v[196:197], v[208:209], v[202:203] op_sel_hi:[0,1,1]
	v_pk_fma_f32 v[204:205], v[196:197], v[210:211], v[204:205] op_sel_hi:[0,1,1]
	v_pk_fma_f32 v[182:183], v[196:197], v[212:213], v[182:183] op_sel_hi:[0,1,1]
	ds_bpermute_b32 v196, v165, v177
	s_waitcnt vmcnt(13)
	v_cvt_pk_f32_fp8_e32 v[206:207], v72
	v_cvt_pk_f32_fp8_sdwa v[208:209], v72 src0_sel:WORD_1
	v_cvt_pk_f32_fp8_e32 v[210:211], v73
	v_cvt_pk_f32_fp8_sdwa v[212:213], v73 src0_sel:WORD_1
	s_waitcnt lgkmcnt(0)
	v_pk_fma_f32 v[184:185], v[196:197], v[206:207], v[184:185] op_sel_hi:[0,1,1]
	v_pk_fma_f32 v[188:189], v[196:197], v[208:209], v[188:189] op_sel_hi:[0,1,1]
	v_pk_fma_f32 v[190:191], v[196:197], v[210:211], v[190:191] op_sel_hi:[0,1,1]
	v_pk_fma_f32 v[198:199], v[196:197], v[212:213], v[198:199] op_sel_hi:[0,1,1]
	v_cvt_pk_f32_fp8_e32 v[206:207], v74
	v_cvt_pk_f32_fp8_sdwa v[208:209], v74 src0_sel:WORD_1
	v_cvt_pk_f32_fp8_e32 v[210:211], v75
	v_cvt_pk_f32_fp8_sdwa v[212:213], v75 src0_sel:WORD_1
	v_pk_fma_f32 v[200:201], v[196:197], v[206:207], v[200:201] op_sel_hi:[0,1,1]
	v_pk_fma_f32 v[202:203], v[196:197], v[208:209], v[202:203] op_sel_hi:[0,1,1]
	v_pk_fma_f32 v[204:205], v[196:197], v[210:211], v[204:205] op_sel_hi:[0,1,1]
	v_pk_fma_f32 v[182:183], v[196:197], v[212:213], v[182:183] op_sel_hi:[0,1,1]
	ds_bpermute_b32 v196, v166, v177
	s_waitcnt vmcnt(12)
	v_cvt_pk_f32_fp8_e32 v[206:207], v76
	v_cvt_pk_f32_fp8_sdwa v[208:209], v76 src0_sel:WORD_1
	v_cvt_pk_f32_fp8_e32 v[210:211], v77
	v_cvt_pk_f32_fp8_sdwa v[212:213], v77 src0_sel:WORD_1
	s_waitcnt lgkmcnt(0)
	v_pk_fma_f32 v[184:185], v[196:197], v[206:207], v[184:185] op_sel_hi:[0,1,1]
	v_pk_fma_f32 v[188:189], v[196:197], v[208:209], v[188:189] op_sel_hi:[0,1,1]
	v_pk_fma_f32 v[190:191], v[196:197], v[210:211], v[190:191] op_sel_hi:[0,1,1]
	v_pk_fma_f32 v[198:199], v[196:197], v[212:213], v[198:199] op_sel_hi:[0,1,1]
	v_cvt_pk_f32_fp8_e32 v[206:207], v78
	v_cvt_pk_f32_fp8_sdwa v[208:209], v78 src0_sel:WORD_1
	v_cvt_pk_f32_fp8_e32 v[210:211], v79
	v_cvt_pk_f32_fp8_sdwa v[212:213], v79 src0_sel:WORD_1
	v_pk_fma_f32 v[200:201], v[196:197], v[206:207], v[200:201] op_sel_hi:[0,1,1]
	v_pk_fma_f32 v[202:203], v[196:197], v[208:209], v[202:203] op_sel_hi:[0,1,1]
	v_pk_fma_f32 v[204:205], v[196:197], v[210:211], v[204:205] op_sel_hi:[0,1,1]
	v_pk_fma_f32 v[182:183], v[196:197], v[212:213], v[182:183] op_sel_hi:[0,1,1]
	ds_bpermute_b32 v196, v167, v177
	s_waitcnt vmcnt(11)
	v_cvt_pk_f32_fp8_e32 v[206:207], v80
	v_cvt_pk_f32_fp8_sdwa v[208:209], v80 src0_sel:WORD_1
	v_cvt_pk_f32_fp8_e32 v[210:211], v81
	v_cvt_pk_f32_fp8_sdwa v[212:213], v81 src0_sel:WORD_1
	s_waitcnt lgkmcnt(0)
	v_pk_fma_f32 v[184:185], v[196:197], v[206:207], v[184:185] op_sel_hi:[0,1,1]
	v_pk_fma_f32 v[188:189], v[196:197], v[208:209], v[188:189] op_sel_hi:[0,1,1]
	v_pk_fma_f32 v[190:191], v[196:197], v[210:211], v[190:191] op_sel_hi:[0,1,1]
	v_pk_fma_f32 v[198:199], v[196:197], v[212:213], v[198:199] op_sel_hi:[0,1,1]
	v_cvt_pk_f32_fp8_e32 v[206:207], v82
	v_cvt_pk_f32_fp8_sdwa v[208:209], v82 src0_sel:WORD_1
	v_cvt_pk_f32_fp8_e32 v[210:211], v83
	v_cvt_pk_f32_fp8_sdwa v[212:213], v83 src0_sel:WORD_1
	v_pk_fma_f32 v[200:201], v[196:197], v[206:207], v[200:201] op_sel_hi:[0,1,1]
	v_pk_fma_f32 v[202:203], v[196:197], v[208:209], v[202:203] op_sel_hi:[0,1,1]
	v_pk_fma_f32 v[204:205], v[196:197], v[210:211], v[204:205] op_sel_hi:[0,1,1]
	v_pk_fma_f32 v[182:183], v[196:197], v[212:213], v[182:183] op_sel_hi:[0,1,1]
	ds_bpermute_b32 v196, v168, v177
	s_waitcnt vmcnt(10)
	v_cvt_pk_f32_fp8_e32 v[206:207], v84
	v_cvt_pk_f32_fp8_sdwa v[208:209], v84 src0_sel:WORD_1
	v_cvt_pk_f32_fp8_e32 v[210:211], v85
	v_cvt_pk_f32_fp8_sdwa v[212:213], v85 src0_sel:WORD_1
	s_waitcnt lgkmcnt(0)
; DI void axpy_fp8_row(f32x2 (&o)[8], float wgt, u32x4 v) {
;     const f32x2 w2 = {wgt, wgt};
; #pragma unroll
;     for (int j = 0; j < 4; ++j) {
;         const f32x2 lo = __builtin_amdgcn_cvt_pk_f32_fp8(v[j], false), hi = __builtin_amdgcn_cvt_pk_f32_fp8(v[j], true);
;         o[2 * j] = __builtin_elementwise_fma(w2, lo, o[2 * j]);
;         o[2 * j + 1] = __builtin_elementwise_fma(w2, hi, o[2 * j + 1]);
;     }
; }
	v_pk_fma_f32 v[184:185], v[196:197], v[206:207], v[184:185] op_sel_hi:[0,1,1]
	v_pk_fma_f32 v[188:189], v[196:197], v[208:209], v[188:189] op_sel_hi:[0,1,1]
	v_pk_fma_f32 v[190:191], v[196:197], v[210:211], v[190:191] op_sel_hi:[0,1,1]
	v_pk_fma_f32 v[198:199], v[196:197], v[212:213], v[198:199] op_sel_hi:[0,1,1]
	v_cvt_pk_f32_fp8_e32 v[206:207], v86
	v_cvt_pk_f32_fp8_sdwa v[208:209], v86 src0_sel:WORD_1
	v_cvt_pk_f32_fp8_e32 v[210:211], v87
	v_cvt_pk_f32_fp8_sdwa v[212:213], v87 src0_sel:WORD_1
	v_pk_fma_f32 v[200:201], v[196:197], v[206:207], v[200:201] op_sel_hi:[0,1,1]
	v_pk_fma_f32 v[202:203], v[196:197], v[208:209], v[202:203] op_sel_hi:[0,1,1]
	v_pk_fma_f32 v[204:205], v[196:197], v[210:211], v[204:205] op_sel_hi:[0,1,1]
	v_pk_fma_f32 v[182:183], v[196:197], v[212:213], v[182:183] op_sel_hi:[0,1,1]
	ds_bpermute_b32 v196, v169, v177
	s_waitcnt vmcnt(9)
	v_cvt_pk_f32_fp8_e32 v[206:207], v88
	v_cvt_pk_f32_fp8_sdwa v[208:209], v88 src0_sel:WORD_1
	v_cvt_pk_f32_fp8_e32 v[210:211], v89
	v_cvt_pk_f32_fp8_sdwa v[212:213], v89 src0_sel:WORD_1
	s_waitcnt lgkmcnt(0)
	v_pk_fma_f32 v[184:185], v[196:197], v[206:207], v[184:185] op_sel_hi:[0,1,1]
	v_pk_fma_f32 v[188:189], v[196:197], v[208:209], v[188:189] op_sel_hi:[0,1,1]
	v_pk_fma_f32 v[190:191], v[196:197], v[210:211], v[190:191] op_sel_hi:[0,1,1]
	v_pk_fma_f32 v[198:199], v[196:197], v[212:213], v[198:199] op_sel_hi:[0,1,1]
	v_cvt_pk_f32_fp8_e32 v[206:207], v90
	v_cvt_pk_f32_fp8_sdwa v[208:209], v90 src0_sel:WORD_1
	v_cvt_pk_f32_fp8_e32 v[210:211], v91
	v_cvt_pk_f32_fp8_sdwa v[212:213], v91 src0_sel:WORD_1
	v_pk_fma_f32 v[200:201], v[196:197], v[206:207], v[200:201] op_sel_hi:[0,1,1]
	v_pk_fma_f32 v[202:203], v[196:197], v[208:209], v[202:203] op_sel_hi:[0,1,1]
	v_pk_fma_f32 v[204:205], v[196:197], v[210:211], v[204:205] op_sel_hi:[0,1,1]
	v_pk_fma_f32 v[182:183], v[196:197], v[212:213], v[182:183] op_sel_hi:[0,1,1]
	ds_bpermute_b32 v196, v174, v177
	s_waitcnt vmcnt(8)
	v_cvt_pk_f32_fp8_e32 v[206:207], v92
	v_cvt_pk_f32_fp8_sdwa v[208:209], v92 src0_sel:WORD_1
	v_cvt_pk_f32_fp8_e32 v[210:211], v93
	v_cvt_pk_f32_fp8_sdwa v[212:213], v93 src0_sel:WORD_1
	s_waitcnt lgkmcnt(0)
	v_pk_fma_f32 v[184:185], v[196:197], v[206:207], v[184:185] op_sel_hi:[0,1,1]
	v_pk_fma_f32 v[188:189], v[196:197], v[208:209], v[188:189] op_sel_hi:[0,1,1]
	v_pk_fma_f32 v[190:191], v[196:197], v[210:211], v[190:191] op_sel_hi:[0,1,1]
	v_pk_fma_f32 v[198:199], v[196:197], v[212:213], v[198:199] op_sel_hi:[0,1,1]
	v_cvt_pk_f32_fp8_e32 v[206:207], v94
	v_cvt_pk_f32_fp8_sdwa v[208:209], v94 src0_sel:WORD_1
	v_cvt_pk_f32_fp8_e32 v[210:211], v95
	v_cvt_pk_f32_fp8_sdwa v[212:213], v95 src0_sel:WORD_1
	v_pk_fma_f32 v[200:201], v[196:197], v[206:207], v[200:201] op_sel_hi:[0,1,1]
	v_pk_fma_f32 v[202:203], v[196:197], v[208:209], v[202:203] op_sel_hi:[0,1,1]
	v_pk_fma_f32 v[204:205], v[196:197], v[210:211], v[204:205] op_sel_hi:[0,1,1]
	v_pk_fma_f32 v[182:183], v[196:197], v[212:213], v[182:183] op_sel_hi:[0,1,1]
	ds_bpermute_b32 v196, v129, v179
	s_waitcnt vmcnt(7)
	v_cvt_pk_f32_fp8_e32 v[206:207], v96
	v_cvt_pk_f32_fp8_sdwa v[208:209], v96 src0_sel:WORD_1
	v_cvt_pk_f32_fp8_e32 v[210:211], v97
	v_cvt_pk_f32_fp8_sdwa v[212:213], v97 src0_sel:WORD_1
	s_waitcnt lgkmcnt(0)
	v_pk_fma_f32 v[184:185], v[196:197], v[206:207], v[184:185] op_sel_hi:[0,1,1]
	v_pk_fma_f32 v[188:189], v[196:197], v[208:209], v[188:189] op_sel_hi:[0,1,1]
	v_pk_fma_f32 v[190:191], v[196:197], v[210:211], v[190:191] op_sel_hi:[0,1,1]
	v_pk_fma_f32 v[198:199], v[196:197], v[212:213], v[198:199] op_sel_hi:[0,1,1]
	v_cvt_pk_f32_fp8_e32 v[206:207], v98
	v_cvt_pk_f32_fp8_sdwa v[208:209], v98 src0_sel:WORD_1
	v_cvt_pk_f32_fp8_e32 v[210:211], v99
	v_cvt_pk_f32_fp8_sdwa v[212:213], v99 src0_sel:WORD_1
	v_pk_fma_f32 v[200:201], v[196:197], v[206:207], v[200:201] op_sel_hi:[0,1,1]
	v_pk_fma_f32 v[202:203], v[196:197], v[208:209], v[202:203] op_sel_hi:[0,1,1]
	v_pk_fma_f32 v[204:205], v[196:197], v[210:211], v[204:205] op_sel_hi:[0,1,1]
	v_pk_fma_f32 v[182:183], v[196:197], v[212:213], v[182:183] op_sel_hi:[0,1,1]
	ds_bpermute_b32 v196, v164, v179
	s_waitcnt vmcnt(6)
	v_cvt_pk_f32_fp8_e32 v[206:207], v100
	v_cvt_pk_f32_fp8_sdwa v[208:209], v100 src0_sel:WORD_1
	v_cvt_pk_f32_fp8_e32 v[210:211], v101
	v_cvt_pk_f32_fp8_sdwa v[212:213], v101 src0_sel:WORD_1
	s_waitcnt lgkmcnt(0)
	v_pk_fma_f32 v[184:185], v[196:197], v[206:207], v[184:185] op_sel_hi:[0,1,1]
	v_pk_fma_f32 v[188:189], v[196:197], v[208:209], v[188:189] op_sel_hi:[0,1,1]
	v_pk_fma_f32 v[190:191], v[196:197], v[210:211], v[190:191] op_sel_hi:[0,1,1]
	v_pk_fma_f32 v[198:199], v[196:197], v[212:213], v[198:199] op_sel_hi:[0,1,1]
	v_cvt_pk_f32_fp8_e32 v[206:207], v102
	v_cvt_pk_f32_fp8_sdwa v[208:209], v102 src0_sel:WORD_1
	v_cvt_pk_f32_fp8_e32 v[210:211], v103
	v_cvt_pk_f32_fp8_sdwa v[212:213], v103 src0_sel:WORD_1
	v_pk_fma_f32 v[200:201], v[196:197], v[206:207], v[200:201] op_sel_hi:[0,1,1]
	v_pk_fma_f32 v[202:203], v[196:197], v[208:209], v[202:203] op_sel_hi:[0,1,1]
	v_pk_fma_f32 v[204:205], v[196:197], v[210:211], v[204:205] op_sel_hi:[0,1,1]
	v_pk_fma_f32 v[182:183], v[196:197], v[212:213], v[182:183] op_sel_hi:[0,1,1]
	ds_bpermute_b32 v196, v165, v179
	s_waitcnt vmcnt(5)
	v_cvt_pk_f32_fp8_e32 v[206:207], v104
	v_cvt_pk_f32_fp8_sdwa v[208:209], v104 src0_sel:WORD_1
	v_cvt_pk_f32_fp8_e32 v[210:211], v105
	v_cvt_pk_f32_fp8_sdwa v[212:213], v105 src0_sel:WORD_1
	s_waitcnt lgkmcnt(0)
; DI void axpy_fp8_row(f32x2 (&o)[8], float wgt, u32x4 v) {
;     const f32x2 w2 = {wgt, wgt};
; #pragma unroll
;     for (int j = 0; j < 4; ++j) {
;         const f32x2 lo = __builtin_amdgcn_cvt_pk_f32_fp8(v[j], false), hi = __builtin_amdgcn_cvt_pk_f32_fp8(v[j], true);
;         o[2 * j] = __builtin_elementwise_fma(w2, lo, o[2 * j]);
;         o[2 * j + 1] = __builtin_elementwise_fma(w2, hi, o[2 * j + 1]);
;     }
; }
	v_pk_fma_f32 v[184:185], v[196:197], v[206:207], v[184:185] op_sel_hi:[0,1,1]
	v_pk_fma_f32 v[188:189], v[196:197], v[208:209], v[188:189] op_sel_hi:[0,1,1]
	v_pk_fma_f32 v[190:191], v[196:197], v[210:211], v[190:191] op_sel_hi:[0,1,1]
	v_pk_fma_f32 v[198:199], v[196:197], v[212:213], v[198:199] op_sel_hi:[0,1,1]
	v_cvt_pk_f32_fp8_e32 v[206:207], v106
	v_cvt_pk_f32_fp8_sdwa v[208:209], v106 src0_sel:WORD_1
	v_cvt_pk_f32_fp8_e32 v[210:211], v107
	v_cvt_pk_f32_fp8_sdwa v[212:213], v107 src0_sel:WORD_1
	v_pk_fma_f32 v[200:201], v[196:197], v[206:207], v[200:201] op_sel_hi:[0,1,1]
	v_pk_fma_f32 v[202:203], v[196:197], v[208:209], v[202:203] op_sel_hi:[0,1,1]
	v_pk_fma_f32 v[204:205], v[196:197], v[210:211], v[204:205] op_sel_hi:[0,1,1]
	v_pk_fma_f32 v[182:183], v[196:197], v[212:213], v[182:183] op_sel_hi:[0,1,1]
	ds_bpermute_b32 v196, v166, v179
	s_waitcnt vmcnt(4)
	v_cvt_pk_f32_fp8_e32 v[206:207], v108
	v_cvt_pk_f32_fp8_sdwa v[208:209], v108 src0_sel:WORD_1
	v_cvt_pk_f32_fp8_e32 v[210:211], v109
	v_cvt_pk_f32_fp8_sdwa v[212:213], v109 src0_sel:WORD_1
	s_waitcnt lgkmcnt(0)
	v_pk_fma_f32 v[184:185], v[196:197], v[206:207], v[184:185] op_sel_hi:[0,1,1]
	v_pk_fma_f32 v[188:189], v[196:197], v[208:209], v[188:189] op_sel_hi:[0,1,1]
	v_pk_fma_f32 v[190:191], v[196:197], v[210:211], v[190:191] op_sel_hi:[0,1,1]
	v_pk_fma_f32 v[198:199], v[196:197], v[212:213], v[198:199] op_sel_hi:[0,1,1]
	v_cvt_pk_f32_fp8_e32 v[206:207], v110
	v_cvt_pk_f32_fp8_sdwa v[208:209], v110 src0_sel:WORD_1
	v_cvt_pk_f32_fp8_e32 v[210:211], v111
	v_cvt_pk_f32_fp8_sdwa v[212:213], v111 src0_sel:WORD_1
	v_pk_fma_f32 v[200:201], v[196:197], v[206:207], v[200:201] op_sel_hi:[0,1,1]
	v_pk_fma_f32 v[202:203], v[196:197], v[208:209], v[202:203] op_sel_hi:[0,1,1]
	v_pk_fma_f32 v[204:205], v[196:197], v[210:211], v[204:205] op_sel_hi:[0,1,1]
	v_pk_fma_f32 v[182:183], v[196:197], v[212:213], v[182:183] op_sel_hi:[0,1,1]
	ds_bpermute_b32 v196, v167, v179
	s_waitcnt vmcnt(3)
	v_cvt_pk_f32_fp8_e32 v[206:207], v112
	v_cvt_pk_f32_fp8_sdwa v[208:209], v112 src0_sel:WORD_1
	v_cvt_pk_f32_fp8_e32 v[210:211], v113
	v_cvt_pk_f32_fp8_sdwa v[212:213], v113 src0_sel:WORD_1
	s_waitcnt lgkmcnt(0)
	v_pk_fma_f32 v[184:185], v[196:197], v[206:207], v[184:185] op_sel_hi:[0,1,1]
	v_pk_fma_f32 v[188:189], v[196:197], v[208:209], v[188:189] op_sel_hi:[0,1,1]
	v_pk_fma_f32 v[190:191], v[196:197], v[210:211], v[190:191] op_sel_hi:[0,1,1]
	v_pk_fma_f32 v[198:199], v[196:197], v[212:213], v[198:199] op_sel_hi:[0,1,1]
	v_cvt_pk_f32_fp8_e32 v[206:207], v114
	v_cvt_pk_f32_fp8_sdwa v[208:209], v114 src0_sel:WORD_1
	v_cvt_pk_f32_fp8_e32 v[210:211], v115
	v_cvt_pk_f32_fp8_sdwa v[212:213], v115 src0_sel:WORD_1
	v_pk_fma_f32 v[200:201], v[196:197], v[206:207], v[200:201] op_sel_hi:[0,1,1]
	v_pk_fma_f32 v[202:203], v[196:197], v[208:209], v[202:203] op_sel_hi:[0,1,1]
	v_pk_fma_f32 v[204:205], v[196:197], v[210:211], v[204:205] op_sel_hi:[0,1,1]
	v_pk_fma_f32 v[182:183], v[196:197], v[212:213], v[182:183] op_sel_hi:[0,1,1]
	ds_bpermute_b32 v196, v168, v179
	s_waitcnt vmcnt(2)
	v_cvt_pk_f32_fp8_e32 v[206:207], v116
	v_cvt_pk_f32_fp8_sdwa v[208:209], v116 src0_sel:WORD_1
	v_cvt_pk_f32_fp8_e32 v[210:211], v117
	v_cvt_pk_f32_fp8_sdwa v[212:213], v117 src0_sel:WORD_1
	s_waitcnt lgkmcnt(0)
	v_pk_fma_f32 v[184:185], v[196:197], v[206:207], v[184:185] op_sel_hi:[0,1,1]
	v_pk_fma_f32 v[188:189], v[196:197], v[208:209], v[188:189] op_sel_hi:[0,1,1]
	v_pk_fma_f32 v[190:191], v[196:197], v[210:211], v[190:191] op_sel_hi:[0,1,1]
	v_pk_fma_f32 v[198:199], v[196:197], v[212:213], v[198:199] op_sel_hi:[0,1,1]
	v_cvt_pk_f32_fp8_e32 v[206:207], v118
	v_cvt_pk_f32_fp8_sdwa v[208:209], v118 src0_sel:WORD_1
	v_cvt_pk_f32_fp8_e32 v[210:211], v119
	v_cvt_pk_f32_fp8_sdwa v[212:213], v119 src0_sel:WORD_1
	v_pk_fma_f32 v[200:201], v[196:197], v[206:207], v[200:201] op_sel_hi:[0,1,1]
	v_pk_fma_f32 v[202:203], v[196:197], v[208:209], v[202:203] op_sel_hi:[0,1,1]
	v_pk_fma_f32 v[204:205], v[196:197], v[210:211], v[204:205] op_sel_hi:[0,1,1]
	v_pk_fma_f32 v[182:183], v[196:197], v[212:213], v[182:183] op_sel_hi:[0,1,1]
	ds_bpermute_b32 v196, v169, v179
	s_waitcnt vmcnt(1)
	v_cvt_pk_f32_fp8_e32 v[206:207], v120
	v_cvt_pk_f32_fp8_sdwa v[208:209], v120 src0_sel:WORD_1
	v_cvt_pk_f32_fp8_e32 v[210:211], v121
	v_cvt_pk_f32_fp8_sdwa v[212:213], v121 src0_sel:WORD_1
	s_waitcnt lgkmcnt(0)
	v_pk_fma_f32 v[184:185], v[196:197], v[206:207], v[184:185] op_sel_hi:[0,1,1]
	v_pk_fma_f32 v[188:189], v[196:197], v[208:209], v[188:189] op_sel_hi:[0,1,1]
	v_pk_fma_f32 v[190:191], v[196:197], v[210:211], v[190:191] op_sel_hi:[0,1,1]
	v_pk_fma_f32 v[198:199], v[196:197], v[212:213], v[198:199] op_sel_hi:[0,1,1]
	v_cvt_pk_f32_fp8_e32 v[206:207], v122
	v_cvt_pk_f32_fp8_sdwa v[208:209], v122 src0_sel:WORD_1
	v_cvt_pk_f32_fp8_e32 v[210:211], v123
	v_cvt_pk_f32_fp8_sdwa v[212:213], v123 src0_sel:WORD_1
	v_pk_fma_f32 v[200:201], v[196:197], v[206:207], v[200:201] op_sel_hi:[0,1,1]
	v_pk_fma_f32 v[202:203], v[196:197], v[208:209], v[202:203] op_sel_hi:[0,1,1]
	v_pk_fma_f32 v[204:205], v[196:197], v[210:211], v[204:205] op_sel_hi:[0,1,1]
	v_pk_fma_f32 v[182:183], v[196:197], v[212:213], v[182:183] op_sel_hi:[0,1,1]
	ds_bpermute_b32 v196, v174, v179
	s_waitcnt vmcnt(0)
	v_cvt_pk_f32_fp8_e32 v[206:207], v124
	v_cvt_pk_f32_fp8_sdwa v[208:209], v124 src0_sel:WORD_1
	v_cvt_pk_f32_fp8_e32 v[210:211], v125
	v_cvt_pk_f32_fp8_sdwa v[212:213], v125 src0_sel:WORD_1
	s_waitcnt lgkmcnt(0)
; #define V_ISSUE(SEG, E0, E1) { _Pragma("unroll") for (int b = 0; b < 16; ++b) { const int e = __shfl((b < 8) ? (E0) : (E1), (b & 7) * 8 + grp); SEG[b] = *(const u32x4*)(vb + (size_t)e * DM); } }
; DI void peer_v_phase(const bf16_t* __restrict__ x1, const int* __restrict__ eidx, const float* __restrict__ wgt, const unsigned char* __restrict__ V8, bf16_t* __restrict__ y) {
;     ...
;             if (n1) {
;                 w0 = w0n; w1 = w1n;
;                 if (n2) { V_ISSUE(sa, e0nn, e1nn) w0n = wgt[(size_t)(t + 2 * step) * 128 + lane]; w1n = wgt[(size_t)(t + 2 * step) * 128 + 64 + lane]; }
;                 if (n3) { e0n = eidx[(size_t)(t + 3 * step) * 128 + lane]; e1n = eidx[(size_t)(t + 3 * step) * 128 + 64 + lane]; }
	v_pk_fma_f32 v[184:185], v[196:197], v[206:207], v[184:185] op_sel_hi:[0,1,1]
	v_cvt_pk_f32_fp8_e32 v[206:207], v126
	v_pk_fma_f32 v[188:189], v[196:197], v[208:209], v[188:189] op_sel_hi:[0,1,1]
	v_cvt_pk_f32_fp8_sdwa v[208:209], v126 src0_sel:WORD_1
	v_pk_fma_f32 v[190:191], v[196:197], v[210:211], v[190:191] op_sel_hi:[0,1,1]
	v_cvt_pk_f32_fp8_e32 v[210:211], v127
	v_pk_fma_f32 v[200:201], v[196:197], v[206:207], v[200:201] op_sel_hi:[0,1,1]
	v_cndmask_b32_e64 v161, v184, v200, s[6:7]
	v_pk_fma_f32 v[198:199], v[196:197], v[212:213], v[198:199] op_sel_hi:[0,1,1]
	v_cvt_pk_f32_fp8_sdwa v[212:213], v127 src0_sel:WORD_1
	v_pk_fma_f32 v[202:203], v[196:197], v[208:209], v[202:203] op_sel_hi:[0,1,1]
	ds_bpermute_b32 v206, v173, v161
	v_cndmask_b32_e64 v161, v185, v201, s[6:7]
	ds_bpermute_b32 v207, v173, v161
	v_cndmask_b32_e64 v161, v188, v202, s[6:7]
	v_pk_fma_f32 v[204:205], v[196:197], v[210:211], v[204:205] op_sel_hi:[0,1,1]
	ds_bpermute_b32 v208, v173, v161
	v_cndmask_b32_e64 v161, v189, v203, s[6:7]
	ds_bpermute_b32 v209, v173, v161
	v_cndmask_b32_e64 v161, v190, v204, s[6:7]
	v_pk_fma_f32 v[182:183], v[196:197], v[212:213], v[182:183] op_sel_hi:[0,1,1]
	ds_bpermute_b32 v210, v173, v161
	v_cndmask_b32_e64 v161, v191, v205, s[6:7]
	ds_bpermute_b32 v211, v173, v161
	v_cndmask_b32_e64 v161, v198, v182, s[6:7]
	ds_bpermute_b32 v212, v173, v161
	v_cndmask_b32_e64 v161, v199, v183, s[6:7]
	ds_bpermute_b32 v213, v173, v161
	s_setprio 0
	v_ashrrev_i32_e32 v161, 31, v160
	v_lshlrev_b64 v[214:215], 11, v[160:161]
	v_lshl_add_u64 v[216:217], v[154:155], 0, v[214:215]
	global_load_dword v161, v[216:217], off
	v_cndmask_b32_e64 v185, v201, v185, s[6:7]
	v_cndmask_b32_e64 v184, v200, v184, s[6:7]
	v_cndmask_b32_e64 v189, v203, v189, s[6:7]
	v_cndmask_b32_e64 v188, v202, v188, s[6:7]
	v_cndmask_b32_e64 v191, v205, v191, s[6:7]
	v_cndmask_b32_e64 v190, v204, v190, s[6:7]
	v_cndmask_b32_e64 v183, v183, v199, s[6:7]
	v_cndmask_b32_e64 v182, v182, v198, s[6:7]
	s_waitcnt lgkmcnt(6)
	v_pk_add_f32 v[184:185], v[184:185], v[206:207]
	s_waitcnt lgkmcnt(4)
	v_pk_add_f32 v[188:189], v[188:189], v[208:209]
	s_waitcnt lgkmcnt(2)
	v_pk_add_f32 v[190:191], v[190:191], v[210:211]
	s_waitcnt lgkmcnt(0)
	v_pk_add_f32 v[182:183], v[182:183], v[212:213]
	v_cndmask_b32_e64 v187, v184, v190, s[8:9]
	v_cndmask_b32_e64 v199, v191, v185, s[8:9]
	v_cndmask_b32_e64 v185, v185, v191, s[8:9]
	v_cndmask_b32_e64 v191, v188, v182, s[8:9]
	v_cndmask_b32_e64 v196, v189, v183, s[8:9]
	ds_bpermute_b32 v200, v175, v187
	ds_bpermute_b32 v201, v175, v185
	ds_bpermute_b32 v202, v175, v191
	ds_bpermute_b32 v203, v175, v196
	v_cndmask_b32_e64 v198, v190, v184, s[8:9]
	v_cndmask_b32_e64 v183, v183, v189, s[8:9]
	v_cndmask_b32_e64 v182, v182, v188, s[8:9]
	s_waitcnt lgkmcnt(2)
	v_pk_add_f32 v[184:185], v[198:199], v[200:201]
	s_waitcnt lgkmcnt(0)
	v_pk_add_f32 v[182:183], v[182:183], v[202:203]
	s_nop 0
	v_cndmask_b32_e64 v187, v184, v182, s[10:11]
	v_cndmask_b32_e64 v189, v185, v183, s[10:11]
	ds_bpermute_b32 v188, v192, v187
	ds_bpermute_b32 v189, v192, v189
	v_cndmask_b32_e64 v183, v183, v185, s[10:11]
	v_cndmask_b32_e64 v182, v182, v184, s[10:11]
	s_waitcnt lgkmcnt(0)
	v_pk_add_f32 v[182:183], v[182:183], v[188:189]
	s_waitcnt vmcnt(0)
	v_lshlrev_b32_e32 v184, 16, v161
	v_and_b32_e32 v185, 0xffff0000, v161
	v_pk_fma_f32 v[182:183], v[184:185], s[18:19], v[182:183] op_sel_hi:[1,0,1]
	s_nop 0
	v_cvt_pk_bf16_f32 v161, v182, v183
	v_lshl_add_u64 v[182:183], v[156:157], 0, v[214:215]
	global_store_dword v[182:183], v161, off
	s_and_saveexec_b64 s[34:35], s[12:13]
	s_cbranch_execz .LBB0_1357
	v_mov_b32_e32 v179, v130
	v_mov_b32_e32 v177, v180
	s_and_saveexec_b64 s[0:1], s[14:15]
	s_cbranch_execz .LBB0_1365
	ds_bpermute_b32 v64, v129, v181
	ds_bpermute_b32 v66, v164, v181
	ds_bpermute_b32 v72, v165, v181
	ds_bpermute_b32 v74, v166, v181
	ds_bpermute_b32 v80, v167, v181
	ds_bpermute_b32 v82, v168, v181
	ds_bpermute_b32 v88, v169, v181
	ds_bpermute_b32 v90, v174, v181
	ds_bpermute_b32 v96, v129, v163
	ds_bpermute_b32 v98, v164, v163
	ds_bpermute_b32 v104, v165, v163
	ds_bpermute_b32 v106, v166, v163
	ds_bpermute_b32 v112, v167, v163
	ds_bpermute_b32 v114, v168, v163
	ds_bpermute_b32 v120, v169, v163
	ds_bpermute_b32 v122, v174, v163
	s_waitcnt lgkmcnt(0)
	v_ashrrev_i32_e32 v163, 31, v162
	v_lshl_add_u32 v64, v64, 7, v252
	v_lshl_add_u32 v66, v66, 7, v252
	v_lshl_add_u32 v72, v72, 7, v252
	v_lshl_add_u32 v74, v74, 7, v252
	v_lshl_add_u32 v80, v80, 7, v252
	v_lshl_add_u32 v82, v82, 7, v252
	v_lshl_add_u32 v88, v88, 7, v252
	v_lshl_add_u32 v90, v90, 7, v252
	v_lshl_add_u32 v96, v96, 7, v252
	v_lshl_add_u32 v98, v98, 7, v252
	v_lshl_add_u32 v104, v104, 7, v252
	v_lshl_add_u32 v106, v106, 7, v252
	v_lshl_add_u32 v112, v112, 7, v252
	v_lshl_add_u32 v114, v114, 7, v252
	v_lshl_add_u32 v120, v120, 7, v252
	v_lshl_add_u32 v122, v122, 7, v252
	v_lshlrev_b64 v[162:163], 9, v[162:163]
	v_mov_b32_e32 v68, v66
	v_mov_b32_e32 v76, v74
	v_mov_b32_e32 v84, v82
	v_mov_b32_e32 v92, v90
	v_mov_b32_e32 v100, v98
	v_mov_b32_e32 v108, v106
	v_mov_b32_e32 v116, v114
	v_mov_b32_e32 v124, v122
	v_lshl_add_u64 v[162:163], v[144:145], 0, v[162:163]
	global_load_dwordx4 v[64:67], v64, s[98:99]
	s_nop 0
	global_load_dwordx4 v[68:71], v68, s[98:99]
	s_nop 0
	global_load_dwordx4 v[72:75], v72, s[98:99]
	s_nop 0
	global_load_dwordx4 v[76:79], v76, s[98:99]
	s_nop 0
	global_load_dwordx4 v[80:83], v80, s[98:99]
	s_nop 0
	global_load_dwordx4 v[84:87], v84, s[98:99]
	s_nop 0
	global_load_dwordx4 v[88:91], v88, s[98:99]
	s_nop 0
	global_load_dwordx4 v[92:95], v92, s[98:99]
	s_nop 0
	global_load_dwordx4 v[96:99], v96, s[98:99]
	s_nop 0
	global_load_dwordx4 v[100:103], v100, s[98:99]
	s_nop 0
	global_load_dwordx4 v[104:107], v104, s[98:99]
	s_nop 0
	global_load_dwordx4 v[108:111], v108, s[98:99]
	s_nop 0
	global_load_dwordx4 v[112:115], v112, s[98:99]
	s_nop 0
	global_load_dwordx4 v[116:119], v116, s[98:99]
	s_nop 0
	global_load_dwordx4 v[120:123], v120, s[98:99]
	s_nop 0
	global_load_dwordx4 v[124:127], v124, s[98:99]
	s_nop 0
	global_load_dword v177, v[162:163], off
	global_load_dword v179, v[162:163], off offset:256
